# combo + blocked 512B-contiguous layout for the unorm8 merge-gate bytes (producer proj/HALFN gate epilogues, consumer merge seams + merge epilogue)
# speedup vs baseline: 1.0143x; 1.0143x over previous
; __device__ __forceinline__ float sigmoid_f(float x) { return __builtin_amdgcn_rcpf(1.0f + __builtin_amdgcn_exp2f(-1.4426950409f * x)); }
;     __device__ __forceinline__ void body_gate(f32x4 (&acc)[2][2][4][2], const Unit& u, int wr, int wc, int fr, int fq, int gbase, const float (&rsv)[2][4]) const {
;         EPI_ROWS_BEGIN
;             const float rs = rsv[ai][m];
; #pragma unroll
;             for (int bj = 0; bj < 2; ++bj) { if (u.half != 0 && bj == 1) continue;
;                 const int gcol = gbase + (bj + (u.half == 2 ? 1 : 0)) * 128 + wc * 32 + 8 * fq;
;                 f32x4 v0 = acc[ai][bj][m][0] * rs, v1 = acc[ai][bj][m][1] * rs;
; #pragma unroll
;                 for (int j = 0; j < 4; ++j) { v0[j] = sigmoid_f(v0[j]); v1[j] = sigmoid_f(v1[j]); }
;                 u32x2 w; w.x = pk_unorm8(v0); w.y = pk_unorm8(v1);
;                 *(u32x2*)((unsigned char*)P + (size_t)row * ROWB + GATE_B0 + gcol) = w;
;             }
;         EPI_END
.LBB0_200:
	s_cmp_gt_u32 s52, 15
	s_cbranch_scc0 .LBB0_218
	s_cmp_gt_u32 s52, 19
	s_cbranch_scc0 .LBB0_215
	s_cmp_gt_u32 s52, 23
	s_cbranch_scc0 .LBB0_212
	s_cmp_gt_u32 s52, 31
	s_cbranch_scc0 .LBB0_209
	v_mov_b32_e32 v159, v158
	v_pk_mul_f32 v[178:179], v[126:127], v[158:159] op_sel_hi:[1,0]
	s_lshl_b32 s6, s52, 8
	v_mul_f32_e32 v160, 0xbfb8aa3b, v178
	v_exp_f32_e32 v170, v160
	v_mad_i64_i32 v[168:169], s[4:5], v154, s33, 0
	v_pk_mul_f32 v[174:175], v[128:129], v[158:159] op_sel_hi:[1,0]
	v_add_f32_e32 v170, 1.0, v170
	v_rcp_f32_e32 v180, v170
	v_pk_mul_f32 v[160:161], v[124:125], v[158:159] op_sel_hi:[1,0]
	v_pk_mul_f32 v[176:177], v[122:123], v[158:159] op_sel_hi:[1,0]
	s_cmp_gt_u32 s52, 35
	v_lshlrev_b32_e32 v216, 3, v210
	s_mov_b64 s[4:5], -1
	v_lshl_add_u64 v[172:173], s[68:69], 0, v[168:169]
	v_mul_f32_e32 v218, 0xbfb8aa3b, v176
	v_mul_f32_e32 v217, 0xbfb8aa3b, v179
	v_mul_f32_e32 v215, 0xbfb8aa3b, v177
	v_mul_f32_e32 v214, 0xbfb8aa3b, v174
	v_mul_f32_e32 v213, 0xbfb8aa3b, v160
	v_mul_f32_e32 v212, 0xbfb8aa3b, v175
	v_mul_f32_e32 v211, 0xbfb8aa3b, v161
	v_pk_mul_f32 v[170:171], v[118:119], v[158:159]
	v_pk_mul_f32 v[168:169], v[110:111], v[158:159]
	s_cbranch_scc0 .LBB0_206
	v_exp_f32_e32 v159, v218
	v_exp_f32_e32 v183, v217
	v_exp_f32_e32 v219, v211
	s_mov_b32 s8, 0x437f0000
	v_add_f32_e32 v159, 1.0, v159
	v_rcp_f32_e32 v181, v159
	v_exp_f32_e32 v159, v215
	v_add_f32_e32 v183, 1.0, v183
	v_rcp_f32_e32 v184, v183
	v_exp_f32_e32 v183, v214
	v_add_f32_e32 v159, 1.0, v159
	v_rcp_f32_e32 v185, v159
	v_exp_f32_e32 v159, v213
	v_add_f32_e32 v183, 1.0, v183
	v_rcp_f32_e32 v186, v183
	v_exp_f32_e32 v183, v212
	v_add_f32_e32 v159, 1.0, v159
	v_rcp_f32_e32 v187, v159
	v_pk_fma_f32 v[184:185], v[184:185], s[8:9], 0.5 op_sel_hi:[1,0,0]
	v_add_f32_e32 v159, 1.0, v183
	v_rcp_f32_e32 v220, v159
	v_add_f32_e32 v159, 1.0, v219
	v_rcp_f32_e32 v221, v159
	v_pk_fma_f32 v[222:223], v[180:181], s[8:9], 0.5 op_sel_hi:[1,0,0]
	v_cvt_u32_f32_e32 v183, v184
	v_cvt_u32_f32_e32 v181, v222
	v_cvt_u32_f32_e32 v219, v185
	v_pk_fma_f32 v[184:185], v[186:187], s[8:9], 0.5 op_sel_hi:[1,0,0]
	v_lshlrev_b32_e32 v183, 8, v183
	v_cvt_u32_f32_sdwa v186, v184 dst_sel:WORD_1 dst_unused:UNUSED_PAD src0_sel:DWORD
	v_cvt_u32_f32_sdwa v187, v185 dst_sel:WORD_1 dst_unused:UNUSED_PAD src0_sel:DWORD
	v_pk_fma_f32 v[184:185], v[220:221], s[8:9], 0.5 op_sel_hi:[1,0,0]
	v_cvt_u32_f32_e32 v159, v223
	v_cvt_u32_f32_sdwa v184, v184 dst_sel:BYTE_3 dst_unused:UNUSED_PAD src0_sel:DWORD
	v_or_b32_e32 v181, v183, v181
	v_or_b32_e32 v181, v181, v186
	v_cvt_u32_f32_sdwa v185, v185 dst_sel:BYTE_3 dst_unused:UNUSED_PAD src0_sel:DWORD
	v_or_b32_e32 v184, v181, v184
	v_mul_f32_e32 v181, 0xbfb8aa3b, v170
	s_add_i32 s4, s27, s6
	s_lshr_b32 s98, s4, 7
	s_and_b32 s98, s98, 14
	s_bfe_u32 s99, s4, 0x10006
	s_or_b32 s98, s98, s99
	v_sub_u32_e32 v230, s98, v1
	s_lshr_b32 s98, s4, 11
	s_lshl_b32 s98, s98, 11
	s_and_b32 s99, s4, 32
	s_lshl_b32 s99, s99, 4
	s_add_i32 s98, s98, s99
	v_lshlrev_b32_e32 v219, 8, v219
	v_exp_f32_e32 v181, v181
	v_lshl_add_u32 v182, v143, 7, s98
	v_lshl_add_u32 v182, v1, 3, v182
	v_mad_i32_i24 v182, v230, s33, v182
	v_or_b32_e32 v159, v219, v159
	v_or_b32_e32 v159, v159, v187
	v_lshl_add_u64 v[186:187], v[172:173], 0, s[64:65]
	v_ashrrev_i32_e32 v183, 31, v182
	v_or_b32_e32 v185, v159, v185
	v_lshl_add_u64 v[220:221], v[186:187], 0, v[182:183]
	v_mov_b32_e32 v159, v158
	v_mul_f32_e32 v219, 0xbfb8aa3b, v168
	global_store_dwordx2 v[220:221], v[184:185], off
	v_pk_mul_f32 v[184:185], v[120:121], v[158:159]
	v_exp_f32_e32 v219, v219
	v_pk_mul_f32 v[220:221], v[112:113], v[158:159]
	v_add_f32_e32 v159, 1.0, v181
	v_mul_f32_e32 v181, 0xbfb8aa3b, v171
	v_exp_f32_e32 v181, v181
	v_rcp_f32_e32 v222, v159
	v_add_f32_e32 v159, 1.0, v219
	v_mul_f32_e32 v219, 0xbfb8aa3b, v169
	v_exp_f32_e32 v219, v219
	v_rcp_f32_e32 v223, v159
	v_add_f32_e32 v159, 1.0, v181
	v_mul_f32_e32 v181, 0xbfb8aa3b, v184
	v_exp_f32_e32 v181, v181
	v_mul_f32_e32 v184, 0xbfb8aa3b, v220
	v_exp_f32_e32 v184, v184
	v_rcp_f32_e32 v224, v159
	v_add_f32_e32 v159, 1.0, v219
	v_rcp_f32_e32 v225, v159
	v_add_f32_e32 v159, 1.0, v181
	v_mul_f32_e32 v181, 0xbfb8aa3b, v185
	v_rcp_f32_e32 v220, v159
	v_add_f32_e32 v159, 1.0, v184
	v_exp_f32_e32 v181, v181
	v_mul_f32_e32 v184, 0xbfb8aa3b, v221
	v_exp_f32_e32 v184, v184
	v_rcp_f32_e32 v221, v159
	v_add_f32_e32 v159, 1.0, v181
	v_rcp_f32_e32 v226, v159
	v_add_f32_e32 v159, 1.0, v184
	v_rcp_f32_e32 v227, v159
	v_pk_fma_f32 v[222:223], v[222:223], s[8:9], 0.5 op_sel_hi:[1,0,0]
	v_pk_fma_f32 v[220:221], v[220:221], s[8:9], 0.5 op_sel_hi:[1,0,0]
	v_cvt_u32_f32_e32 v159, v223
	v_cvt_u32_f32_e32 v181, v222
	v_pk_fma_f32 v[222:223], v[224:225], s[8:9], 0.5 op_sel_hi:[1,0,0]
	v_add_u32_e32 v184, 0x400, v182
	v_cvt_u32_f32_e32 v185, v222
	v_cvt_u32_f32_e32 v219, v223
	v_cvt_u32_f32_sdwa v222, v220 dst_sel:WORD_1 dst_unused:UNUSED_PAD src0_sel:DWORD
	v_cvt_u32_f32_sdwa v223, v221 dst_sel:WORD_1 dst_unused:UNUSED_PAD src0_sel:DWORD
	v_pk_fma_f32 v[220:221], v[226:227], s[8:9], 0.5 op_sel_hi:[1,0,0]
	v_lshlrev_b32_e32 v219, 8, v219
	v_cvt_u32_f32_sdwa v220, v220 dst_sel:BYTE_3 dst_unused:UNUSED_PAD src0_sel:DWORD
	v_cvt_u32_f32_sdwa v221, v221 dst_sel:BYTE_3 dst_unused:UNUSED_PAD src0_sel:DWORD
	v_lshlrev_b32_e32 v185, 8, v185
	v_or_b32_e32 v159, v219, v159
	v_or_b32_e32 v181, v185, v181
	v_or_b32_e32 v159, v159, v223
	v_or_b32_e32 v181, v181, v222
	v_ashrrev_i32_e32 v185, 31, v184
	v_or_b32_e32 v221, v159, v221
	v_or_b32_e32 v220, v181, v220
	v_lshl_add_u64 v[186:187], v[186:187], 0, v[184:185]
	global_store_dwordx2 v[186:187], v[220:221], off
	v_pk_mul_f32 v[220:221], v[114:115], v[156:157] op_sel_hi:[1,0]
; __device__ __forceinline__ float sigmoid_f(float x) { return __builtin_amdgcn_rcpf(1.0f + __builtin_amdgcn_exp2f(-1.4426950409f * x)); }
;     __device__ __forceinline__ void body_gate(f32x4 (&acc)[2][2][4][2], const Unit& u, int wr, int wc, int fr, int fq, int gbase, const float (&rsv)[2][4]) const {
;     ...
;             const float rs = rsv[ai][m];
; #pragma unroll
;             for (int bj = 0; bj < 2; ++bj) { if (u.half != 0 && bj == 1) continue;
;                 const int gcol = gbase + (bj + (u.half == 2 ? 1 : 0)) * 128 + wc * 32 + 8 * fq;
;                 f32x4 v0 = acc[ai][bj][m][0] * rs, v1 = acc[ai][bj][m][1] * rs;
; #pragma unroll
;                 for (int j = 0; j < 4; ++j) { v0[j] = sigmoid_f(v0[j]); v1[j] = sigmoid_f(v1[j]); }
;                 u32x2 w; w.x = pk_unorm8(v0); w.y = pk_unorm8(v1);
;                 *(u32x2*)((unsigned char*)P + (size_t)row * ROWB + GATE_B0 + gcol) = w;
	v_pk_mul_f32 v[222:223], v[106:107], v[156:157] op_sel_hi:[1,0]
	v_mul_f32_e32 v159, 0xbfb8aa3b, v220
	v_exp_f32_e32 v159, v159
	v_mul_f32_e32 v181, 0xbfb8aa3b, v222
	v_exp_f32_e32 v181, v181
	v_mul_f32_e32 v219, 0xbfb8aa3b, v223
	v_add_f32_e32 v159, 1.0, v159
	v_rcp_f32_e32 v220, v159
	v_add_f32_e32 v159, 1.0, v181
	v_mul_f32_e32 v181, 0xbfb8aa3b, v221
	v_exp_f32_e32 v181, v181
	v_pk_mul_f32 v[186:187], v[116:117], v[156:157] op_sel_hi:[1,0]
	v_exp_f32_e32 v219, v219
	v_rcp_f32_e32 v221, v159
	v_add_f32_e32 v159, 1.0, v181
	v_mul_f32_e32 v181, 0xbfb8aa3b, v186
	v_pk_mul_f32 v[224:225], v[108:109], v[156:157] op_sel_hi:[1,0]
	v_exp_f32_e32 v181, v181
	v_mul_f32_e32 v186, 0xbfb8aa3b, v224
	v_rcp_f32_e32 v222, v159
	v_add_f32_e32 v159, 1.0, v219
	v_exp_f32_e32 v219, v186
	v_rcp_f32_e32 v223, v159
	v_add_f32_e32 v159, 1.0, v181
	v_mul_f32_e32 v181, 0xbfb8aa3b, v187
	v_exp_f32_e32 v181, v181
	v_mul_f32_e32 v187, 0xbfb8aa3b, v225
	v_rcp_f32_e32 v186, v159
	v_add_f32_e32 v159, 1.0, v219
	v_exp_f32_e32 v219, v187
	v_rcp_f32_e32 v187, v159
	v_add_f32_e32 v159, 1.0, v181
	v_rcp_f32_e32 v224, v159
	v_add_f32_e32 v159, 1.0, v219
	v_rcp_f32_e32 v225, v159
	v_pk_fma_f32 v[220:221], v[220:221], s[8:9], 0.5 op_sel_hi:[1,0,0]
	v_pk_fma_f32 v[186:187], v[186:187], s[8:9], 0.5 op_sel_hi:[1,0,0]
	v_cvt_u32_f32_e32 v159, v221
	v_cvt_u32_f32_e32 v181, v220
	v_pk_fma_f32 v[220:221], v[222:223], s[8:9], 0.5 op_sel_hi:[1,0,0]
	v_cvt_u32_f32_sdwa v222, v187 dst_sel:WORD_1 dst_unused:UNUSED_PAD src0_sel:DWORD
	v_cvt_u32_f32_e32 v219, v220
	v_cvt_u32_f32_e32 v220, v221
	v_cvt_u32_f32_sdwa v221, v186 dst_sel:WORD_1 dst_unused:UNUSED_PAD src0_sel:DWORD
	v_pk_fma_f32 v[186:187], v[224:225], s[8:9], 0.5 op_sel_hi:[1,0,0]
	v_lshlrev_b32_e32 v219, 8, v219
	v_cvt_u32_f32_sdwa v186, v186 dst_sel:BYTE_3 dst_unused:UNUSED_PAD src0_sel:DWORD
	v_cvt_u32_f32_sdwa v187, v187 dst_sel:BYTE_3 dst_unused:UNUSED_PAD src0_sel:DWORD
	v_lshlrev_b32_e32 v220, 8, v220
	v_or_b32_e32 v159, v220, v159
	v_or_b32_e32 v181, v219, v181
	v_or_b32_e32 v159, v159, v222
	v_or_b32_e32 v181, v181, v221
	v_or_b32_e32 v221, v159, v187
	v_or_b32_e32 v220, v181, v186
	v_mov_b64_e32 v[186:187], s[68:69]
	v_mad_i64_i32 v[222:223], s[4:5], v209, s33, v[186:187]
	v_lshl_add_u64 v[222:223], v[222:223], 0, s[64:65]
	v_lshl_add_u64 v[224:225], v[222:223], 0, v[182:183]
	global_store_dwordx2 v[224:225], v[220:221], off
	v_pk_mul_f32 v[224:225], v[98:99], v[156:157] op_sel_hi:[1,0]
	v_pk_mul_f32 v[226:227], v[90:91], v[156:157] op_sel_hi:[1,0]
	v_mul_f32_e32 v159, 0xbfb8aa3b, v224
	v_exp_f32_e32 v159, v159
	v_mul_f32_e32 v181, 0xbfb8aa3b, v226
	v_exp_f32_e32 v181, v181
	v_mul_f32_e32 v219, 0xbfb8aa3b, v227
	v_add_f32_e32 v159, 1.0, v159
	v_rcp_f32_e32 v224, v159
	v_add_f32_e32 v159, 1.0, v181
	v_mul_f32_e32 v181, 0xbfb8aa3b, v225
	v_exp_f32_e32 v181, v181
	v_exp_f32_e32 v219, v219
	v_pk_mul_f32 v[220:221], v[100:101], v[156:157] op_sel_hi:[1,0]
	v_pk_mul_f32 v[228:229], v[92:93], v[156:157] op_sel_hi:[1,0]
	v_rcp_f32_e32 v225, v159
	v_add_f32_e32 v159, 1.0, v181
	v_mul_f32_e32 v181, 0xbfb8aa3b, v220
	v_rcp_f32_e32 v226, v159
	v_add_f32_e32 v159, 1.0, v219
	v_exp_f32_e32 v181, v181
	v_mul_f32_e32 v219, 0xbfb8aa3b, v228
	v_exp_f32_e32 v219, v219
	v_rcp_f32_e32 v227, v159
	v_add_f32_e32 v159, 1.0, v181
	v_mul_f32_e32 v181, 0xbfb8aa3b, v221
	v_rcp_f32_e32 v220, v159
	v_add_f32_e32 v159, 1.0, v219
	v_exp_f32_e32 v181, v181
	v_mul_f32_e32 v219, 0xbfb8aa3b, v229
	v_exp_f32_e32 v219, v219
	v_rcp_f32_e32 v221, v159
	v_add_f32_e32 v159, 1.0, v181
	v_rcp_f32_e32 v228, v159
	v_add_f32_e32 v159, 1.0, v219
	v_rcp_f32_e32 v229, v159
	v_pk_fma_f32 v[224:225], v[224:225], s[8:9], 0.5 op_sel_hi:[1,0,0]
	v_pk_fma_f32 v[220:221], v[220:221], s[8:9], 0.5 op_sel_hi:[1,0,0]
	v_cvt_u32_f32_e32 v159, v225
	v_cvt_u32_f32_e32 v181, v224
	v_pk_fma_f32 v[224:225], v[226:227], s[8:9], 0.5 op_sel_hi:[1,0,0]
	v_cvt_u32_f32_sdwa v226, v221 dst_sel:WORD_1 dst_unused:UNUSED_PAD src0_sel:DWORD
	v_cvt_u32_f32_e32 v219, v224
	v_cvt_u32_f32_e32 v224, v225
	v_cvt_u32_f32_sdwa v225, v220 dst_sel:WORD_1 dst_unused:UNUSED_PAD src0_sel:DWORD
	v_pk_fma_f32 v[220:221], v[228:229], s[8:9], 0.5 op_sel_hi:[1,0,0]
	v_lshlrev_b32_e32 v219, 8, v219
	v_cvt_u32_f32_sdwa v220, v220 dst_sel:BYTE_3 dst_unused:UNUSED_PAD src0_sel:DWORD
	v_cvt_u32_f32_sdwa v221, v221 dst_sel:BYTE_3 dst_unused:UNUSED_PAD src0_sel:DWORD
	v_lshlrev_b32_e32 v224, 8, v224
	v_or_b32_e32 v159, v224, v159
	v_or_b32_e32 v181, v219, v181
	v_or_b32_e32 v159, v159, v226
	v_or_b32_e32 v181, v181, v225
	v_or_b32_e32 v221, v159, v221
	v_or_b32_e32 v220, v181, v220
	v_lshl_add_u64 v[222:223], v[222:223], 0, v[184:185]
	global_store_dwordx2 v[222:223], v[220:221], off
	v_pk_mul_f32 v[222:223], v[102:103], v[152:153] op_sel_hi:[1,0]
	v_pk_mul_f32 v[224:225], v[94:95], v[152:153] op_sel_hi:[1,0]
	v_mul_f32_e32 v159, 0xbfb8aa3b, v222
	v_exp_f32_e32 v159, v159
	v_mul_f32_e32 v181, 0xbfb8aa3b, v224
	v_exp_f32_e32 v181, v181
	v_mul_f32_e32 v219, 0xbfb8aa3b, v225
	v_add_f32_e32 v159, 1.0, v159
	v_rcp_f32_e32 v222, v159
	v_add_f32_e32 v159, 1.0, v181
	v_mul_f32_e32 v181, 0xbfb8aa3b, v223
	v_exp_f32_e32 v181, v181
	v_exp_f32_e32 v219, v219
	v_pk_mul_f32 v[220:221], v[104:105], v[152:153] op_sel_hi:[1,0]
	v_pk_mul_f32 v[226:227], v[96:97], v[152:153] op_sel_hi:[1,0]
	v_rcp_f32_e32 v223, v159
	v_add_f32_e32 v159, 1.0, v181
	v_mul_f32_e32 v181, 0xbfb8aa3b, v220
	v_rcp_f32_e32 v224, v159
	v_add_f32_e32 v159, 1.0, v219
	v_exp_f32_e32 v181, v181
	v_mul_f32_e32 v219, 0xbfb8aa3b, v226
	v_exp_f32_e32 v219, v219
	v_rcp_f32_e32 v225, v159
	v_add_f32_e32 v159, 1.0, v181
	v_mul_f32_e32 v181, 0xbfb8aa3b, v221
; __device__ __forceinline__ float sigmoid_f(float x) { return __builtin_amdgcn_rcpf(1.0f + __builtin_amdgcn_exp2f(-1.4426950409f * x)); }
;     __device__ __forceinline__ void body_gate(f32x4 (&acc)[2][2][4][2], const Unit& u, int wr, int wc, int fr, int fq, int gbase, const float (&rsv)[2][4]) const {
;         EPI_ROWS_BEGIN
;             const float rs = rsv[ai][m];
; #pragma unroll
;             for (int bj = 0; bj < 2; ++bj) { if (u.half != 0 && bj == 1) continue;
;                 const int gcol = gbase + (bj + (u.half == 2 ? 1 : 0)) * 128 + wc * 32 + 8 * fq;
;                 f32x4 v0 = acc[ai][bj][m][0] * rs, v1 = acc[ai][bj][m][1] * rs;
; #pragma unroll
;                 for (int j = 0; j < 4; ++j) { v0[j] = sigmoid_f(v0[j]); v1[j] = sigmoid_f(v1[j]); }
;                 u32x2 w; w.x = pk_unorm8(v0); w.y = pk_unorm8(v1);
;                 *(u32x2*)((unsigned char*)P + (size_t)row * ROWB + GATE_B0 + gcol) = w;
;             }
;         EPI_END
;     }
	v_rcp_f32_e32 v220, v159
	v_add_f32_e32 v159, 1.0, v219
	v_exp_f32_e32 v181, v181
	v_mul_f32_e32 v219, 0xbfb8aa3b, v227
	v_exp_f32_e32 v219, v219
	v_rcp_f32_e32 v221, v159
	v_add_f32_e32 v159, 1.0, v181
	v_rcp_f32_e32 v226, v159
	v_add_f32_e32 v159, 1.0, v219
	v_pk_fma_f32 v[222:223], v[222:223], s[8:9], 0.5 op_sel_hi:[1,0,0]
	v_rcp_f32_e32 v227, v159
	v_cvt_u32_f32_e32 v159, v223
	v_cvt_u32_f32_e32 v181, v222
	v_pk_fma_f32 v[222:223], v[224:225], s[8:9], 0.5 op_sel_hi:[1,0,0]
	v_pk_fma_f32 v[220:221], v[220:221], s[8:9], 0.5 op_sel_hi:[1,0,0]
	v_cvt_u32_f32_e32 v219, v222
	v_cvt_u32_f32_e32 v222, v223
	v_cvt_u32_f32_sdwa v223, v220 dst_sel:WORD_1 dst_unused:UNUSED_PAD src0_sel:DWORD
	v_cvt_u32_f32_sdwa v224, v221 dst_sel:WORD_1 dst_unused:UNUSED_PAD src0_sel:DWORD
	v_pk_fma_f32 v[220:221], v[226:227], s[8:9], 0.5 op_sel_hi:[1,0,0]
	v_lshlrev_b32_e32 v219, 8, v219
	v_cvt_u32_f32_sdwa v220, v220 dst_sel:BYTE_3 dst_unused:UNUSED_PAD src0_sel:DWORD
	v_cvt_u32_f32_sdwa v221, v221 dst_sel:BYTE_3 dst_unused:UNUSED_PAD src0_sel:DWORD
	v_lshlrev_b32_e32 v222, 8, v222
	v_or_b32_e32 v181, v219, v181
	v_or_b32_e32 v159, v222, v159
	v_or_b32_e32 v181, v181, v223
	v_mad_i64_i32 v[222:223], s[4:5], v208, s33, v[186:187]
	v_or_b32_e32 v159, v159, v224
	v_lshl_add_u64 v[222:223], v[222:223], 0, s[64:65]
	v_or_b32_e32 v221, v159, v221
	v_or_b32_e32 v220, v181, v220
	v_lshl_add_u64 v[224:225], v[222:223], 0, v[182:183]
	global_store_dwordx2 v[224:225], v[220:221], off
	v_pk_mul_f32 v[224:225], v[82:83], v[152:153] op_sel_hi:[1,0]
	v_pk_mul_f32 v[226:227], v[74:75], v[152:153] op_sel_hi:[1,0]
	v_mul_f32_e32 v159, 0xbfb8aa3b, v224
	v_exp_f32_e32 v159, v159
	v_mul_f32_e32 v181, 0xbfb8aa3b, v226
	v_exp_f32_e32 v181, v181
	v_mul_f32_e32 v219, 0xbfb8aa3b, v227
	v_add_f32_e32 v159, 1.0, v159
	v_rcp_f32_e32 v224, v159
	v_add_f32_e32 v159, 1.0, v181
	v_mul_f32_e32 v181, 0xbfb8aa3b, v225
	v_exp_f32_e32 v181, v181
	v_exp_f32_e32 v219, v219
	v_pk_mul_f32 v[220:221], v[84:85], v[152:153] op_sel_hi:[1,0]
	v_pk_mul_f32 v[228:229], v[76:77], v[152:153] op_sel_hi:[1,0]
	v_rcp_f32_e32 v225, v159
	v_add_f32_e32 v159, 1.0, v181
	v_mul_f32_e32 v181, 0xbfb8aa3b, v220
	v_rcp_f32_e32 v226, v159
	v_add_f32_e32 v159, 1.0, v219
	v_exp_f32_e32 v181, v181
	v_mul_f32_e32 v219, 0xbfb8aa3b, v228
	v_exp_f32_e32 v219, v219
	v_rcp_f32_e32 v227, v159
	v_add_f32_e32 v159, 1.0, v181
	v_mul_f32_e32 v181, 0xbfb8aa3b, v221
	v_rcp_f32_e32 v220, v159
	v_add_f32_e32 v159, 1.0, v219
	v_exp_f32_e32 v181, v181
	v_mul_f32_e32 v219, 0xbfb8aa3b, v229
	v_exp_f32_e32 v219, v219
	v_rcp_f32_e32 v221, v159
	v_add_f32_e32 v159, 1.0, v181
	v_rcp_f32_e32 v228, v159
	v_add_f32_e32 v159, 1.0, v219
	v_rcp_f32_e32 v229, v159
	v_pk_fma_f32 v[224:225], v[224:225], s[8:9], 0.5 op_sel_hi:[1,0,0]
	v_pk_fma_f32 v[220:221], v[220:221], s[8:9], 0.5 op_sel_hi:[1,0,0]
	v_cvt_u32_f32_e32 v159, v225
	v_cvt_u32_f32_e32 v181, v224
	v_pk_fma_f32 v[224:225], v[226:227], s[8:9], 0.5 op_sel_hi:[1,0,0]
	v_cvt_u32_f32_sdwa v226, v221 dst_sel:WORD_1 dst_unused:UNUSED_PAD src0_sel:DWORD
	v_cvt_u32_f32_e32 v219, v224
	v_cvt_u32_f32_e32 v224, v225
	v_cvt_u32_f32_sdwa v225, v220 dst_sel:WORD_1 dst_unused:UNUSED_PAD src0_sel:DWORD
	v_pk_fma_f32 v[220:221], v[228:229], s[8:9], 0.5 op_sel_hi:[1,0,0]
	v_lshlrev_b32_e32 v219, 8, v219
	v_cvt_u32_f32_sdwa v220, v220 dst_sel:BYTE_3 dst_unused:UNUSED_PAD src0_sel:DWORD
	v_cvt_u32_f32_sdwa v221, v221 dst_sel:BYTE_3 dst_unused:UNUSED_PAD src0_sel:DWORD
	v_lshlrev_b32_e32 v224, 8, v224
	v_or_b32_e32 v159, v224, v159
	v_or_b32_e32 v181, v219, v181
	v_or_b32_e32 v159, v159, v226
	v_or_b32_e32 v181, v181, v225
	v_or_b32_e32 v221, v159, v221
	v_or_b32_e32 v220, v181, v220
	v_lshl_add_u64 v[222:223], v[222:223], 0, v[184:185]
	global_store_dwordx2 v[222:223], v[220:221], off
	v_pk_mul_f32 v[222:223], v[86:87], v[150:151] op_sel_hi:[1,0]
	v_pk_mul_f32 v[224:225], v[78:79], v[150:151] op_sel_hi:[1,0]
	v_mul_f32_e32 v159, 0xbfb8aa3b, v222
	v_exp_f32_e32 v159, v159
	v_mul_f32_e32 v181, 0xbfb8aa3b, v224
	v_exp_f32_e32 v181, v181
	v_mul_f32_e32 v219, 0xbfb8aa3b, v225
	v_add_f32_e32 v159, 1.0, v159
	v_rcp_f32_e32 v222, v159
	v_add_f32_e32 v159, 1.0, v181
	v_mul_f32_e32 v181, 0xbfb8aa3b, v223
	v_exp_f32_e32 v181, v181
	v_exp_f32_e32 v219, v219
	v_pk_mul_f32 v[220:221], v[88:89], v[150:151] op_sel_hi:[1,0]
	v_pk_mul_f32 v[226:227], v[80:81], v[150:151] op_sel_hi:[1,0]
	v_rcp_f32_e32 v223, v159
	v_add_f32_e32 v159, 1.0, v181
	v_mul_f32_e32 v181, 0xbfb8aa3b, v220
	v_rcp_f32_e32 v224, v159
	v_add_f32_e32 v159, 1.0, v219
	v_exp_f32_e32 v181, v181
	v_mul_f32_e32 v219, 0xbfb8aa3b, v226
	v_exp_f32_e32 v219, v219
	v_rcp_f32_e32 v225, v159
	v_add_f32_e32 v159, 1.0, v181
	v_mul_f32_e32 v181, 0xbfb8aa3b, v221
	v_rcp_f32_e32 v220, v159
	v_add_f32_e32 v159, 1.0, v219
	v_exp_f32_e32 v181, v181
	v_mul_f32_e32 v219, 0xbfb8aa3b, v227
	v_exp_f32_e32 v219, v219
	v_rcp_f32_e32 v221, v159
	v_add_f32_e32 v159, 1.0, v181
	v_rcp_f32_e32 v226, v159
	v_add_f32_e32 v159, 1.0, v219
	v_pk_fma_f32 v[222:223], v[222:223], s[8:9], 0.5 op_sel_hi:[1,0,0]
	v_rcp_f32_e32 v227, v159
	v_cvt_u32_f32_e32 v159, v223
	v_cvt_u32_f32_e32 v181, v222
	v_pk_fma_f32 v[222:223], v[224:225], s[8:9], 0.5 op_sel_hi:[1,0,0]
	v_pk_fma_f32 v[220:221], v[220:221], s[8:9], 0.5 op_sel_hi:[1,0,0]
	v_cvt_u32_f32_e32 v219, v222
	v_cvt_u32_f32_e32 v222, v223
	v_cvt_u32_f32_sdwa v223, v220 dst_sel:WORD_1 dst_unused:UNUSED_PAD src0_sel:DWORD
	v_cvt_u32_f32_sdwa v224, v221 dst_sel:WORD_1 dst_unused:UNUSED_PAD src0_sel:DWORD
	v_pk_fma_f32 v[220:221], v[226:227], s[8:9], 0.5 op_sel_hi:[1,0,0]
	v_lshlrev_b32_e32 v219, 8, v219
	v_cvt_u32_f32_sdwa v220, v220 dst_sel:BYTE_3 dst_unused:UNUSED_PAD src0_sel:DWORD
; __device__ __forceinline__ float sigmoid_f(float x) { return __builtin_amdgcn_rcpf(1.0f + __builtin_amdgcn_exp2f(-1.4426950409f * x)); }
;     __device__ __forceinline__ void body_gate(f32x4 (&acc)[2][2][4][2], const Unit& u, int wr, int wc, int fr, int fq, int gbase, const float (&rsv)[2][4]) const {
;         EPI_ROWS_BEGIN
;             const float rs = rsv[ai][m];
; #pragma unroll
;             for (int bj = 0; bj < 2; ++bj) { if (u.half != 0 && bj == 1) continue;
;                 const int gcol = gbase + (bj + (u.half == 2 ? 1 : 0)) * 128 + wc * 32 + 8 * fq;
;                 f32x4 v0 = acc[ai][bj][m][0] * rs, v1 = acc[ai][bj][m][1] * rs;
; #pragma unroll
;                 for (int j = 0; j < 4; ++j) { v0[j] = sigmoid_f(v0[j]); v1[j] = sigmoid_f(v1[j]); }
;                 u32x2 w; w.x = pk_unorm8(v0); w.y = pk_unorm8(v1);
;                 *(u32x2*)((unsigned char*)P + (size_t)row * ROWB + GATE_B0 + gcol) = w;
;             }
;         EPI_END
;     }
	v_cvt_u32_f32_sdwa v221, v221 dst_sel:BYTE_3 dst_unused:UNUSED_PAD src0_sel:DWORD
	v_lshlrev_b32_e32 v222, 8, v222
	v_or_b32_e32 v181, v219, v181
	v_or_b32_e32 v159, v222, v159
	v_or_b32_e32 v181, v181, v223
	v_mad_i64_i32 v[222:223], s[4:5], v157, s33, v[186:187]
	v_or_b32_e32 v159, v159, v224
	v_lshl_add_u64 v[222:223], v[222:223], 0, s[64:65]
	v_or_b32_e32 v221, v159, v221
	v_or_b32_e32 v220, v181, v220
	v_lshl_add_u64 v[224:225], v[222:223], 0, v[182:183]
	global_store_dwordx2 v[224:225], v[220:221], off
	v_pk_mul_f32 v[224:225], v[70:71], v[150:151] op_sel_hi:[1,0]
	v_pk_mul_f32 v[226:227], v[66:67], v[150:151] op_sel_hi:[1,0]
	v_mul_f32_e32 v159, 0xbfb8aa3b, v224
	v_exp_f32_e32 v159, v159
	v_mul_f32_e32 v181, 0xbfb8aa3b, v226
	v_exp_f32_e32 v181, v181
	v_mul_f32_e32 v219, 0xbfb8aa3b, v227
	v_add_f32_e32 v159, 1.0, v159
	v_rcp_f32_e32 v224, v159
	v_add_f32_e32 v159, 1.0, v181
	v_mul_f32_e32 v181, 0xbfb8aa3b, v225
	v_exp_f32_e32 v181, v181
	v_exp_f32_e32 v219, v219
	v_pk_mul_f32 v[220:221], v[72:73], v[150:151] op_sel_hi:[1,0]
	v_pk_mul_f32 v[228:229], v[68:69], v[150:151] op_sel_hi:[1,0]
	v_rcp_f32_e32 v225, v159
	v_add_f32_e32 v159, 1.0, v181
	v_mul_f32_e32 v181, 0xbfb8aa3b, v220
	v_rcp_f32_e32 v226, v159
	v_add_f32_e32 v159, 1.0, v219
	v_exp_f32_e32 v181, v181
	v_mul_f32_e32 v219, 0xbfb8aa3b, v228
	v_exp_f32_e32 v219, v219
	v_rcp_f32_e32 v227, v159
	v_add_f32_e32 v159, 1.0, v181
	v_mul_f32_e32 v181, 0xbfb8aa3b, v221
	v_rcp_f32_e32 v220, v159
	v_add_f32_e32 v159, 1.0, v219
	v_exp_f32_e32 v181, v181
	v_mul_f32_e32 v219, 0xbfb8aa3b, v229
	v_exp_f32_e32 v219, v219
	v_rcp_f32_e32 v221, v159
	v_add_f32_e32 v159, 1.0, v181
	v_rcp_f32_e32 v228, v159
	v_add_f32_e32 v159, 1.0, v219
	v_rcp_f32_e32 v229, v159
	v_pk_fma_f32 v[224:225], v[224:225], s[8:9], 0.5 op_sel_hi:[1,0,0]
	v_pk_fma_f32 v[220:221], v[220:221], s[8:9], 0.5 op_sel_hi:[1,0,0]
	v_cvt_u32_f32_e32 v159, v225
	v_cvt_u32_f32_e32 v181, v224
	v_pk_fma_f32 v[224:225], v[226:227], s[8:9], 0.5 op_sel_hi:[1,0,0]
	v_cvt_u32_f32_sdwa v226, v221 dst_sel:WORD_1 dst_unused:UNUSED_PAD src0_sel:DWORD
	v_cvt_u32_f32_e32 v219, v224
	v_cvt_u32_f32_e32 v224, v225
	v_cvt_u32_f32_sdwa v225, v220 dst_sel:WORD_1 dst_unused:UNUSED_PAD src0_sel:DWORD
	v_pk_fma_f32 v[220:221], v[228:229], s[8:9], 0.5 op_sel_hi:[1,0,0]
	v_lshlrev_b32_e32 v219, 8, v219
	v_cvt_u32_f32_sdwa v220, v220 dst_sel:BYTE_3 dst_unused:UNUSED_PAD src0_sel:DWORD
	v_cvt_u32_f32_sdwa v221, v221 dst_sel:BYTE_3 dst_unused:UNUSED_PAD src0_sel:DWORD
	v_lshlrev_b32_e32 v224, 8, v224
	v_or_b32_e32 v159, v224, v159
	v_or_b32_e32 v181, v219, v181
	v_or_b32_e32 v159, v159, v226
	v_or_b32_e32 v181, v181, v225
	v_or_b32_e32 v221, v159, v221
	v_or_b32_e32 v220, v181, v220
	v_lshl_add_u64 v[222:223], v[222:223], 0, v[184:185]
	global_store_dwordx2 v[222:223], v[220:221], off
	v_pk_mul_f32 v[222:223], v[62:63], v[148:149] op_sel_hi:[1,0]
	v_pk_mul_f32 v[224:225], v[58:59], v[148:149] op_sel_hi:[1,0]
	v_mul_f32_e32 v159, 0xbfb8aa3b, v222
	v_exp_f32_e32 v159, v159
	v_mul_f32_e32 v181, 0xbfb8aa3b, v224
	v_exp_f32_e32 v181, v181
	v_mul_f32_e32 v219, 0xbfb8aa3b, v225
	v_add_f32_e32 v159, 1.0, v159
	v_rcp_f32_e32 v222, v159
	v_add_f32_e32 v159, 1.0, v181
	v_mul_f32_e32 v181, 0xbfb8aa3b, v223
	v_exp_f32_e32 v181, v181
	v_exp_f32_e32 v219, v219
	v_pk_mul_f32 v[220:221], v[64:65], v[148:149] op_sel_hi:[1,0]
	v_pk_mul_f32 v[226:227], v[60:61], v[148:149] op_sel_hi:[1,0]
	v_rcp_f32_e32 v223, v159
	v_add_f32_e32 v159, 1.0, v181
	v_mul_f32_e32 v181, 0xbfb8aa3b, v220
	v_rcp_f32_e32 v224, v159
	v_add_f32_e32 v159, 1.0, v219
	v_exp_f32_e32 v181, v181
	v_mul_f32_e32 v219, 0xbfb8aa3b, v226
	v_exp_f32_e32 v219, v219
	v_rcp_f32_e32 v225, v159
	v_add_f32_e32 v159, 1.0, v181
	v_mul_f32_e32 v181, 0xbfb8aa3b, v221
	v_rcp_f32_e32 v220, v159
	v_add_f32_e32 v159, 1.0, v219
	v_exp_f32_e32 v181, v181
	v_mul_f32_e32 v219, 0xbfb8aa3b, v227
	v_exp_f32_e32 v219, v219
	v_rcp_f32_e32 v221, v159
	v_add_f32_e32 v159, 1.0, v181
	v_rcp_f32_e32 v226, v159
	v_add_f32_e32 v159, 1.0, v219
	v_pk_fma_f32 v[222:223], v[222:223], s[8:9], 0.5 op_sel_hi:[1,0,0]
	v_rcp_f32_e32 v227, v159
	v_cvt_u32_f32_e32 v159, v223
	v_cvt_u32_f32_e32 v181, v222
	v_pk_fma_f32 v[222:223], v[224:225], s[8:9], 0.5 op_sel_hi:[1,0,0]
	v_pk_fma_f32 v[220:221], v[220:221], s[8:9], 0.5 op_sel_hi:[1,0,0]
	v_cvt_u32_f32_e32 v219, v222
	v_cvt_u32_f32_e32 v222, v223
	v_cvt_u32_f32_sdwa v223, v220 dst_sel:WORD_1 dst_unused:UNUSED_PAD src0_sel:DWORD
	v_cvt_u32_f32_sdwa v224, v221 dst_sel:WORD_1 dst_unused:UNUSED_PAD src0_sel:DWORD
	v_pk_fma_f32 v[220:221], v[226:227], s[8:9], 0.5 op_sel_hi:[1,0,0]
	v_lshlrev_b32_e32 v219, 8, v219
	v_cvt_u32_f32_sdwa v220, v220 dst_sel:BYTE_3 dst_unused:UNUSED_PAD src0_sel:DWORD
	v_cvt_u32_f32_sdwa v221, v221 dst_sel:BYTE_3 dst_unused:UNUSED_PAD src0_sel:DWORD
	v_lshlrev_b32_e32 v222, 8, v222
	v_or_b32_e32 v181, v219, v181
	v_or_b32_e32 v159, v222, v159
	v_or_b32_e32 v181, v181, v223
	v_mad_i64_i32 v[222:223], s[4:5], v155, s33, v[186:187]
	v_or_b32_e32 v159, v159, v224
	v_lshl_add_u64 v[222:223], v[222:223], 0, s[64:65]
	v_or_b32_e32 v221, v159, v221
	v_or_b32_e32 v220, v181, v220
	v_lshl_add_u64 v[224:225], v[222:223], 0, v[182:183]
	global_store_dwordx2 v[224:225], v[220:221], off
	v_pk_mul_f32 v[224:225], v[50:51], v[148:149] op_sel_hi:[1,0]
	v_pk_mul_f32 v[226:227], v[42:43], v[148:149] op_sel_hi:[1,0]
	v_mul_f32_e32 v159, 0xbfb8aa3b, v224
	v_exp_f32_e32 v159, v159
	v_mul_f32_e32 v181, 0xbfb8aa3b, v226
	v_exp_f32_e32 v181, v181
	v_mul_f32_e32 v219, 0xbfb8aa3b, v227
	v_add_f32_e32 v159, 1.0, v159
	v_rcp_f32_e32 v224, v159
	v_add_f32_e32 v159, 1.0, v181
	v_mul_f32_e32 v181, 0xbfb8aa3b, v225
; __device__ __forceinline__ float sigmoid_f(float x) { return __builtin_amdgcn_rcpf(1.0f + __builtin_amdgcn_exp2f(-1.4426950409f * x)); }
;     __device__ __forceinline__ void body_gate(f32x4 (&acc)[2][2][4][2], const Unit& u, int wr, int wc, int fr, int fq, int gbase, const float (&rsv)[2][4]) const {
;         EPI_ROWS_BEGIN
;             const float rs = rsv[ai][m];
; #pragma unroll
;             for (int bj = 0; bj < 2; ++bj) { if (u.half != 0 && bj == 1) continue;
;                 const int gcol = gbase + (bj + (u.half == 2 ? 1 : 0)) * 128 + wc * 32 + 8 * fq;
;                 f32x4 v0 = acc[ai][bj][m][0] * rs, v1 = acc[ai][bj][m][1] * rs;
; #pragma unroll
;                 for (int j = 0; j < 4; ++j) { v0[j] = sigmoid_f(v0[j]); v1[j] = sigmoid_f(v1[j]); }
;                 u32x2 w; w.x = pk_unorm8(v0); w.y = pk_unorm8(v1);
;                 *(u32x2*)((unsigned char*)P + (size_t)row * ROWB + GATE_B0 + gcol) = w;
;             }
;         EPI_END
;     }
	v_exp_f32_e32 v181, v181
	v_exp_f32_e32 v219, v219
	v_pk_mul_f32 v[220:221], v[52:53], v[148:149] op_sel_hi:[1,0]
	v_pk_mul_f32 v[228:229], v[44:45], v[148:149] op_sel_hi:[1,0]
	v_rcp_f32_e32 v225, v159
	v_add_f32_e32 v159, 1.0, v181
	v_mul_f32_e32 v181, 0xbfb8aa3b, v220
	v_rcp_f32_e32 v226, v159
	v_add_f32_e32 v159, 1.0, v219
	v_exp_f32_e32 v181, v181
	v_mul_f32_e32 v219, 0xbfb8aa3b, v228
	v_exp_f32_e32 v219, v219
	v_rcp_f32_e32 v227, v159
	v_add_f32_e32 v159, 1.0, v181
	v_mul_f32_e32 v181, 0xbfb8aa3b, v221
	v_rcp_f32_e32 v220, v159
	v_add_f32_e32 v159, 1.0, v219
	v_exp_f32_e32 v181, v181
	v_mul_f32_e32 v219, 0xbfb8aa3b, v229
	v_exp_f32_e32 v219, v219
	v_rcp_f32_e32 v221, v159
	v_add_f32_e32 v159, 1.0, v181
	v_rcp_f32_e32 v228, v159
	v_add_f32_e32 v159, 1.0, v219
	v_rcp_f32_e32 v229, v159
	v_pk_fma_f32 v[224:225], v[224:225], s[8:9], 0.5 op_sel_hi:[1,0,0]
	v_pk_fma_f32 v[220:221], v[220:221], s[8:9], 0.5 op_sel_hi:[1,0,0]
	v_cvt_u32_f32_e32 v159, v225
	v_cvt_u32_f32_e32 v181, v224
	v_pk_fma_f32 v[224:225], v[226:227], s[8:9], 0.5 op_sel_hi:[1,0,0]
	v_cvt_u32_f32_sdwa v226, v221 dst_sel:WORD_1 dst_unused:UNUSED_PAD src0_sel:DWORD
	v_cvt_u32_f32_e32 v219, v224
	v_cvt_u32_f32_e32 v224, v225
	v_cvt_u32_f32_sdwa v225, v220 dst_sel:WORD_1 dst_unused:UNUSED_PAD src0_sel:DWORD
	v_pk_fma_f32 v[220:221], v[228:229], s[8:9], 0.5 op_sel_hi:[1,0,0]
	v_lshlrev_b32_e32 v219, 8, v219
	v_cvt_u32_f32_sdwa v220, v220 dst_sel:BYTE_3 dst_unused:UNUSED_PAD src0_sel:DWORD
	v_cvt_u32_f32_sdwa v221, v221 dst_sel:BYTE_3 dst_unused:UNUSED_PAD src0_sel:DWORD
	v_lshlrev_b32_e32 v224, 8, v224
	v_or_b32_e32 v159, v224, v159
	v_or_b32_e32 v181, v219, v181
	v_or_b32_e32 v159, v159, v226
	v_or_b32_e32 v181, v181, v225
	v_or_b32_e32 v221, v159, v221
	v_or_b32_e32 v220, v181, v220
	v_lshl_add_u64 v[222:223], v[222:223], 0, v[184:185]
	global_store_dwordx2 v[222:223], v[220:221], off
	v_pk_mul_f32 v[222:223], v[54:55], v[146:147] op_sel_hi:[1,0]
	v_pk_mul_f32 v[224:225], v[46:47], v[146:147] op_sel_hi:[1,0]
	v_mul_f32_e32 v159, 0xbfb8aa3b, v222
	v_exp_f32_e32 v159, v159
	v_mul_f32_e32 v181, 0xbfb8aa3b, v224
	v_exp_f32_e32 v181, v181
	v_mul_f32_e32 v219, 0xbfb8aa3b, v225
	v_add_f32_e32 v159, 1.0, v159
	v_rcp_f32_e32 v222, v159
	v_add_f32_e32 v159, 1.0, v181
	v_mul_f32_e32 v181, 0xbfb8aa3b, v223
	v_exp_f32_e32 v181, v181
	v_exp_f32_e32 v219, v219
	v_pk_mul_f32 v[220:221], v[56:57], v[146:147] op_sel_hi:[1,0]
	v_pk_mul_f32 v[226:227], v[48:49], v[146:147] op_sel_hi:[1,0]
	v_rcp_f32_e32 v223, v159
	v_add_f32_e32 v159, 1.0, v181
	v_mul_f32_e32 v181, 0xbfb8aa3b, v220
	v_rcp_f32_e32 v224, v159
	v_add_f32_e32 v159, 1.0, v219
	v_exp_f32_e32 v181, v181
	v_mul_f32_e32 v219, 0xbfb8aa3b, v226
	v_exp_f32_e32 v219, v219
	v_rcp_f32_e32 v225, v159
	v_add_f32_e32 v159, 1.0, v181
	v_mul_f32_e32 v181, 0xbfb8aa3b, v221
	v_rcp_f32_e32 v220, v159
	v_add_f32_e32 v159, 1.0, v219
	v_exp_f32_e32 v181, v181
	v_mul_f32_e32 v219, 0xbfb8aa3b, v227
	v_exp_f32_e32 v219, v219
	v_rcp_f32_e32 v221, v159
	v_add_f32_e32 v159, 1.0, v181
	v_rcp_f32_e32 v226, v159
	v_add_f32_e32 v159, 1.0, v219
	v_pk_fma_f32 v[222:223], v[222:223], s[8:9], 0.5 op_sel_hi:[1,0,0]
	v_rcp_f32_e32 v227, v159
	v_cvt_u32_f32_e32 v159, v223
	v_cvt_u32_f32_e32 v181, v222
	v_pk_fma_f32 v[222:223], v[224:225], s[8:9], 0.5 op_sel_hi:[1,0,0]
	v_pk_fma_f32 v[220:221], v[220:221], s[8:9], 0.5 op_sel_hi:[1,0,0]
	v_cvt_u32_f32_e32 v219, v222
	v_cvt_u32_f32_e32 v222, v223
	v_cvt_u32_f32_sdwa v223, v220 dst_sel:WORD_1 dst_unused:UNUSED_PAD src0_sel:DWORD
	v_cvt_u32_f32_sdwa v224, v221 dst_sel:WORD_1 dst_unused:UNUSED_PAD src0_sel:DWORD
	v_pk_fma_f32 v[220:221], v[226:227], s[8:9], 0.5 op_sel_hi:[1,0,0]
	v_lshlrev_b32_e32 v219, 8, v219
	v_cvt_u32_f32_sdwa v220, v220 dst_sel:BYTE_3 dst_unused:UNUSED_PAD src0_sel:DWORD
	v_cvt_u32_f32_sdwa v221, v221 dst_sel:BYTE_3 dst_unused:UNUSED_PAD src0_sel:DWORD
	v_lshlrev_b32_e32 v222, 8, v222
	v_or_b32_e32 v181, v219, v181
	v_or_b32_e32 v159, v222, v159
	v_or_b32_e32 v181, v181, v223
	v_mad_i64_i32 v[222:223], s[4:5], v153, s33, v[186:187]
	v_or_b32_e32 v159, v159, v224
	v_lshl_add_u64 v[222:223], v[222:223], 0, s[64:65]
	v_or_b32_e32 v221, v159, v221
	v_or_b32_e32 v220, v181, v220
	v_lshl_add_u64 v[224:225], v[222:223], 0, v[182:183]
	global_store_dwordx2 v[224:225], v[220:221], off
	v_pk_mul_f32 v[224:225], v[34:35], v[146:147] op_sel_hi:[1,0]
	v_pk_mul_f32 v[226:227], v[26:27], v[146:147] op_sel_hi:[1,0]
	v_mul_f32_e32 v159, 0xbfb8aa3b, v224
	v_exp_f32_e32 v159, v159
	v_mul_f32_e32 v181, 0xbfb8aa3b, v226
	v_exp_f32_e32 v181, v181
	v_mul_f32_e32 v219, 0xbfb8aa3b, v227
	v_add_f32_e32 v159, 1.0, v159
	v_rcp_f32_e32 v224, v159
	v_add_f32_e32 v159, 1.0, v181
	v_mul_f32_e32 v181, 0xbfb8aa3b, v225
	v_exp_f32_e32 v181, v181
	v_exp_f32_e32 v219, v219
	v_pk_mul_f32 v[220:221], v[36:37], v[146:147] op_sel_hi:[1,0]
	v_pk_mul_f32 v[228:229], v[28:29], v[146:147] op_sel_hi:[1,0]
	v_rcp_f32_e32 v225, v159
	v_add_f32_e32 v159, 1.0, v181
	v_mul_f32_e32 v181, 0xbfb8aa3b, v220
	v_rcp_f32_e32 v226, v159
	v_add_f32_e32 v159, 1.0, v219
	v_exp_f32_e32 v181, v181
	v_mul_f32_e32 v219, 0xbfb8aa3b, v228
	v_exp_f32_e32 v219, v219
	v_rcp_f32_e32 v227, v159
	v_add_f32_e32 v159, 1.0, v181
	v_mul_f32_e32 v181, 0xbfb8aa3b, v221
	v_rcp_f32_e32 v220, v159
	v_add_f32_e32 v159, 1.0, v219
	v_exp_f32_e32 v181, v181
	v_mul_f32_e32 v219, 0xbfb8aa3b, v229
	v_exp_f32_e32 v219, v219
	v_rcp_f32_e32 v221, v159
	v_add_f32_e32 v159, 1.0, v181
	v_rcp_f32_e32 v228, v159
	v_add_f32_e32 v159, 1.0, v219
	v_rcp_f32_e32 v229, v159
	v_pk_fma_f32 v[224:225], v[224:225], s[8:9], 0.5 op_sel_hi:[1,0,0]
	v_pk_fma_f32 v[220:221], v[220:221], s[8:9], 0.5 op_sel_hi:[1,0,0]
; __device__ __forceinline__ float sigmoid_f(float x) { return __builtin_amdgcn_rcpf(1.0f + __builtin_amdgcn_exp2f(-1.4426950409f * x)); }
;     __device__ __forceinline__ void body_gate(f32x4 (&acc)[2][2][4][2], const Unit& u, int wr, int wc, int fr, int fq, int gbase, const float (&rsv)[2][4]) const {
;         EPI_ROWS_BEGIN
;             const float rs = rsv[ai][m];
; #pragma unroll
;             for (int bj = 0; bj < 2; ++bj) { if (u.half != 0 && bj == 1) continue;
;                 const int gcol = gbase + (bj + (u.half == 2 ? 1 : 0)) * 128 + wc * 32 + 8 * fq;
;                 f32x4 v0 = acc[ai][bj][m][0] * rs, v1 = acc[ai][bj][m][1] * rs;
; #pragma unroll
;                 for (int j = 0; j < 4; ++j) { v0[j] = sigmoid_f(v0[j]); v1[j] = sigmoid_f(v1[j]); }
;                 u32x2 w; w.x = pk_unorm8(v0); w.y = pk_unorm8(v1);
;                 *(u32x2*)((unsigned char*)P + (size_t)row * ROWB + GATE_B0 + gcol) = w;
;             }
;         EPI_END
;     }
	v_cvt_u32_f32_e32 v159, v225
	v_cvt_u32_f32_e32 v181, v224
	v_pk_fma_f32 v[224:225], v[226:227], s[8:9], 0.5 op_sel_hi:[1,0,0]
	v_cvt_u32_f32_sdwa v226, v221 dst_sel:WORD_1 dst_unused:UNUSED_PAD src0_sel:DWORD
	v_cvt_u32_f32_e32 v219, v224
	v_cvt_u32_f32_e32 v224, v225
	v_cvt_u32_f32_sdwa v225, v220 dst_sel:WORD_1 dst_unused:UNUSED_PAD src0_sel:DWORD
	v_pk_fma_f32 v[220:221], v[228:229], s[8:9], 0.5 op_sel_hi:[1,0,0]
	v_lshlrev_b32_e32 v219, 8, v219
	v_cvt_u32_f32_sdwa v220, v220 dst_sel:BYTE_3 dst_unused:UNUSED_PAD src0_sel:DWORD
	v_cvt_u32_f32_sdwa v221, v221 dst_sel:BYTE_3 dst_unused:UNUSED_PAD src0_sel:DWORD
	v_lshlrev_b32_e32 v224, 8, v224
	v_or_b32_e32 v159, v224, v159
	v_or_b32_e32 v181, v219, v181
	v_or_b32_e32 v159, v159, v226
	v_or_b32_e32 v181, v181, v225
	v_or_b32_e32 v221, v159, v221
	v_or_b32_e32 v220, v181, v220
	v_lshl_add_u64 v[222:223], v[222:223], 0, v[184:185]
	global_store_dwordx2 v[222:223], v[220:221], off
	v_pk_mul_f32 v[222:223], v[38:39], v[144:145] op_sel_hi:[1,0]
	v_pk_mul_f32 v[224:225], v[30:31], v[144:145] op_sel_hi:[1,0]
	v_mul_f32_e32 v159, 0xbfb8aa3b, v222
	v_exp_f32_e32 v159, v159
	v_mul_f32_e32 v181, 0xbfb8aa3b, v224
	v_exp_f32_e32 v181, v181
	v_mul_f32_e32 v219, 0xbfb8aa3b, v225
	v_add_f32_e32 v159, 1.0, v159
	v_rcp_f32_e32 v222, v159
	v_add_f32_e32 v159, 1.0, v181
	v_mul_f32_e32 v181, 0xbfb8aa3b, v223
	v_exp_f32_e32 v181, v181
	v_exp_f32_e32 v219, v219
	v_pk_mul_f32 v[220:221], v[40:41], v[144:145] op_sel_hi:[1,0]
	v_pk_mul_f32 v[226:227], v[32:33], v[144:145] op_sel_hi:[1,0]
	v_rcp_f32_e32 v223, v159
	v_add_f32_e32 v159, 1.0, v181
	v_mul_f32_e32 v181, 0xbfb8aa3b, v220
	v_rcp_f32_e32 v224, v159
	v_add_f32_e32 v159, 1.0, v219
	v_exp_f32_e32 v181, v181
	v_mul_f32_e32 v219, 0xbfb8aa3b, v226
	v_exp_f32_e32 v219, v219
	v_rcp_f32_e32 v225, v159
	v_add_f32_e32 v159, 1.0, v181
	v_mul_f32_e32 v181, 0xbfb8aa3b, v221
	v_rcp_f32_e32 v220, v159
	v_add_f32_e32 v159, 1.0, v219
	v_exp_f32_e32 v181, v181
	v_mul_f32_e32 v219, 0xbfb8aa3b, v227
	v_exp_f32_e32 v219, v219
	v_rcp_f32_e32 v221, v159
	v_add_f32_e32 v159, 1.0, v181
	v_rcp_f32_e32 v226, v159
	v_add_f32_e32 v159, 1.0, v219
	v_pk_fma_f32 v[222:223], v[222:223], s[8:9], 0.5 op_sel_hi:[1,0,0]
	v_rcp_f32_e32 v227, v159
	v_cvt_u32_f32_e32 v159, v223
	v_cvt_u32_f32_e32 v181, v222
	v_pk_fma_f32 v[222:223], v[224:225], s[8:9], 0.5 op_sel_hi:[1,0,0]
	v_pk_fma_f32 v[220:221], v[220:221], s[8:9], 0.5 op_sel_hi:[1,0,0]
	v_cvt_u32_f32_e32 v219, v222
	v_cvt_u32_f32_e32 v222, v223
	v_cvt_u32_f32_sdwa v223, v220 dst_sel:WORD_1 dst_unused:UNUSED_PAD src0_sel:DWORD
	v_cvt_u32_f32_sdwa v224, v221 dst_sel:WORD_1 dst_unused:UNUSED_PAD src0_sel:DWORD
	v_pk_fma_f32 v[220:221], v[226:227], s[8:9], 0.5 op_sel_hi:[1,0,0]
	v_lshlrev_b32_e32 v219, 8, v219
	v_cvt_u32_f32_sdwa v220, v220 dst_sel:BYTE_3 dst_unused:UNUSED_PAD src0_sel:DWORD
	v_cvt_u32_f32_sdwa v221, v221 dst_sel:BYTE_3 dst_unused:UNUSED_PAD src0_sel:DWORD
	v_lshlrev_b32_e32 v222, 8, v222
	v_or_b32_e32 v181, v219, v181
	v_or_b32_e32 v159, v222, v159
	v_or_b32_e32 v181, v181, v223
	v_mad_i64_i32 v[222:223], s[4:5], v151, s33, v[186:187]
	v_or_b32_e32 v159, v159, v224
	v_lshl_add_u64 v[222:223], v[222:223], 0, s[64:65]
	v_or_b32_e32 v221, v159, v221
	v_or_b32_e32 v220, v181, v220
	v_lshl_add_u64 v[224:225], v[222:223], 0, v[182:183]
	global_store_dwordx2 v[224:225], v[220:221], off
	v_pk_mul_f32 v[224:225], v[18:19], v[144:145] op_sel_hi:[1,0]
	v_pk_mul_f32 v[226:227], v[10:11], v[144:145] op_sel_hi:[1,0]
	v_mul_f32_e32 v159, 0xbfb8aa3b, v224
	v_exp_f32_e32 v159, v159
	v_mul_f32_e32 v181, 0xbfb8aa3b, v226
	v_exp_f32_e32 v181, v181
	v_mul_f32_e32 v219, 0xbfb8aa3b, v227
	v_add_f32_e32 v159, 1.0, v159
	v_rcp_f32_e32 v224, v159
	v_add_f32_e32 v159, 1.0, v181
	v_mul_f32_e32 v181, 0xbfb8aa3b, v225
	v_exp_f32_e32 v181, v181
	v_exp_f32_e32 v219, v219
	v_pk_mul_f32 v[220:221], v[20:21], v[144:145] op_sel_hi:[1,0]
	v_pk_mul_f32 v[228:229], v[12:13], v[144:145] op_sel_hi:[1,0]
	v_rcp_f32_e32 v225, v159
	v_add_f32_e32 v159, 1.0, v181
	v_mul_f32_e32 v181, 0xbfb8aa3b, v220
	v_rcp_f32_e32 v226, v159
	v_add_f32_e32 v159, 1.0, v219
	v_exp_f32_e32 v181, v181
	v_mul_f32_e32 v219, 0xbfb8aa3b, v228
	v_exp_f32_e32 v219, v219
	v_rcp_f32_e32 v227, v159
	v_add_f32_e32 v159, 1.0, v181
	v_mul_f32_e32 v181, 0xbfb8aa3b, v221
	v_rcp_f32_e32 v220, v159
	v_add_f32_e32 v159, 1.0, v219
	v_exp_f32_e32 v181, v181
	v_mul_f32_e32 v219, 0xbfb8aa3b, v229
	v_exp_f32_e32 v219, v219
	v_rcp_f32_e32 v221, v159
	v_add_f32_e32 v159, 1.0, v181
	v_rcp_f32_e32 v228, v159
	v_add_f32_e32 v159, 1.0, v219
	v_rcp_f32_e32 v229, v159
	v_pk_fma_f32 v[224:225], v[224:225], s[8:9], 0.5 op_sel_hi:[1,0,0]
	v_pk_fma_f32 v[220:221], v[220:221], s[8:9], 0.5 op_sel_hi:[1,0,0]
	v_cvt_u32_f32_e32 v159, v225
	v_cvt_u32_f32_e32 v181, v224
	v_pk_fma_f32 v[224:225], v[226:227], s[8:9], 0.5 op_sel_hi:[1,0,0]
	v_cvt_u32_f32_sdwa v226, v221 dst_sel:WORD_1 dst_unused:UNUSED_PAD src0_sel:DWORD
	v_cvt_u32_f32_e32 v219, v224
	v_cvt_u32_f32_e32 v224, v225
	v_cvt_u32_f32_sdwa v225, v220 dst_sel:WORD_1 dst_unused:UNUSED_PAD src0_sel:DWORD
	v_pk_fma_f32 v[220:221], v[228:229], s[8:9], 0.5 op_sel_hi:[1,0,0]
	v_lshlrev_b32_e32 v219, 8, v219
; __device__ __forceinline__ float sigmoid_f(float x) { return __builtin_amdgcn_rcpf(1.0f + __builtin_amdgcn_exp2f(-1.4426950409f * x)); }
;     __device__ __forceinline__ void body_gate(f32x4 (&acc)[2][2][4][2], const Unit& u, int wr, int wc, int fr, int fq, int gbase, const float (&rsv)[2][4]) const {
;         EPI_ROWS_BEGIN
;             const float rs = rsv[ai][m];
; #pragma unroll
;             for (int bj = 0; bj < 2; ++bj) { if (u.half != 0 && bj == 1) continue;
;                 const int gcol = gbase + (bj + (u.half == 2 ? 1 : 0)) * 128 + wc * 32 + 8 * fq;
;                 f32x4 v0 = acc[ai][bj][m][0] * rs, v1 = acc[ai][bj][m][1] * rs;
; #pragma unroll
;                 for (int j = 0; j < 4; ++j) { v0[j] = sigmoid_f(v0[j]); v1[j] = sigmoid_f(v1[j]); }
;                 u32x2 w; w.x = pk_unorm8(v0); w.y = pk_unorm8(v1);
;                 *(u32x2*)((unsigned char*)P + (size_t)row * ROWB + GATE_B0 + gcol) = w;
;             }
;         EPI_END
;     }
	v_cvt_u32_f32_sdwa v220, v220 dst_sel:BYTE_3 dst_unused:UNUSED_PAD src0_sel:DWORD
	v_cvt_u32_f32_sdwa v221, v221 dst_sel:BYTE_3 dst_unused:UNUSED_PAD src0_sel:DWORD
	v_lshlrev_b32_e32 v224, 8, v224
	v_or_b32_e32 v159, v224, v159
	v_or_b32_e32 v181, v219, v181
	v_or_b32_e32 v159, v159, v226
	v_or_b32_e32 v181, v181, v225
	v_or_b32_e32 v221, v159, v221
	v_or_b32_e32 v220, v181, v220
	v_lshl_add_u64 v[222:223], v[222:223], 0, v[184:185]
	global_store_dwordx2 v[222:223], v[220:221], off
	v_pk_mul_f32 v[222:223], v[22:23], v[142:143] op_sel_hi:[1,0]
	v_pk_mul_f32 v[224:225], v[14:15], v[142:143] op_sel_hi:[1,0]
	v_mul_f32_e32 v159, 0xbfb8aa3b, v222
	v_exp_f32_e32 v159, v159
	v_mul_f32_e32 v181, 0xbfb8aa3b, v224
	v_exp_f32_e32 v181, v181
	v_mul_f32_e32 v219, 0xbfb8aa3b, v225
	v_add_f32_e32 v159, 1.0, v159
	v_rcp_f32_e32 v222, v159
	v_add_f32_e32 v159, 1.0, v181
	v_mul_f32_e32 v181, 0xbfb8aa3b, v223
	v_exp_f32_e32 v181, v181
	v_exp_f32_e32 v219, v219
	v_pk_mul_f32 v[220:221], v[24:25], v[142:143] op_sel_hi:[1,0]
	v_pk_mul_f32 v[226:227], v[16:17], v[142:143] op_sel_hi:[1,0]
	v_rcp_f32_e32 v223, v159
	v_add_f32_e32 v159, 1.0, v181
	v_mul_f32_e32 v181, 0xbfb8aa3b, v220
	v_rcp_f32_e32 v224, v159
	v_add_f32_e32 v159, 1.0, v219
	v_exp_f32_e32 v181, v181
	v_mul_f32_e32 v219, 0xbfb8aa3b, v226
	v_exp_f32_e32 v219, v219
	v_rcp_f32_e32 v225, v159
	v_add_f32_e32 v159, 1.0, v181
	v_mul_f32_e32 v181, 0xbfb8aa3b, v221
	v_rcp_f32_e32 v220, v159
	v_add_f32_e32 v159, 1.0, v219
	v_exp_f32_e32 v181, v181
	v_mul_f32_e32 v219, 0xbfb8aa3b, v227
	v_exp_f32_e32 v219, v219
	v_rcp_f32_e32 v221, v159
	v_add_f32_e32 v159, 1.0, v181
	v_rcp_f32_e32 v226, v159
	v_add_f32_e32 v159, 1.0, v219
	v_rcp_f32_e32 v227, v159
	v_pk_fma_f32 v[222:223], v[222:223], s[8:9], 0.5 op_sel_hi:[1,0,0]
	v_pk_fma_f32 v[220:221], v[220:221], s[8:9], 0.5 op_sel_hi:[1,0,0]
	v_cvt_u32_f32_e32 v159, v223
	v_cvt_u32_f32_e32 v181, v222
	v_pk_fma_f32 v[222:223], v[224:225], s[8:9], 0.5 op_sel_hi:[1,0,0]
	v_cvt_u32_f32_sdwa v224, v221 dst_sel:WORD_1 dst_unused:UNUSED_PAD src0_sel:DWORD
	v_cvt_u32_f32_e32 v219, v222
	v_cvt_u32_f32_e32 v222, v223
	v_cvt_u32_f32_sdwa v223, v220 dst_sel:WORD_1 dst_unused:UNUSED_PAD src0_sel:DWORD
	v_pk_fma_f32 v[220:221], v[226:227], s[8:9], 0.5 op_sel_hi:[1,0,0]
	v_lshlrev_b32_e32 v219, 8, v219
	v_cvt_u32_f32_sdwa v220, v220 dst_sel:BYTE_3 dst_unused:UNUSED_PAD src0_sel:DWORD
	v_cvt_u32_f32_sdwa v221, v221 dst_sel:BYTE_3 dst_unused:UNUSED_PAD src0_sel:DWORD
	v_lshlrev_b32_e32 v222, 8, v222
	v_or_b32_e32 v159, v222, v159
	v_or_b32_e32 v181, v219, v181
	v_mad_i64_i32 v[186:187], s[4:5], v149, s33, v[186:187]
	v_or_b32_e32 v159, v159, v224
	v_or_b32_e32 v181, v181, v223
	v_lshl_add_u64 v[186:187], v[186:187], 0, s[64:65]
	v_or_b32_e32 v221, v159, v221
	v_or_b32_e32 v220, v181, v220
	v_lshl_add_u64 v[182:183], v[186:187], 0, v[182:183]
	global_store_dwordx2 v[182:183], v[220:221], off
	v_pk_mul_f32 v[220:221], v[6:7], v[142:143] op_sel_hi:[1,0]
	v_pk_mul_f32 v[222:223], v[2:3], v[142:143] op_sel_hi:[1,0]
	v_mul_f32_e32 v159, 0xbfb8aa3b, v220
	v_exp_f32_e32 v159, v159
	v_mul_f32_e32 v181, 0xbfb8aa3b, v222
	v_exp_f32_e32 v181, v181
	v_mul_f32_e32 v219, 0xbfb8aa3b, v223
	v_add_f32_e32 v159, 1.0, v159
	v_rcp_f32_e32 v220, v159
	v_add_f32_e32 v159, 1.0, v181
	v_mul_f32_e32 v181, 0xbfb8aa3b, v221
	v_exp_f32_e32 v181, v181
	v_pk_mul_f32 v[182:183], v[8:9], v[142:143] op_sel_hi:[1,0]
	v_exp_f32_e32 v219, v219
	v_rcp_f32_e32 v221, v159
	v_add_f32_e32 v159, 1.0, v181
	v_mul_f32_e32 v181, 0xbfb8aa3b, v182
	v_pk_mul_f32 v[224:225], v[4:5], v[142:143] op_sel_hi:[1,0]
	v_exp_f32_e32 v181, v181
	v_mul_f32_e32 v182, 0xbfb8aa3b, v224
	v_rcp_f32_e32 v222, v159
	v_add_f32_e32 v159, 1.0, v219
	v_exp_f32_e32 v219, v182
	v_rcp_f32_e32 v223, v159
	v_add_f32_e32 v159, 1.0, v181
	v_mul_f32_e32 v181, 0xbfb8aa3b, v183
	v_exp_f32_e32 v181, v181
	v_mul_f32_e32 v183, 0xbfb8aa3b, v225
	v_rcp_f32_e32 v182, v159
	v_add_f32_e32 v159, 1.0, v219
	v_exp_f32_e32 v219, v183
	v_rcp_f32_e32 v183, v159
	v_add_f32_e32 v159, 1.0, v181
	v_rcp_f32_e32 v224, v159
	v_add_f32_e32 v159, 1.0, v219
	v_rcp_f32_e32 v225, v159
	v_pk_fma_f32 v[220:221], v[220:221], s[8:9], 0.5 op_sel_hi:[1,0,0]
	v_pk_fma_f32 v[182:183], v[182:183], s[8:9], 0.5 op_sel_hi:[1,0,0]
	v_cvt_u32_f32_e32 v159, v221
	v_cvt_u32_f32_e32 v181, v220
	v_pk_fma_f32 v[220:221], v[222:223], s[8:9], 0.5 op_sel_hi:[1,0,0]
	v_cvt_u32_f32_sdwa v222, v183 dst_sel:WORD_1 dst_unused:UNUSED_PAD src0_sel:DWORD
	v_cvt_u32_f32_e32 v219, v220
	v_cvt_u32_f32_e32 v220, v221
	v_cvt_u32_f32_sdwa v221, v182 dst_sel:WORD_1 dst_unused:UNUSED_PAD src0_sel:DWORD
	v_pk_fma_f32 v[182:183], v[224:225], s[8:9], 0.5 op_sel_hi:[1,0,0]
	v_lshlrev_b32_e32 v219, 8, v219
	v_cvt_u32_f32_sdwa v182, v182 dst_sel:BYTE_3 dst_unused:UNUSED_PAD src0_sel:DWORD
	v_cvt_u32_f32_sdwa v183, v183 dst_sel:BYTE_3 dst_unused:UNUSED_PAD src0_sel:DWORD
	v_lshlrev_b32_e32 v220, 8, v220
	v_or_b32_e32 v159, v220, v159
	v_or_b32_e32 v181, v219, v181
	v_or_b32_e32 v159, v159, v222
	v_or_b32_e32 v181, v181, v221
	v_or_b32_e32 v183, v159, v183
	v_or_b32_e32 v182, v181, v182
	v_lshl_add_u64 v[184:185], v[186:187], 0, v[184:185]
	global_store_dwordx2 v[184:185], v[182:183], off
	s_mov_b64 s[4:5], 0

; __device__ __forceinline__ float sigmoid_f(float x) { return __builtin_amdgcn_rcpf(1.0f + __builtin_amdgcn_exp2f(-1.4426950409f * x)); }
;     __device__ __forceinline__ void body_gate(f32x4 (&acc)[2][2][4][2], const Unit& u, int wr, int wc, int fr, int fq, int gbase, const float (&rsv)[2][4]) const {
;         EPI_ROWS_BEGIN
;             const float rs = rsv[ai][m];
; #pragma unroll
;             for (int bj = 0; bj < 2; ++bj) { if (u.half != 0 && bj == 1) continue;
;                 const int gcol = gbase + (bj + (u.half == 2 ? 1 : 0)) * 128 + wc * 32 + 8 * fq;
;                 f32x4 v0 = acc[ai][bj][m][0] * rs, v1 = acc[ai][bj][m][1] * rs;
; #pragma unroll
;                 for (int j = 0; j < 4; ++j) { v0[j] = sigmoid_f(v0[j]); v1[j] = sigmoid_f(v1[j]); }
;                 u32x2 w; w.x = pk_unorm8(v0); w.y = pk_unorm8(v1);
;                 *(u32x2*)((unsigned char*)P + (size_t)row * ROWB + GATE_B0 + gcol) = w;
;             }
;         EPI_END
;     }
;     __device__ __forceinline__ void operator()(f32x4 (&acc)[2][2][4][2], const Unit& u, int wr, int wc, int fr, int fq) const {
;     ...
;         const int pn = u.pn + pn0;
;         if (pn < 8) body_pair<0>(acc, u, wr, wc, fr, fq, OQ + pn * 128, rsv);
;         else if (pn < 16) body_pair<1>(acc, u, wr, wc, fr, fq, OAB + (pn - 8) * 128, rsv);
;         else if (pn < 20) body<0>(acc, u, wr, wc, fr, fq, OBIN + (pn - 16) * 256, rsv);
;         else if (pn < 24) body<1>(acc, u, wr, wc, fr, fq, OBZ + (pn - 20) * 256, rsv);
;         else if (pn < 32) body_pair<2>(acc, u, wr, wc, fr, fq, OV + (pn - 24) * 128, rsv);
;         else if (pn < 36) body<1>(acc, u, wr, wc, fr, fq, OCZ + (pn - 32) * 256, rsv);
;         else body_gate(acc, u, wr, wc, fr, fq, (pn - 36) * 256, rsv);
.LBB0_245:
	s_cmp_gt_u32 s8, 15
	s_cbranch_scc0 .LBB0_263
	s_cmp_gt_u32 s8, 19
	s_cbranch_scc0 .LBB0_260
	s_cmp_gt_u32 s8, 23
	s_cbranch_scc0 .LBB0_257
	s_cmp_gt_u32 s8, 31
	s_cbranch_scc0 .LBB0_254
	v_pk_mul_f32 v[104:105], v[62:63], v[94:95] op_sel_hi:[1,0]
	s_lshl_b32 s9, s8, 8
	v_mul_f32_e32 v95, 0xbfb8aa3b, v104
	v_exp_f32_e32 v95, v95
	v_mad_i64_i32 v[98:99], s[4:5], v88, s33, 0
	s_cmp_gt_u32 s8, 35
	v_pk_mul_f32 v[100:101], v[64:65], v[94:95] op_sel_hi:[1,0]
	v_pk_mul_f32 v[96:97], v[60:61], v[94:95] op_sel_hi:[1,0]
	v_pk_mul_f32 v[102:103], v[58:59], v[94:95] op_sel_hi:[1,0]
	v_add_f32_e32 v95, 1.0, v95
	v_rcp_f32_e32 v106, v95
	v_lshlrev_b32_e32 v121, 3, v114
	s_mov_b64 s[4:5], -1
	v_lshl_add_u64 v[98:99], s[68:69], 0, v[98:99]
	v_mul_f32_e32 v122, 0xbfb8aa3b, v102
	v_mul_f32_e32 v120, 0xbfb8aa3b, v105
	v_mul_f32_e32 v119, 0xbfb8aa3b, v103
	v_mul_f32_e32 v118, 0xbfb8aa3b, v100
	v_mul_f32_e32 v117, 0xbfb8aa3b, v96
	v_mul_f32_e32 v116, 0xbfb8aa3b, v101
	v_mul_f32_e32 v115, 0xbfb8aa3b, v97
	s_cbranch_scc0 .LBB0_251
	v_exp_f32_e32 v95, v122
	v_exp_f32_e32 v108, v120
	v_exp_f32_e32 v109, v115
	s_mov_b32 s26, 0x437f0000
	v_add_f32_e32 v95, 1.0, v95
	v_rcp_f32_e32 v107, v95
	v_exp_f32_e32 v95, v119
	v_add_f32_e32 v108, 1.0, v108
	v_rcp_f32_e32 v110, v108
	v_exp_f32_e32 v108, v118
	v_add_f32_e32 v95, 1.0, v95
	v_rcp_f32_e32 v111, v95
	v_exp_f32_e32 v95, v117
	v_add_f32_e32 v108, 1.0, v108
	v_rcp_f32_e32 v124, v108
	v_exp_f32_e32 v108, v116
	v_add_f32_e32 v95, 1.0, v95
	v_rcp_f32_e32 v125, v95
	v_pk_fma_f32 v[110:111], v[110:111], s[26:27], 0.5 op_sel_hi:[1,0,0]
	v_add_f32_e32 v95, 1.0, v108
	v_rcp_f32_e32 v126, v95
	v_add_f32_e32 v95, 1.0, v109
	v_rcp_f32_e32 v127, v95
	s_cmp_eq_u32 s80, 2
	v_pk_fma_f32 v[128:129], v[106:107], s[26:27], 0.5 op_sel_hi:[1,0,0]
	v_cvt_u32_f32_e32 v109, v110
	v_cvt_u32_f32_e32 v123, v111
	s_cselect_b32 s4, 0x80, 0
	v_cvt_u32_f32_e32 v95, v129
	v_cvt_u32_f32_e32 v107, v128
	v_pk_fma_f32 v[110:111], v[124:125], s[26:27], 0.5 op_sel_hi:[1,0,0]
	s_or_b32 s4, s4, s79
	v_cvt_u32_f32_sdwa v124, v110 dst_sel:WORD_1 dst_unused:UNUSED_PAD src0_sel:DWORD
	v_cvt_u32_f32_sdwa v125, v111 dst_sel:WORD_1 dst_unused:UNUSED_PAD src0_sel:DWORD
	s_add_i32 s4, s4, s9
	s_lshr_b32 s98, s4, 7
	s_and_b32 s98, s98, 14
	s_bfe_u32 s99, s4, 0x10006
	s_or_b32 s98, s98, s99
	v_sub_u32_e32 v230, s98, v1
	s_lshr_b32 s98, s4, 11
	s_lshl_b32 s98, s98, 11
	s_and_b32 s99, s4, 128
	s_lshl_b32 s99, s99, 3
	s_add_i32 s98, s98, s99
	s_and_b32 s99, s4, 32
	s_lshl_b32 s99, s99, 4
	s_add_i32 s98, s98, s99
	v_pk_fma_f32 v[110:111], v[126:127], s[26:27], 0.5 op_sel_hi:[1,0,0]
	v_lshl_add_u32 v108, v114, 7, s98
	v_lshl_add_u32 v108, v1, 3, v108
	v_mad_i32_i24 v108, v230, s33, v108
	v_cvt_u32_f32_sdwa v110, v110 dst_sel:BYTE_3 dst_unused:UNUSED_PAD src0_sel:DWORD
	v_cvt_u32_f32_sdwa v111, v111 dst_sel:BYTE_3 dst_unused:UNUSED_PAD src0_sel:DWORD
	v_lshlrev_b32_e32 v123, 8, v123
	v_lshlrev_b32_e32 v109, 8, v109
	v_or_b32_e32 v95, v123, v95
	v_or_b32_e32 v107, v109, v107
	v_ashrrev_i32_e32 v109, 31, v108
	v_or_b32_e32 v95, v95, v125
	v_or_b32_e32 v107, v107, v124
	v_lshl_add_u64 v[124:125], v[98:99], 0, v[108:109]
	v_add_co_u32_e32 v124, vcc, s12, v124
	v_or_b32_e32 v111, v95, v111
	v_or_b32_e32 v110, v107, v110
	v_addc_co_u32_e32 v125, vcc, 0, v125, vcc
	global_store_dwordx2 v[124:125], v[110:111], off
	v_pk_mul_f32 v[124:125], v[54:55], v[92:93] op_sel_hi:[1,0]
	v_pk_mul_f32 v[126:127], v[50:51], v[92:93] op_sel_hi:[1,0]
	v_mul_f32_e32 v95, 0xbfb8aa3b, v124
	v_exp_f32_e32 v95, v95
	v_mul_f32_e32 v107, 0xbfb8aa3b, v126
	v_exp_f32_e32 v107, v107
	v_mul_f32_e32 v123, 0xbfb8aa3b, v127
	v_add_f32_e32 v95, 1.0, v95
	v_rcp_f32_e32 v124, v95
	v_add_f32_e32 v95, 1.0, v107
	v_mul_f32_e32 v107, 0xbfb8aa3b, v125
	v_exp_f32_e32 v107, v107
	v_pk_mul_f32 v[110:111], v[56:57], v[92:93] op_sel_hi:[1,0]
	v_exp_f32_e32 v123, v123
	v_rcp_f32_e32 v125, v95
	v_add_f32_e32 v95, 1.0, v107
	v_mul_f32_e32 v107, 0xbfb8aa3b, v110
	v_pk_mul_f32 v[128:129], v[52:53], v[92:93] op_sel_hi:[1,0]
	v_exp_f32_e32 v107, v107
	v_mul_f32_e32 v110, 0xbfb8aa3b, v128
	v_rcp_f32_e32 v126, v95
	v_add_f32_e32 v95, 1.0, v123
	v_exp_f32_e32 v123, v110
	v_rcp_f32_e32 v127, v95
	v_add_f32_e32 v95, 1.0, v107
	v_mul_f32_e32 v107, 0xbfb8aa3b, v111
	v_exp_f32_e32 v107, v107
	v_mul_f32_e32 v111, 0xbfb8aa3b, v129
	v_rcp_f32_e32 v110, v95
	v_add_f32_e32 v95, 1.0, v123
	v_exp_f32_e32 v123, v111
	v_rcp_f32_e32 v111, v95
	v_add_f32_e32 v95, 1.0, v107
	v_rcp_f32_e32 v128, v95
	v_add_f32_e32 v95, 1.0, v123
	v_rcp_f32_e32 v129, v95
	v_pk_fma_f32 v[124:125], v[124:125], s[26:27], 0.5 op_sel_hi:[1,0,0]
	v_pk_fma_f32 v[110:111], v[110:111], s[26:27], 0.5 op_sel_hi:[1,0,0]
	v_cvt_u32_f32_e32 v95, v125
	v_cvt_u32_f32_e32 v107, v124
	v_pk_fma_f32 v[124:125], v[126:127], s[26:27], 0.5 op_sel_hi:[1,0,0]
	v_cvt_u32_f32_sdwa v126, v111 dst_sel:WORD_1 dst_unused:UNUSED_PAD src0_sel:DWORD
	v_cvt_u32_f32_e32 v123, v124
	v_cvt_u32_f32_e32 v124, v125
	v_cvt_u32_f32_sdwa v125, v110 dst_sel:WORD_1 dst_unused:UNUSED_PAD src0_sel:DWORD
	v_pk_fma_f32 v[110:111], v[128:129], s[26:27], 0.5 op_sel_hi:[1,0,0]
	v_lshlrev_b32_e32 v123, 8, v123
	v_cvt_u32_f32_sdwa v110, v110 dst_sel:BYTE_3 dst_unused:UNUSED_PAD src0_sel:DWORD
	v_cvt_u32_f32_sdwa v111, v111 dst_sel:BYTE_3 dst_unused:UNUSED_PAD src0_sel:DWORD
	v_lshlrev_b32_e32 v124, 8, v124
	v_or_b32_e32 v95, v124, v95
	v_or_b32_e32 v107, v123, v107
	v_or_b32_e32 v95, v95, v126
	v_or_b32_e32 v107, v107, v125
	v_or_b32_e32 v125, v95, v111
	v_or_b32_e32 v124, v107, v110
	v_mov_b64_e32 v[110:111], s[68:69]
	v_mad_i64_i32 v[126:127], s[4:5], v113, s33, v[110:111]
	v_lshl_add_u64 v[126:127], v[126:127], 0, v[108:109]
; __device__ __forceinline__ float sigmoid_f(float x) { return __builtin_amdgcn_rcpf(1.0f + __builtin_amdgcn_exp2f(-1.4426950409f * x)); }
;     __device__ __forceinline__ void body_gate(f32x4 (&acc)[2][2][4][2], const Unit& u, int wr, int wc, int fr, int fq, int gbase, const float (&rsv)[2][4]) const {
;         EPI_ROWS_BEGIN
;             const float rs = rsv[ai][m];
; #pragma unroll
;             for (int bj = 0; bj < 2; ++bj) { if (u.half != 0 && bj == 1) continue;
;                 const int gcol = gbase + (bj + (u.half == 2 ? 1 : 0)) * 128 + wc * 32 + 8 * fq;
;                 f32x4 v0 = acc[ai][bj][m][0] * rs, v1 = acc[ai][bj][m][1] * rs;
; #pragma unroll
;                 for (int j = 0; j < 4; ++j) { v0[j] = sigmoid_f(v0[j]); v1[j] = sigmoid_f(v1[j]); }
;                 u32x2 w; w.x = pk_unorm8(v0); w.y = pk_unorm8(v1);
;                 *(u32x2*)((unsigned char*)P + (size_t)row * ROWB + GATE_B0 + gcol) = w;
;             }
;         EPI_END
;     }
	v_add_co_u32_e32 v126, vcc, s12, v126
	v_pk_mul_f32 v[128:129], v[42:43], v[90:91] op_sel_hi:[1,0]
	s_nop 0
	v_addc_co_u32_e32 v127, vcc, 0, v127, vcc
	global_store_dwordx2 v[126:127], v[124:125], off
	v_pk_mul_f32 v[126:127], v[46:47], v[90:91] op_sel_hi:[1,0]
	v_mul_f32_e32 v107, 0xbfb8aa3b, v128
	v_mul_f32_e32 v95, 0xbfb8aa3b, v126
	v_exp_f32_e32 v95, v95
	v_exp_f32_e32 v107, v107
	v_mul_f32_e32 v123, 0xbfb8aa3b, v129
	v_exp_f32_e32 v123, v123
	v_add_f32_e32 v95, 1.0, v95
	v_rcp_f32_e32 v126, v95
	v_add_f32_e32 v95, 1.0, v107
	v_mul_f32_e32 v107, 0xbfb8aa3b, v127
	v_exp_f32_e32 v107, v107
	v_pk_mul_f32 v[124:125], v[48:49], v[90:91] op_sel_hi:[1,0]
	v_pk_mul_f32 v[130:131], v[44:45], v[90:91] op_sel_hi:[1,0]
	v_rcp_f32_e32 v127, v95
	v_add_f32_e32 v95, 1.0, v107
	v_mul_f32_e32 v107, 0xbfb8aa3b, v124
	v_rcp_f32_e32 v128, v95
	v_add_f32_e32 v95, 1.0, v123
	v_exp_f32_e32 v107, v107
	v_mul_f32_e32 v123, 0xbfb8aa3b, v130
	v_exp_f32_e32 v123, v123
	v_rcp_f32_e32 v129, v95
	v_add_f32_e32 v95, 1.0, v107
	v_mul_f32_e32 v107, 0xbfb8aa3b, v125
	v_rcp_f32_e32 v124, v95
	v_add_f32_e32 v95, 1.0, v123
	v_exp_f32_e32 v107, v107
	v_mul_f32_e32 v123, 0xbfb8aa3b, v131
	v_exp_f32_e32 v123, v123
	v_rcp_f32_e32 v125, v95
	v_add_f32_e32 v95, 1.0, v107
	v_rcp_f32_e32 v130, v95
	v_add_f32_e32 v95, 1.0, v123
	v_pk_fma_f32 v[126:127], v[126:127], s[26:27], 0.5 op_sel_hi:[1,0,0]
	v_rcp_f32_e32 v131, v95
	v_cvt_u32_f32_e32 v95, v127
	v_cvt_u32_f32_e32 v107, v126
	v_pk_fma_f32 v[126:127], v[128:129], s[26:27], 0.5 op_sel_hi:[1,0,0]
	v_pk_fma_f32 v[124:125], v[124:125], s[26:27], 0.5 op_sel_hi:[1,0,0]
	v_cvt_u32_f32_e32 v123, v126
	v_cvt_u32_f32_e32 v126, v127
	v_cvt_u32_f32_sdwa v127, v124 dst_sel:WORD_1 dst_unused:UNUSED_PAD src0_sel:DWORD
	v_cvt_u32_f32_sdwa v128, v125 dst_sel:WORD_1 dst_unused:UNUSED_PAD src0_sel:DWORD
	v_pk_fma_f32 v[124:125], v[130:131], s[26:27], 0.5 op_sel_hi:[1,0,0]
	v_lshlrev_b32_e32 v123, 8, v123
	v_cvt_u32_f32_sdwa v124, v124 dst_sel:BYTE_3 dst_unused:UNUSED_PAD src0_sel:DWORD
	v_cvt_u32_f32_sdwa v125, v125 dst_sel:BYTE_3 dst_unused:UNUSED_PAD src0_sel:DWORD
	v_lshlrev_b32_e32 v126, 8, v126
	v_or_b32_e32 v107, v123, v107
	v_or_b32_e32 v95, v126, v95
	v_or_b32_e32 v107, v107, v127
	v_mad_i64_i32 v[126:127], s[4:5], v112, s33, v[110:111]
	v_lshl_add_u64 v[126:127], v[126:127], 0, v[108:109]
	v_or_b32_e32 v95, v95, v128
	v_add_co_u32_e32 v126, vcc, s12, v126
	v_or_b32_e32 v125, v95, v125
	v_or_b32_e32 v124, v107, v124
	v_addc_co_u32_e32 v127, vcc, 0, v127, vcc
	global_store_dwordx2 v[126:127], v[124:125], off
	v_pk_mul_f32 v[126:127], v[38:39], v[86:87] op_sel_hi:[1,0]
	v_pk_mul_f32 v[128:129], v[34:35], v[86:87] op_sel_hi:[1,0]
	v_mul_f32_e32 v95, 0xbfb8aa3b, v126
	v_exp_f32_e32 v95, v95
	v_mul_f32_e32 v107, 0xbfb8aa3b, v128
	v_exp_f32_e32 v107, v107
	v_mul_f32_e32 v123, 0xbfb8aa3b, v129
	v_add_f32_e32 v95, 1.0, v95
	v_rcp_f32_e32 v126, v95
	v_add_f32_e32 v95, 1.0, v107
	v_mul_f32_e32 v107, 0xbfb8aa3b, v127
	v_exp_f32_e32 v107, v107
	v_exp_f32_e32 v123, v123
	v_pk_mul_f32 v[124:125], v[40:41], v[86:87] op_sel_hi:[1,0]
	v_pk_mul_f32 v[130:131], v[36:37], v[86:87] op_sel_hi:[1,0]
	v_rcp_f32_e32 v127, v95
	v_add_f32_e32 v95, 1.0, v107
	v_mul_f32_e32 v107, 0xbfb8aa3b, v124
	v_rcp_f32_e32 v128, v95
	v_add_f32_e32 v95, 1.0, v123
	v_exp_f32_e32 v107, v107
	v_mul_f32_e32 v123, 0xbfb8aa3b, v130
	v_exp_f32_e32 v123, v123
	v_rcp_f32_e32 v129, v95
	v_add_f32_e32 v95, 1.0, v107
	v_mul_f32_e32 v107, 0xbfb8aa3b, v125
	v_rcp_f32_e32 v124, v95
	v_add_f32_e32 v95, 1.0, v123
	v_exp_f32_e32 v107, v107
	v_mul_f32_e32 v123, 0xbfb8aa3b, v131
	v_exp_f32_e32 v123, v123
	v_rcp_f32_e32 v125, v95
	v_add_f32_e32 v95, 1.0, v107
	v_rcp_f32_e32 v130, v95
	v_add_f32_e32 v95, 1.0, v123
	v_pk_fma_f32 v[126:127], v[126:127], s[26:27], 0.5 op_sel_hi:[1,0,0]
	v_rcp_f32_e32 v131, v95
	v_cvt_u32_f32_e32 v95, v127
	v_cvt_u32_f32_e32 v107, v126
	v_pk_fma_f32 v[126:127], v[128:129], s[26:27], 0.5 op_sel_hi:[1,0,0]
	v_pk_fma_f32 v[124:125], v[124:125], s[26:27], 0.5 op_sel_hi:[1,0,0]
	v_cvt_u32_f32_e32 v123, v126
	v_cvt_u32_f32_e32 v126, v127
	v_cvt_u32_f32_sdwa v127, v124 dst_sel:WORD_1 dst_unused:UNUSED_PAD src0_sel:DWORD
	v_cvt_u32_f32_sdwa v128, v125 dst_sel:WORD_1 dst_unused:UNUSED_PAD src0_sel:DWORD
	v_pk_fma_f32 v[124:125], v[130:131], s[26:27], 0.5 op_sel_hi:[1,0,0]
	v_lshlrev_b32_e32 v123, 8, v123
	v_cvt_u32_f32_sdwa v124, v124 dst_sel:BYTE_3 dst_unused:UNUSED_PAD src0_sel:DWORD
	v_cvt_u32_f32_sdwa v125, v125 dst_sel:BYTE_3 dst_unused:UNUSED_PAD src0_sel:DWORD
	v_lshlrev_b32_e32 v126, 8, v126
	v_or_b32_e32 v107, v123, v107
	v_or_b32_e32 v95, v126, v95
	v_or_b32_e32 v107, v107, v127
	v_mad_i64_i32 v[126:127], s[4:5], v93, s33, v[110:111]
	v_lshl_add_u64 v[126:127], v[126:127], 0, v[108:109]
	v_or_b32_e32 v95, v95, v128
	v_add_co_u32_e32 v126, vcc, s12, v126
	v_or_b32_e32 v125, v95, v125
	v_or_b32_e32 v124, v107, v124
	v_addc_co_u32_e32 v127, vcc, 0, v127, vcc
	global_store_dwordx2 v[126:127], v[124:125], off
	v_pk_mul_f32 v[126:127], v[30:31], v[84:85] op_sel_hi:[1,0]
	v_pk_mul_f32 v[128:129], v[26:27], v[84:85] op_sel_hi:[1,0]
	v_mul_f32_e32 v95, 0xbfb8aa3b, v126
	v_exp_f32_e32 v95, v95
	v_mul_f32_e32 v107, 0xbfb8aa3b, v128
	v_exp_f32_e32 v107, v107
	v_mul_f32_e32 v123, 0xbfb8aa3b, v129
	v_add_f32_e32 v95, 1.0, v95
	v_rcp_f32_e32 v126, v95
	v_add_f32_e32 v95, 1.0, v107
	v_mul_f32_e32 v107, 0xbfb8aa3b, v127
	v_exp_f32_e32 v107, v107
	v_exp_f32_e32 v123, v123
	v_pk_mul_f32 v[124:125], v[32:33], v[84:85] op_sel_hi:[1,0]
	v_pk_mul_f32 v[130:131], v[28:29], v[84:85] op_sel_hi:[1,0]
	v_rcp_f32_e32 v127, v95
	v_add_f32_e32 v95, 1.0, v107
	v_mul_f32_e32 v107, 0xbfb8aa3b, v124
; __device__ __forceinline__ float sigmoid_f(float x) { return __builtin_amdgcn_rcpf(1.0f + __builtin_amdgcn_exp2f(-1.4426950409f * x)); }
;     __device__ __forceinline__ void body_gate(f32x4 (&acc)[2][2][4][2], const Unit& u, int wr, int wc, int fr, int fq, int gbase, const float (&rsv)[2][4]) const {
;         EPI_ROWS_BEGIN
;             const float rs = rsv[ai][m];
; #pragma unroll
;             for (int bj = 0; bj < 2; ++bj) { if (u.half != 0 && bj == 1) continue;
;                 const int gcol = gbase + (bj + (u.half == 2 ? 1 : 0)) * 128 + wc * 32 + 8 * fq;
;                 f32x4 v0 = acc[ai][bj][m][0] * rs, v1 = acc[ai][bj][m][1] * rs;
; #pragma unroll
;                 for (int j = 0; j < 4; ++j) { v0[j] = sigmoid_f(v0[j]); v1[j] = sigmoid_f(v1[j]); }
;                 u32x2 w; w.x = pk_unorm8(v0); w.y = pk_unorm8(v1);
;                 *(u32x2*)((unsigned char*)P + (size_t)row * ROWB + GATE_B0 + gcol) = w;
;             }
;         EPI_END
;     }
	v_rcp_f32_e32 v128, v95
	v_add_f32_e32 v95, 1.0, v123
	v_exp_f32_e32 v107, v107
	v_mul_f32_e32 v123, 0xbfb8aa3b, v130
	v_exp_f32_e32 v123, v123
	v_rcp_f32_e32 v129, v95
	v_add_f32_e32 v95, 1.0, v107
	v_mul_f32_e32 v107, 0xbfb8aa3b, v125
	v_rcp_f32_e32 v124, v95
	v_add_f32_e32 v95, 1.0, v123
	v_exp_f32_e32 v107, v107
	v_mul_f32_e32 v123, 0xbfb8aa3b, v131
	v_exp_f32_e32 v123, v123
	v_rcp_f32_e32 v125, v95
	v_add_f32_e32 v95, 1.0, v107
	v_rcp_f32_e32 v130, v95
	v_add_f32_e32 v95, 1.0, v123
	v_pk_fma_f32 v[126:127], v[126:127], s[26:27], 0.5 op_sel_hi:[1,0,0]
	v_rcp_f32_e32 v131, v95
	v_cvt_u32_f32_e32 v95, v127
	v_cvt_u32_f32_e32 v107, v126
	v_pk_fma_f32 v[126:127], v[128:129], s[26:27], 0.5 op_sel_hi:[1,0,0]
	v_pk_fma_f32 v[124:125], v[124:125], s[26:27], 0.5 op_sel_hi:[1,0,0]
	v_cvt_u32_f32_e32 v123, v126
	v_cvt_u32_f32_e32 v126, v127
	v_cvt_u32_f32_sdwa v127, v124 dst_sel:WORD_1 dst_unused:UNUSED_PAD src0_sel:DWORD
	v_cvt_u32_f32_sdwa v128, v125 dst_sel:WORD_1 dst_unused:UNUSED_PAD src0_sel:DWORD
	v_pk_fma_f32 v[124:125], v[130:131], s[26:27], 0.5 op_sel_hi:[1,0,0]
	v_lshlrev_b32_e32 v123, 8, v123
	v_cvt_u32_f32_sdwa v124, v124 dst_sel:BYTE_3 dst_unused:UNUSED_PAD src0_sel:DWORD
	v_cvt_u32_f32_sdwa v125, v125 dst_sel:BYTE_3 dst_unused:UNUSED_PAD src0_sel:DWORD
	v_lshlrev_b32_e32 v126, 8, v126
	v_or_b32_e32 v107, v123, v107
	v_or_b32_e32 v95, v126, v95
	v_or_b32_e32 v107, v107, v127
	v_mad_i64_i32 v[126:127], s[4:5], v91, s33, v[110:111]
	v_lshl_add_u64 v[126:127], v[126:127], 0, v[108:109]
	v_or_b32_e32 v95, v95, v128
	v_add_co_u32_e32 v126, vcc, s12, v126
	v_or_b32_e32 v125, v95, v125
	v_or_b32_e32 v124, v107, v124
	v_addc_co_u32_e32 v127, vcc, 0, v127, vcc
	global_store_dwordx2 v[126:127], v[124:125], off
	v_pk_mul_f32 v[126:127], v[22:23], v[82:83] op_sel_hi:[1,0]
	v_pk_mul_f32 v[128:129], v[18:19], v[82:83] op_sel_hi:[1,0]
	v_mul_f32_e32 v95, 0xbfb8aa3b, v126
	v_exp_f32_e32 v95, v95
	v_mul_f32_e32 v107, 0xbfb8aa3b, v128
	v_exp_f32_e32 v107, v107
	v_mul_f32_e32 v123, 0xbfb8aa3b, v129
	v_add_f32_e32 v95, 1.0, v95
	v_rcp_f32_e32 v126, v95
	v_add_f32_e32 v95, 1.0, v107
	v_mul_f32_e32 v107, 0xbfb8aa3b, v127
	v_exp_f32_e32 v107, v107
	v_exp_f32_e32 v123, v123
	v_pk_mul_f32 v[124:125], v[24:25], v[82:83] op_sel_hi:[1,0]
	v_pk_mul_f32 v[130:131], v[20:21], v[82:83] op_sel_hi:[1,0]
	v_rcp_f32_e32 v127, v95
	v_add_f32_e32 v95, 1.0, v107
	v_mul_f32_e32 v107, 0xbfb8aa3b, v124
	v_rcp_f32_e32 v128, v95
	v_add_f32_e32 v95, 1.0, v123
	v_exp_f32_e32 v107, v107
	v_mul_f32_e32 v123, 0xbfb8aa3b, v130
	v_exp_f32_e32 v123, v123
	v_rcp_f32_e32 v129, v95
	v_add_f32_e32 v95, 1.0, v107
	v_mul_f32_e32 v107, 0xbfb8aa3b, v125
	v_rcp_f32_e32 v124, v95
	v_add_f32_e32 v95, 1.0, v123
	v_exp_f32_e32 v107, v107
	v_mul_f32_e32 v123, 0xbfb8aa3b, v131
	v_exp_f32_e32 v123, v123
	v_rcp_f32_e32 v125, v95
	v_add_f32_e32 v95, 1.0, v107
	v_rcp_f32_e32 v130, v95
	v_add_f32_e32 v95, 1.0, v123
	v_pk_fma_f32 v[126:127], v[126:127], s[26:27], 0.5 op_sel_hi:[1,0,0]
	v_rcp_f32_e32 v131, v95
	v_cvt_u32_f32_e32 v95, v127
	v_cvt_u32_f32_e32 v107, v126
	v_pk_fma_f32 v[126:127], v[128:129], s[26:27], 0.5 op_sel_hi:[1,0,0]
	v_pk_fma_f32 v[124:125], v[124:125], s[26:27], 0.5 op_sel_hi:[1,0,0]
	v_cvt_u32_f32_e32 v123, v126
	v_cvt_u32_f32_e32 v126, v127
	v_cvt_u32_f32_sdwa v127, v124 dst_sel:WORD_1 dst_unused:UNUSED_PAD src0_sel:DWORD
	v_cvt_u32_f32_sdwa v128, v125 dst_sel:WORD_1 dst_unused:UNUSED_PAD src0_sel:DWORD
	v_pk_fma_f32 v[124:125], v[130:131], s[26:27], 0.5 op_sel_hi:[1,0,0]
	v_lshlrev_b32_e32 v123, 8, v123
	v_cvt_u32_f32_sdwa v124, v124 dst_sel:BYTE_3 dst_unused:UNUSED_PAD src0_sel:DWORD
	v_cvt_u32_f32_sdwa v125, v125 dst_sel:BYTE_3 dst_unused:UNUSED_PAD src0_sel:DWORD
	v_lshlrev_b32_e32 v126, 8, v126
	v_or_b32_e32 v107, v123, v107
	v_or_b32_e32 v95, v126, v95
	v_or_b32_e32 v107, v107, v127
	v_mad_i64_i32 v[126:127], s[4:5], v89, s33, v[110:111]
	v_lshl_add_u64 v[126:127], v[126:127], 0, v[108:109]
	v_or_b32_e32 v95, v95, v128
	v_add_co_u32_e32 v126, vcc, s12, v126
	v_or_b32_e32 v125, v95, v125
	v_or_b32_e32 v124, v107, v124
	v_addc_co_u32_e32 v127, vcc, 0, v127, vcc
	global_store_dwordx2 v[126:127], v[124:125], off
	v_pk_mul_f32 v[126:127], v[14:15], v[80:81] op_sel_hi:[1,0]
	v_pk_mul_f32 v[128:129], v[10:11], v[80:81] op_sel_hi:[1,0]
	v_mul_f32_e32 v95, 0xbfb8aa3b, v126
	v_exp_f32_e32 v95, v95
	v_mul_f32_e32 v107, 0xbfb8aa3b, v128
	v_exp_f32_e32 v107, v107
	v_mul_f32_e32 v123, 0xbfb8aa3b, v129
	v_add_f32_e32 v95, 1.0, v95
	v_rcp_f32_e32 v126, v95
; __device__ __forceinline__ float sigmoid_f(float x) { return __builtin_amdgcn_rcpf(1.0f + __builtin_amdgcn_exp2f(-1.4426950409f * x)); }
;     __device__ __forceinline__ void body_gate(f32x4 (&acc)[2][2][4][2], const Unit& u, int wr, int wc, int fr, int fq, int gbase, const float (&rsv)[2][4]) const {
;         EPI_ROWS_BEGIN
;             const float rs = rsv[ai][m];
; #pragma unroll
;             for (int bj = 0; bj < 2; ++bj) { if (u.half != 0 && bj == 1) continue;
;                 const int gcol = gbase + (bj + (u.half == 2 ? 1 : 0)) * 128 + wc * 32 + 8 * fq;
;                 f32x4 v0 = acc[ai][bj][m][0] * rs, v1 = acc[ai][bj][m][1] * rs;
; #pragma unroll
;                 for (int j = 0; j < 4; ++j) { v0[j] = sigmoid_f(v0[j]); v1[j] = sigmoid_f(v1[j]); }
;                 u32x2 w; w.x = pk_unorm8(v0); w.y = pk_unorm8(v1);
;                 *(u32x2*)((unsigned char*)P + (size_t)row * ROWB + GATE_B0 + gcol) = w;
;             }
;         EPI_END
;     }
	v_add_f32_e32 v95, 1.0, v107
	v_mul_f32_e32 v107, 0xbfb8aa3b, v127
	v_exp_f32_e32 v107, v107
	v_exp_f32_e32 v123, v123
	v_pk_mul_f32 v[124:125], v[16:17], v[80:81] op_sel_hi:[1,0]
	v_pk_mul_f32 v[130:131], v[12:13], v[80:81] op_sel_hi:[1,0]
	v_rcp_f32_e32 v127, v95
	v_add_f32_e32 v95, 1.0, v107
	v_mul_f32_e32 v107, 0xbfb8aa3b, v124
	v_rcp_f32_e32 v128, v95
	v_add_f32_e32 v95, 1.0, v123
	v_exp_f32_e32 v107, v107
	v_mul_f32_e32 v123, 0xbfb8aa3b, v130
	v_exp_f32_e32 v123, v123
	v_rcp_f32_e32 v129, v95
	v_add_f32_e32 v95, 1.0, v107
	v_mul_f32_e32 v107, 0xbfb8aa3b, v125
	v_rcp_f32_e32 v124, v95
	v_add_f32_e32 v95, 1.0, v123
	v_exp_f32_e32 v107, v107
	v_mul_f32_e32 v123, 0xbfb8aa3b, v131
	v_exp_f32_e32 v123, v123
	v_rcp_f32_e32 v125, v95
	v_add_f32_e32 v95, 1.0, v107
	v_rcp_f32_e32 v130, v95
	v_add_f32_e32 v95, 1.0, v123
	v_pk_fma_f32 v[126:127], v[126:127], s[26:27], 0.5 op_sel_hi:[1,0,0]
	v_rcp_f32_e32 v131, v95
	v_cvt_u32_f32_e32 v95, v127
	v_cvt_u32_f32_e32 v107, v126
	v_pk_fma_f32 v[126:127], v[128:129], s[26:27], 0.5 op_sel_hi:[1,0,0]
	v_pk_fma_f32 v[124:125], v[124:125], s[26:27], 0.5 op_sel_hi:[1,0,0]
	v_cvt_u32_f32_e32 v123, v126
	v_cvt_u32_f32_e32 v126, v127
	v_cvt_u32_f32_sdwa v127, v124 dst_sel:WORD_1 dst_unused:UNUSED_PAD src0_sel:DWORD
	v_cvt_u32_f32_sdwa v128, v125 dst_sel:WORD_1 dst_unused:UNUSED_PAD src0_sel:DWORD
	v_pk_fma_f32 v[124:125], v[130:131], s[26:27], 0.5 op_sel_hi:[1,0,0]
	v_lshlrev_b32_e32 v123, 8, v123
	v_cvt_u32_f32_sdwa v124, v124 dst_sel:BYTE_3 dst_unused:UNUSED_PAD src0_sel:DWORD
	v_cvt_u32_f32_sdwa v125, v125 dst_sel:BYTE_3 dst_unused:UNUSED_PAD src0_sel:DWORD
	v_lshlrev_b32_e32 v126, 8, v126
	v_or_b32_e32 v107, v123, v107
	v_or_b32_e32 v95, v126, v95
	v_or_b32_e32 v107, v107, v127
	v_mad_i64_i32 v[126:127], s[4:5], v87, s33, v[110:111]
	v_lshl_add_u64 v[126:127], v[126:127], 0, v[108:109]
	v_or_b32_e32 v95, v95, v128
	v_add_co_u32_e32 v126, vcc, s12, v126
	v_or_b32_e32 v125, v95, v125
	v_or_b32_e32 v124, v107, v124
	v_addc_co_u32_e32 v127, vcc, 0, v127, vcc
	global_store_dwordx2 v[126:127], v[124:125], off
	v_pk_mul_f32 v[126:127], v[6:7], v[78:79] op_sel_hi:[1,0]
	v_pk_mul_f32 v[128:129], v[2:3], v[78:79] op_sel_hi:[1,0]
	v_mul_f32_e32 v95, 0xbfb8aa3b, v126
	v_exp_f32_e32 v95, v95
	v_mul_f32_e32 v107, 0xbfb8aa3b, v128
	v_exp_f32_e32 v107, v107
	v_mul_f32_e32 v123, 0xbfb8aa3b, v129
	v_add_f32_e32 v95, 1.0, v95
	v_rcp_f32_e32 v126, v95
	v_add_f32_e32 v95, 1.0, v107
	v_mul_f32_e32 v107, 0xbfb8aa3b, v127
	v_exp_f32_e32 v107, v107
	v_exp_f32_e32 v123, v123
	v_pk_mul_f32 v[124:125], v[8:9], v[78:79] op_sel_hi:[1,0]
	v_pk_mul_f32 v[130:131], v[4:5], v[78:79] op_sel_hi:[1,0]
	v_rcp_f32_e32 v127, v95
	v_add_f32_e32 v95, 1.0, v107
	v_mul_f32_e32 v107, 0xbfb8aa3b, v124
	v_rcp_f32_e32 v128, v95
	v_add_f32_e32 v95, 1.0, v123
	v_exp_f32_e32 v107, v107
	v_mul_f32_e32 v123, 0xbfb8aa3b, v130
	v_exp_f32_e32 v123, v123
	v_rcp_f32_e32 v129, v95
	v_add_f32_e32 v95, 1.0, v107
	v_mul_f32_e32 v107, 0xbfb8aa3b, v125
	v_rcp_f32_e32 v124, v95
	v_add_f32_e32 v95, 1.0, v123
	v_exp_f32_e32 v107, v107
	v_mul_f32_e32 v123, 0xbfb8aa3b, v131
	v_exp_f32_e32 v123, v123
	v_rcp_f32_e32 v125, v95
	v_add_f32_e32 v95, 1.0, v107
	v_rcp_f32_e32 v130, v95
	v_add_f32_e32 v95, 1.0, v123
	v_rcp_f32_e32 v131, v95
	v_pk_fma_f32 v[126:127], v[126:127], s[26:27], 0.5 op_sel_hi:[1,0,0]
	v_pk_fma_f32 v[124:125], v[124:125], s[26:27], 0.5 op_sel_hi:[1,0,0]
	v_cvt_u32_f32_e32 v95, v127
	v_cvt_u32_f32_e32 v107, v126
	v_pk_fma_f32 v[126:127], v[128:129], s[26:27], 0.5 op_sel_hi:[1,0,0]
	v_cvt_u32_f32_sdwa v128, v125 dst_sel:WORD_1 dst_unused:UNUSED_PAD src0_sel:DWORD
	v_cvt_u32_f32_e32 v123, v126
	v_cvt_u32_f32_e32 v126, v127
	v_cvt_u32_f32_sdwa v127, v124 dst_sel:WORD_1 dst_unused:UNUSED_PAD src0_sel:DWORD
	v_pk_fma_f32 v[124:125], v[130:131], s[26:27], 0.5 op_sel_hi:[1,0,0]
	v_lshlrev_b32_e32 v123, 8, v123
	v_cvt_u32_f32_sdwa v124, v124 dst_sel:BYTE_3 dst_unused:UNUSED_PAD src0_sel:DWORD
	v_cvt_u32_f32_sdwa v125, v125 dst_sel:BYTE_3 dst_unused:UNUSED_PAD src0_sel:DWORD
	v_lshlrev_b32_e32 v126, 8, v126
	v_mad_i64_i32 v[110:111], s[4:5], v85, s33, v[110:111]
	v_or_b32_e32 v95, v126, v95
	v_or_b32_e32 v107, v123, v107
	v_lshl_add_u64 v[108:109], v[110:111], 0, v[108:109]
	v_or_b32_e32 v95, v95, v128
	v_or_b32_e32 v107, v107, v127
	v_add_co_u32_e32 v108, vcc, 0x3000, v108
	v_or_b32_e32 v125, v95, v125
	v_or_b32_e32 v124, v107, v124
	v_addc_co_u32_e32 v109, vcc, 0, v109, vcc
	global_store_dwordx2 v[108:109], v[124:125], off
	s_mov_b64 s[4:5], 0

; __device__ __forceinline__ f32x4 un_unorm8(unsigned w) { return (f32x4){fmaxf((float)(w & 255u), 0.5f), fmaxf((float)((w >> 8) & 255u), 0.5f), fmaxf((float)((w >> 16) & 255u), 0.5f), fmaxf((float)(w >> 24), 0.5f)}; }
; #define EPI_OPAQUE asm volatile("" : "+v"(fr), "+v"(fq));
;     __device__ __forceinline__ void seam(f32x4 (&acc)[2][2][4][2], const Unit& u, int n, int wr, int wc, int fr, int fq) const {
;         EPI_OPAQUE
; #pragma unroll
;         for (int ai = 0; ai < 2; ++ai) {
;             u32x2 ga[4][2], gb[4][2];
; #pragma unroll
;             for (int m = 0; m < 4; ++m)
; #pragma unroll
;                 for (int bj = 0; bj < 2; ++bj) { const int row = u.pm * 256 + ai * 128 + wr * 64 + m * 16 + fr, col = u.pn * 256 + bj * 128 + wc * 32 + 8 * fq;
;                     const unsigned char* gp = (const unsigned char*)P + (size_t)row * ROWB + GATE_B0 + n * DM + col; ga[m][bj] = *(const u32x2*)gp; gb[m][bj] = *(const u32x2*)(gp + DM); }
; #pragma unroll
;             for (int m = 0; m < 4; ++m)
; #pragma unroll
;                 for (int bj = 0; bj < 2; ++bj) { const f32x4 a0 = un_unorm8(ga[m][bj].x), a1 = un_unorm8(ga[m][bj].y), b0 = un_unorm8(gb[m][bj].x), b1 = un_unorm8(gb[m][bj].y);
; #pragma unroll
;                     for (int j = 0; j < 4; ++j) { acc[ai][bj][m][0][j] *= a0[j] * __builtin_amdgcn_rcpf(b0[j]); acc[ai][bj][m][1][j] *= a1[j] * __builtin_amdgcn_rcpf(b1[j]); } }
;             asm volatile("" ::: "memory");
;         }
;     }
.Lsm_a:
	s_lshr_b32 s98, s42, 7
	s_bfe_u32 s99, s42, 0x10006
	s_or_b32 s98, s98, s99
	v_mov_b32_e32 v1, s98
	v_mov_b32_e32 v2, v181
	s_cmpk_eq_i32 s54, 0x800
	v_add_u32_e32 v1, s20, v1
	v_add_u32_e32 v154, s8, v1
	v_mov_b64_e32 v[148:149], s[68:69]
	s_cselect_b32 s56, 0, 0x800
	s_and_b32 s99, s42, 32
	s_lshl_b32 s99, s99, 4
	v_lshl_add_u32 v2, v2, 7, s99
	v_lshl_add_u32 v2, v180, 3, v2
	v_mad_i64_i32 v[150:151], s[4:5], v154, s33, v[148:149]
	v_ashrrev_i32_e32 v3, 31, v2
	v_lshl_add_u64 v[150:151], v[150:151], 0, s[56:57]
	v_lshl_add_u64 v[150:151], v[150:151], 0, v[2:3]
	v_lshl_add_u64 v[152:153], v[150:151], 0, s[64:65]
	v_add_co_u32_e32 v150, vcc, s12, v150
	global_load_dwordx2 v[184:185], v[152:153], off offset:2048
	s_nop 0
	v_addc_co_u32_e32 v151, vcc, 0, v151, vcc
	global_load_dwordx2 v[186:187], v[150:151], off
	global_load_dwordx2 v[208:209], v[152:153], off offset:3072
	global_load_dwordx2 v[210:211], v[152:153], off offset:1024
	v_add_u32_e32 v150, 16, v154
	v_add_u32_e32 v156, 48, v154
	v_mad_i64_i32 v[150:151], s[4:5], v150, s33, v[148:149]
	v_mad_i64_i32 v[156:157], s[4:5], v156, s33, v[148:149]
	v_lshl_add_u64 v[150:151], v[150:151], 0, s[56:57]
	v_lshl_add_u64 v[156:157], v[156:157], 0, s[56:57]
	v_lshl_add_u64 v[150:151], v[150:151], 0, v[2:3]
	v_lshl_add_u64 v[152:153], v[156:157], 0, v[2:3]
	v_lshl_add_u64 v[156:157], v[150:151], 0, s[64:65]
	v_add_co_u32_e32 v150, vcc, s12, v150
	v_add_u32_e32 v155, 32, v154
	s_nop 0
	v_addc_co_u32_e32 v151, vcc, 0, v151, vcc
	global_load_dwordx2 v[176:177], v[156:157], off offset:2048
	global_load_dwordx2 v[178:179], v[150:151], off
	global_load_dwordx2 v[172:173], v[156:157], off offset:3072
	global_load_dwordx2 v[174:175], v[156:157], off offset:1024
	v_mad_i64_i32 v[154:155], s[4:5], v155, s33, v[148:149]
	v_lshl_add_u64 v[154:155], v[154:155], 0, s[56:57]
	v_lshl_add_u64 v[154:155], v[154:155], 0, v[2:3]
	v_lshl_add_u64 v[160:161], v[154:155], 0, s[64:65]
	v_add_co_u32_e32 v154, vcc, s12, v154
	v_lshl_add_u64 v[212:213], v[152:153], 0, s[64:65]
	s_nop 0
	v_addc_co_u32_e32 v155, vcc, 0, v155, vcc
	global_load_dwordx2 v[168:169], v[160:161], off offset:2048
	global_load_dwordx2 v[170:171], v[154:155], off
	global_load_dwordx2 v[158:159], v[160:161], off offset:3072
	s_nop 0
	global_load_dwordx2 v[160:161], v[160:161], off offset:1024
	v_add_co_u32_e32 v150, vcc, s12, v152
	v_add_u32_e32 v1, s43, v1
	s_nop 0
	v_addc_co_u32_e32 v151, vcc, 0, v153, vcc
	global_load_dwordx2 v[154:155], v[212:213], off offset:2048
	global_load_dwordx2 v[156:157], v[150:151], off
	s_nop 0
	global_load_dwordx2 v[150:151], v[212:213], off offset:3072
	global_load_dwordx2 v[152:153], v[212:213], off offset:1024
	s_waitcnt vmcnt(0)
	v_cvt_f32_ubyte0_e32 v212, v184
	v_cvt_f32_ubyte1_e32 v213, v184
	v_cvt_f32_ubyte2_e32 v214, v184
	v_cvt_f32_ubyte0_e32 v219, v187
	v_cvt_f32_ubyte3_e32 v184, v184
	v_cvt_f32_ubyte3_e32 v218, v186
	v_max_f32_e32 v225, 0.5, v214
	v_max_f32_e32 v214, 0.5, v219
	v_max_f32_e32 v219, 0.5, v184
	v_cvt_f32_ubyte0_e32 v184, v185
	v_cvt_f32_ubyte2_e32 v217, v186
	v_cvt_f32_ubyte3_e32 v222, v187
	v_max_f32_e32 v224, 0.5, v213
	v_max_f32_e32 v213, 0.5, v218
	v_max_f32_e32 v218, 0.5, v184
	v_cvt_f32_ubyte1_e32 v184, v185
	v_max_f32_e32 v223, 0.5, v212
	v_max_f32_e32 v212, 0.5, v217
	v_max_f32_e32 v217, 0.5, v222
	v_max_f32_e32 v222, 0.5, v184
	v_cvt_f32_ubyte2_e32 v184, v185
	v_cvt_f32_ubyte0_e32 v215, v186
	v_cvt_f32_ubyte1_e32 v216, v186
	v_cvt_f32_ubyte1_e32 v220, v187
	v_cvt_f32_ubyte2_e32 v221, v187
	v_max_f32_e32 v226, 0.5, v184
	v_cvt_f32_ubyte3_e32 v184, v185
	v_max_f32_e32 v186, 0.5, v215
	v_max_f32_e32 v187, 0.5, v216
	v_max_f32_e32 v215, 0.5, v220
	v_max_f32_e32 v216, 0.5, v221
	v_max_f32_e32 v227, 0.5, v184
	v_rcp_f32_e32 v184, v223
	v_rcp_f32_e32 v185, v224
	v_rcp_f32_e32 v220, v225
	v_rcp_f32_e32 v221, v219
	v_rcp_f32_e32 v218, v218
	v_rcp_f32_e32 v219, v222
	v_rcp_f32_e32 v222, v226
	v_rcp_f32_e32 v223, v227
	v_pk_mul_f32 v[184:185], v[186:187], v[184:185]
	v_pk_mul_f32 v[186:187], v[212:213], v[220:221]
	v_pk_mul_f32 v[128:129], v[128:129], v[184:185]
	v_pk_mul_f32 v[130:131], v[130:131], v[186:187]
	v_pk_mul_f32 v[184:185], v[214:215], v[218:219]
	v_pk_mul_f32 v[186:187], v[216:217], v[222:223]
	v_cvt_f32_ubyte0_e32 v214, v208
	v_cvt_f32_ubyte1_e32 v215, v208
	v_cvt_f32_ubyte2_e32 v216, v208
	v_cvt_f32_ubyte3_e32 v208, v208
	v_max_f32_e32 v217, 0.5, v208
	v_cvt_f32_ubyte0_e32 v208, v209
	v_max_f32_e32 v218, 0.5, v208
	v_cvt_f32_ubyte1_e32 v208, v209
	v_max_f32_e32 v219, 0.5, v208
	v_cvt_f32_ubyte2_e32 v208, v209
	v_max_f32_e32 v214, 0.5, v214
	v_max_f32_e32 v215, 0.5, v215
	v_max_f32_e32 v216, 0.5, v216
	v_max_f32_e32 v220, 0.5, v208
	v_cvt_f32_ubyte3_e32 v208, v209
	v_max_f32_e32 v221, 0.5, v208
	v_rcp_f32_e32 v208, v214
	v_rcp_f32_e32 v209, v215
	v_rcp_f32_e32 v216, v216
	v_rcp_f32_e32 v217, v217
	v_pk_mul_f32 v[126:127], v[126:127], v[186:187]
	v_pk_mul_f32 v[124:125], v[124:125], v[184:185]
	v_cvt_f32_ubyte0_e32 v184, v210
	v_cvt_f32_ubyte1_e32 v185, v210
	v_cvt_f32_ubyte2_e32 v186, v210
	v_cvt_f32_ubyte3_e32 v187, v210
	v_cvt_f32_ubyte0_e32 v210, v211
	v_rcp_f32_e32 v214, v218
	v_rcp_f32_e32 v215, v219
	v_rcp_f32_e32 v218, v220
	v_rcp_f32_e32 v219, v221
	v_max_f32_e32 v212, 0.5, v210
	v_cvt_f32_ubyte1_e32 v210, v211
	v_max_f32_e32 v184, 0.5, v184
	v_max_f32_e32 v185, 0.5, v185
	v_max_f32_e32 v186, 0.5, v186
	v_max_f32_e32 v187, 0.5, v187
	v_max_f32_e32 v213, 0.5, v210
	v_cvt_f32_ubyte2_e32 v210, v211
	v_cvt_f32_ubyte3_e32 v211, v211
	v_max_f32_e32 v210, 0.5, v210
	v_max_f32_e32 v211, 0.5, v211
	v_pk_mul_f32 v[184:185], v[184:185], v[208:209]
	v_pk_mul_f32 v[186:187], v[186:187], v[216:217]
; __device__ __forceinline__ f32x4 un_unorm8(unsigned w) { return (f32x4){fmaxf((float)(w & 255u), 0.5f), fmaxf((float)((w >> 8) & 255u), 0.5f), fmaxf((float)((w >> 16) & 255u), 0.5f), fmaxf((float)(w >> 24), 0.5f)}; }
; #define EPI_OPAQUE asm volatile("" : "+v"(fr), "+v"(fq));
;     __device__ __forceinline__ void seam(f32x4 (&acc)[2][2][4][2], const Unit& u, int n, int wr, int wc, int fr, int fq) const {
;         EPI_OPAQUE
; #pragma unroll
;         for (int ai = 0; ai < 2; ++ai) {
;             u32x2 ga[4][2], gb[4][2];
; #pragma unroll
;             for (int m = 0; m < 4; ++m)
; #pragma unroll
;                 for (int bj = 0; bj < 2; ++bj) { const int row = u.pm * 256 + ai * 128 + wr * 64 + m * 16 + fr, col = u.pn * 256 + bj * 128 + wc * 32 + 8 * fq;
;                     const unsigned char* gp = (const unsigned char*)P + (size_t)row * ROWB + GATE_B0 + n * DM + col; ga[m][bj] = *(const u32x2*)gp; gb[m][bj] = *(const u32x2*)(gp + DM); }
; #pragma unroll
;             for (int m = 0; m < 4; ++m)
; #pragma unroll
;                 for (int bj = 0; bj < 2; ++bj) { const f32x4 a0 = un_unorm8(ga[m][bj].x), a1 = un_unorm8(ga[m][bj].y), b0 = un_unorm8(gb[m][bj].x), b1 = un_unorm8(gb[m][bj].y);
; #pragma unroll
;                     for (int j = 0; j < 4; ++j) { acc[ai][bj][m][0][j] *= a0[j] * __builtin_amdgcn_rcpf(b0[j]); acc[ai][bj][m][1][j] *= a1[j] * __builtin_amdgcn_rcpf(b1[j]); } }
;             asm volatile("" ::: "memory");
;         }
;     }
	v_pk_mul_f32 v[120:121], v[120:121], v[184:185]
	v_pk_mul_f32 v[122:123], v[122:123], v[186:187]
	v_pk_mul_f32 v[184:185], v[212:213], v[214:215]
	v_pk_mul_f32 v[186:187], v[210:211], v[218:219]
	v_cvt_f32_ubyte0_e32 v210, v176
	v_cvt_f32_ubyte1_e32 v211, v176
	v_cvt_f32_ubyte2_e32 v212, v176
	v_cvt_f32_ubyte3_e32 v176, v176
	v_max_f32_e32 v213, 0.5, v176
	v_cvt_f32_ubyte0_e32 v176, v177
	v_max_f32_e32 v214, 0.5, v176
	v_cvt_f32_ubyte1_e32 v176, v177
	v_max_f32_e32 v215, 0.5, v176
	v_cvt_f32_ubyte2_e32 v176, v177
	v_max_f32_e32 v210, 0.5, v210
	v_max_f32_e32 v211, 0.5, v211
	v_max_f32_e32 v216, 0.5, v176
	v_cvt_f32_ubyte3_e32 v176, v177
	v_max_f32_e32 v212, 0.5, v212
	v_max_f32_e32 v217, 0.5, v176
	v_rcp_f32_e32 v176, v210
	v_rcp_f32_e32 v177, v211
	v_pk_mul_f32 v[118:119], v[118:119], v[186:187]
	v_pk_mul_f32 v[116:117], v[116:117], v[184:185]
	v_cvt_f32_ubyte0_e32 v184, v178
	v_cvt_f32_ubyte1_e32 v185, v178
	v_cvt_f32_ubyte2_e32 v186, v178
	v_cvt_f32_ubyte3_e32 v178, v178
	v_rcp_f32_e32 v210, v214
	v_rcp_f32_e32 v212, v212
	v_rcp_f32_e32 v213, v213
	v_rcp_f32_e32 v211, v215
	v_max_f32_e32 v187, 0.5, v178
	v_cvt_f32_ubyte0_e32 v178, v179
	v_max_f32_e32 v184, 0.5, v184
	v_max_f32_e32 v185, 0.5, v185
	v_max_f32_e32 v208, 0.5, v178
	v_cvt_f32_ubyte1_e32 v178, v179
	v_max_f32_e32 v186, 0.5, v186
	v_max_f32_e32 v209, 0.5, v178
	v_pk_mul_f32 v[176:177], v[184:185], v[176:177]
	v_pk_mul_f32 v[184:185], v[186:187], v[212:213]
	v_pk_mul_f32 v[112:113], v[112:113], v[176:177]
	v_pk_mul_f32 v[176:177], v[208:209], v[210:211]
	v_cvt_f32_ubyte0_e32 v186, v172
	v_cvt_f32_ubyte1_e32 v187, v172
	v_cvt_f32_ubyte2_e32 v208, v172
	v_cvt_f32_ubyte3_e32 v172, v172
	v_rcp_f32_e32 v214, v216
	v_rcp_f32_e32 v215, v217
	v_max_f32_e32 v209, 0.5, v172
	v_cvt_f32_ubyte0_e32 v172, v173
	v_max_f32_e32 v210, 0.5, v172
	v_cvt_f32_ubyte1_e32 v172, v173
	v_cvt_f32_ubyte2_e32 v178, v179
	v_cvt_f32_ubyte3_e32 v179, v179
	v_max_f32_e32 v211, 0.5, v172
	v_cvt_f32_ubyte2_e32 v172, v173
	v_max_f32_e32 v178, 0.5, v178
	v_max_f32_e32 v179, 0.5, v179
	v_max_f32_e32 v186, 0.5, v186
	v_max_f32_e32 v187, 0.5, v187
	v_max_f32_e32 v212, 0.5, v172
	v_cvt_f32_ubyte3_e32 v172, v173
	v_pk_mul_f32 v[178:179], v[178:179], v[214:215]
	v_max_f32_e32 v208, 0.5, v208
	v_max_f32_e32 v213, 0.5, v172
	v_rcp_f32_e32 v172, v186
	v_rcp_f32_e32 v173, v187
	v_pk_mul_f32 v[110:111], v[110:111], v[178:179]
	v_pk_mul_f32 v[108:109], v[108:109], v[176:177]
	v_cvt_f32_ubyte0_e32 v176, v174
	v_cvt_f32_ubyte1_e32 v177, v174
	v_cvt_f32_ubyte2_e32 v178, v174
	v_cvt_f32_ubyte3_e32 v174, v174
	v_rcp_f32_e32 v186, v210
	v_rcp_f32_e32 v208, v208
	v_rcp_f32_e32 v209, v209
	v_rcp_f32_e32 v187, v211
	v_max_f32_e32 v179, 0.5, v174
	v_cvt_f32_ubyte0_e32 v174, v175
	v_pk_mul_f32 v[114:115], v[114:115], v[184:185]
	v_max_f32_e32 v176, 0.5, v176
	v_max_f32_e32 v177, 0.5, v177
	v_max_f32_e32 v184, 0.5, v174
	v_cvt_f32_ubyte1_e32 v174, v175
	v_max_f32_e32 v178, 0.5, v178
	v_max_f32_e32 v185, 0.5, v174
	v_pk_mul_f32 v[172:173], v[176:177], v[172:173]
	v_pk_mul_f32 v[176:177], v[178:179], v[208:209]
	v_pk_mul_f32 v[104:105], v[104:105], v[172:173]
	v_pk_mul_f32 v[172:173], v[184:185], v[186:187]
	v_cvt_f32_ubyte0_e32 v178, v168
	v_cvt_f32_ubyte1_e32 v179, v168
	v_cvt_f32_ubyte2_e32 v184, v168
	v_cvt_f32_ubyte3_e32 v168, v168
	v_rcp_f32_e32 v210, v212
	v_rcp_f32_e32 v211, v213
	v_max_f32_e32 v185, 0.5, v168
	v_cvt_f32_ubyte0_e32 v168, v169
	v_max_f32_e32 v186, 0.5, v168
	v_cvt_f32_ubyte1_e32 v168, v169
	v_cvt_f32_ubyte2_e32 v174, v175
	v_cvt_f32_ubyte3_e32 v175, v175
	v_max_f32_e32 v187, 0.5, v168
	v_cvt_f32_ubyte2_e32 v168, v169
	v_max_f32_e32 v174, 0.5, v174
	v_max_f32_e32 v175, 0.5, v175
	v_max_f32_e32 v178, 0.5, v178
	v_max_f32_e32 v179, 0.5, v179
	v_max_f32_e32 v208, 0.5, v168
	v_cvt_f32_ubyte3_e32 v168, v169
	v_pk_mul_f32 v[174:175], v[174:175], v[210:211]
	v_max_f32_e32 v184, 0.5, v184
	v_max_f32_e32 v209, 0.5, v168
	v_rcp_f32_e32 v168, v178
	v_rcp_f32_e32 v169, v179
	v_pk_mul_f32 v[102:103], v[102:103], v[174:175]
	v_pk_mul_f32 v[100:101], v[100:101], v[172:173]
	v_cvt_f32_ubyte0_e32 v172, v170
	v_cvt_f32_ubyte1_e32 v173, v170
	v_cvt_f32_ubyte2_e32 v174, v170
	v_cvt_f32_ubyte3_e32 v170, v170
	v_rcp_f32_e32 v178, v186
	v_rcp_f32_e32 v184, v184
	v_rcp_f32_e32 v185, v185
	v_rcp_f32_e32 v179, v187
	v_max_f32_e32 v175, 0.5, v170
	v_cvt_f32_ubyte0_e32 v170, v171
	v_pk_mul_f32 v[106:107], v[106:107], v[176:177]
	v_max_f32_e32 v172, 0.5, v172
	v_max_f32_e32 v173, 0.5, v173
	v_max_f32_e32 v176, 0.5, v170
	v_cvt_f32_ubyte1_e32 v170, v171
	v_max_f32_e32 v174, 0.5, v174
	v_max_f32_e32 v177, 0.5, v170
	v_pk_mul_f32 v[168:169], v[172:173], v[168:169]
	v_pk_mul_f32 v[172:173], v[174:175], v[184:185]
	v_pk_mul_f32 v[96:97], v[96:97], v[168:169]
	v_pk_mul_f32 v[168:169], v[176:177], v[178:179]
	v_cvt_f32_ubyte0_e32 v174, v158
	v_cvt_f32_ubyte1_e32 v175, v158
	v_cvt_f32_ubyte2_e32 v176, v158
	v_cvt_f32_ubyte3_e32 v158, v158
	v_rcp_f32_e32 v186, v208
	v_rcp_f32_e32 v187, v209
	v_max_f32_e32 v177, 0.5, v158
	v_cvt_f32_ubyte0_e32 v158, v159
	v_max_f32_e32 v178, 0.5, v158
	v_cvt_f32_ubyte1_e32 v158, v159
	v_cvt_f32_ubyte2_e32 v170, v171
	v_cvt_f32_ubyte3_e32 v171, v171
	v_max_f32_e32 v179, 0.5, v158
	v_cvt_f32_ubyte2_e32 v158, v159
	v_max_f32_e32 v170, 0.5, v170
	v_max_f32_e32 v171, 0.5, v171
	v_max_f32_e32 v174, 0.5, v174
	v_max_f32_e32 v175, 0.5, v175
	v_max_f32_e32 v184, 0.5, v158
	v_cvt_f32_ubyte3_e32 v158, v159
	v_pk_mul_f32 v[170:171], v[170:171], v[186:187]
	v_max_f32_e32 v176, 0.5, v176
	v_max_f32_e32 v185, 0.5, v158
	v_rcp_f32_e32 v158, v174
	v_rcp_f32_e32 v159, v175
	v_pk_mul_f32 v[94:95], v[94:95], v[170:171]
; __device__ __forceinline__ f32x4 un_unorm8(unsigned w) { return (f32x4){fmaxf((float)(w & 255u), 0.5f), fmaxf((float)((w >> 8) & 255u), 0.5f), fmaxf((float)((w >> 16) & 255u), 0.5f), fmaxf((float)(w >> 24), 0.5f)}; }
; #define EPI_OPAQUE asm volatile("" : "+v"(fr), "+v"(fq));
;     __device__ __forceinline__ void seam(f32x4 (&acc)[2][2][4][2], const Unit& u, int n, int wr, int wc, int fr, int fq) const {
;         EPI_OPAQUE
; #pragma unroll
;         for (int ai = 0; ai < 2; ++ai) {
;             u32x2 ga[4][2], gb[4][2];
; #pragma unroll
;             for (int m = 0; m < 4; ++m)
; #pragma unroll
;                 for (int bj = 0; bj < 2; ++bj) { const int row = u.pm * 256 + ai * 128 + wr * 64 + m * 16 + fr, col = u.pn * 256 + bj * 128 + wc * 32 + 8 * fq;
;                     const unsigned char* gp = (const unsigned char*)P + (size_t)row * ROWB + GATE_B0 + n * DM + col; ga[m][bj] = *(const u32x2*)gp; gb[m][bj] = *(const u32x2*)(gp + DM); }
; #pragma unroll
;             for (int m = 0; m < 4; ++m)
; #pragma unroll
;                 for (int bj = 0; bj < 2; ++bj) { const f32x4 a0 = un_unorm8(ga[m][bj].x), a1 = un_unorm8(ga[m][bj].y), b0 = un_unorm8(gb[m][bj].x), b1 = un_unorm8(gb[m][bj].y);
; #pragma unroll
;                     for (int j = 0; j < 4; ++j) { acc[ai][bj][m][0][j] *= a0[j] * __builtin_amdgcn_rcpf(b0[j]); acc[ai][bj][m][1][j] *= a1[j] * __builtin_amdgcn_rcpf(b1[j]); } }
;             asm volatile("" ::: "memory");
;         }
;     }
	v_pk_mul_f32 v[92:93], v[92:93], v[168:169]
	v_cvt_f32_ubyte0_e32 v168, v160
	v_cvt_f32_ubyte1_e32 v169, v160
	v_cvt_f32_ubyte2_e32 v170, v160
	v_cvt_f32_ubyte3_e32 v160, v160
	v_rcp_f32_e32 v174, v178
	v_rcp_f32_e32 v176, v176
	v_rcp_f32_e32 v177, v177
	v_rcp_f32_e32 v175, v179
	v_max_f32_e32 v171, 0.5, v160
	v_cvt_f32_ubyte0_e32 v160, v161
	v_pk_mul_f32 v[98:99], v[98:99], v[172:173]
	v_max_f32_e32 v168, 0.5, v168
	v_max_f32_e32 v169, 0.5, v169
	v_max_f32_e32 v172, 0.5, v160
	v_cvt_f32_ubyte1_e32 v160, v161
	v_max_f32_e32 v170, 0.5, v170
	v_max_f32_e32 v173, 0.5, v160
	v_pk_mul_f32 v[158:159], v[168:169], v[158:159]
	v_pk_mul_f32 v[168:169], v[170:171], v[176:177]
	v_pk_mul_f32 v[88:89], v[88:89], v[158:159]
	v_pk_mul_f32 v[158:159], v[172:173], v[174:175]
	v_cvt_f32_ubyte0_e32 v170, v154
	v_cvt_f32_ubyte1_e32 v171, v154
	v_cvt_f32_ubyte2_e32 v172, v154
	v_cvt_f32_ubyte3_e32 v154, v154
	v_max_f32_e32 v173, 0.5, v154
	v_cvt_f32_ubyte0_e32 v154, v155
	v_rcp_f32_e32 v178, v184
	v_rcp_f32_e32 v179, v185
	v_max_f32_e32 v174, 0.5, v154
	v_cvt_f32_ubyte1_e32 v154, v155
	v_max_f32_e32 v175, 0.5, v154
	v_cvt_f32_ubyte2_e32 v154, v155
	v_cvt_f32_ubyte2_e32 v160, v161
	v_cvt_f32_ubyte3_e32 v161, v161
	v_max_f32_e32 v170, 0.5, v170
	v_max_f32_e32 v171, 0.5, v171
	v_max_f32_e32 v172, 0.5, v172
	v_max_f32_e32 v176, 0.5, v154
	v_cvt_f32_ubyte3_e32 v154, v155
	v_max_f32_e32 v160, 0.5, v160
	v_max_f32_e32 v161, 0.5, v161
	v_max_f32_e32 v177, 0.5, v154
	v_rcp_f32_e32 v154, v170
	v_rcp_f32_e32 v155, v171
	v_rcp_f32_e32 v172, v172
	v_rcp_f32_e32 v173, v173
	v_pk_mul_f32 v[160:161], v[160:161], v[178:179]
	v_pk_mul_f32 v[84:85], v[84:85], v[158:159]
	v_pk_mul_f32 v[86:87], v[86:87], v[160:161]
	v_cvt_f32_ubyte0_e32 v158, v156
	v_cvt_f32_ubyte1_e32 v159, v156
	v_cvt_f32_ubyte2_e32 v160, v156
	v_cvt_f32_ubyte3_e32 v156, v156
	v_max_f32_e32 v158, 0.5, v158
	v_max_f32_e32 v159, 0.5, v159
	v_max_f32_e32 v160, 0.5, v160
	v_max_f32_e32 v161, 0.5, v156
	v_rcp_f32_e32 v170, v174
	v_rcp_f32_e32 v171, v175
	v_cvt_f32_ubyte0_e32 v156, v157
	v_pk_mul_f32 v[154:155], v[158:159], v[154:155]
	v_pk_mul_f32 v[158:159], v[160:161], v[172:173]
	v_mad_i64_i32 v[160:161], s[4:5], v1, s33, v[148:149]
	v_pk_mul_f32 v[90:91], v[90:91], v[168:169]
	v_max_f32_e32 v168, 0.5, v156
	v_cvt_f32_ubyte1_e32 v156, v157
	v_lshl_add_u64 v[160:161], v[160:161], 0, s[56:57]
	v_max_f32_e32 v169, 0.5, v156
	v_lshl_add_u64 v[160:161], v[160:161], 0, v[2:3]
	v_pk_mul_f32 v[80:81], v[80:81], v[154:155]
	v_pk_mul_f32 v[154:155], v[168:169], v[170:171]
	v_add_co_u32_e32 v168, vcc, s12, v160
	v_rcp_f32_e32 v174, v176
	s_nop 0
	v_addc_co_u32_e32 v169, vcc, 0, v161, vcc
	global_load_dwordx2 v[172:173], v[168:169], off
	v_rcp_f32_e32 v175, v177
	v_cvt_f32_ubyte2_e32 v156, v157
	v_cvt_f32_ubyte3_e32 v157, v157
	v_max_f32_e32 v156, 0.5, v156
	v_max_f32_e32 v157, 0.5, v157
	v_lshl_add_u64 v[160:161], v[160:161], 0, s[64:65]
	v_pk_mul_f32 v[156:157], v[156:157], v[174:175]
	global_load_dwordx2 v[174:175], v[160:161], off offset:2048
	v_cvt_f32_ubyte0_e32 v168, v150
	v_cvt_f32_ubyte1_e32 v169, v150
	v_cvt_f32_ubyte2_e32 v170, v150
	v_cvt_f32_ubyte3_e32 v150, v150
	v_max_f32_e32 v171, 0.5, v150
	v_cvt_f32_ubyte0_e32 v150, v151
	v_max_f32_e32 v176, 0.5, v150
	v_cvt_f32_ubyte1_e32 v150, v151
	v_max_f32_e32 v177, 0.5, v150
	v_cvt_f32_ubyte2_e32 v150, v151
	v_max_f32_e32 v178, 0.5, v150
	v_cvt_f32_ubyte3_e32 v150, v151
	v_pk_mul_f32 v[78:79], v[78:79], v[156:157]
	v_pk_mul_f32 v[76:77], v[76:77], v[154:155]
	v_cvt_f32_ubyte0_e32 v154, v152
	v_cvt_f32_ubyte1_e32 v155, v152
	v_cvt_f32_ubyte2_e32 v156, v152
	v_cvt_f32_ubyte3_e32 v152, v152
	v_max_f32_e32 v168, 0.5, v168
	v_max_f32_e32 v169, 0.5, v169
	v_max_f32_e32 v179, 0.5, v150
	v_max_f32_e32 v157, 0.5, v152
	v_cvt_f32_ubyte0_e32 v152, v153
	v_rcp_f32_e32 v150, v168
	v_rcp_f32_e32 v168, v176
	v_rcp_f32_e32 v151, v169
	v_rcp_f32_e32 v169, v177
	v_rcp_f32_e32 v176, v178
	v_rcp_f32_e32 v177, v179
	v_pk_mul_f32 v[82:83], v[82:83], v[158:159]
	v_max_f32_e32 v158, 0.5, v152
	v_cvt_f32_ubyte1_e32 v152, v153
	v_max_f32_e32 v159, 0.5, v152
	v_cvt_f32_ubyte2_e32 v152, v153
	v_cvt_f32_ubyte3_e32 v153, v153
	v_max_f32_e32 v152, 0.5, v152
	v_max_f32_e32 v153, 0.5, v153
	v_pk_mul_f32 v[152:153], v[152:153], v[176:177]
	global_load_dwordx2 v[176:177], v[160:161], off offset:3072
	global_load_dwordx2 v[178:179], v[160:161], off offset:1024
	v_max_f32_e32 v154, 0.5, v154
	v_max_f32_e32 v155, 0.5, v155
	v_pk_mul_f32 v[150:151], v[154:155], v[150:151]
	v_max_f32_e32 v170, 0.5, v170
	v_pk_mul_f32 v[72:73], v[72:73], v[150:151]
	v_pk_mul_f32 v[150:151], v[158:159], v[168:169]
	v_rcp_f32_e32 v170, v170
	v_pk_mul_f32 v[68:69], v[68:69], v[150:151]
	v_add_u32_e32 v150, 16, v1
	v_mad_i64_i32 v[150:151], s[4:5], v150, s33, v[148:149]
	v_rcp_f32_e32 v171, v171
	v_lshl_add_u64 v[150:151], v[150:151], 0, s[56:57]
	v_lshl_add_u64 v[150:151], v[150:151], 0, v[2:3]
	v_pk_mul_f32 v[70:71], v[70:71], v[152:153]
	v_lshl_add_u64 v[152:153], v[150:151], 0, s[64:65]
	v_add_co_u32_e32 v150, vcc, s12, v150
	v_max_f32_e32 v156, 0.5, v156
	s_nop 0
	v_addc_co_u32_e32 v151, vcc, 0, v151, vcc
	v_pk_mul_f32 v[154:155], v[156:157], v[170:171]
	global_load_dwordx2 v[184:185], v[150:151], off
	global_load_dwordx2 v[186:187], v[152:153], off offset:2048
	global_load_dwordx2 v[168:169], v[152:153], off offset:3072
	global_load_dwordx2 v[170:171], v[152:153], off offset:1024
	v_add_u32_e32 v150, 32, v1
	v_mad_i64_i32 v[150:151], s[4:5], v150, s33, v[148:149]
	v_lshl_add_u64 v[150:151], v[150:151], 0, s[56:57]
	v_lshl_add_u64 v[150:151], v[150:151], 0, v[2:3]
	v_lshl_add_u64 v[152:153], v[150:151], 0, s[64:65]
	v_add_co_u32_e32 v150, vcc, s12, v150
	v_pk_mul_f32 v[74:75], v[74:75], v[154:155]
	s_nop 0
	v_addc_co_u32_e32 v151, vcc, 0, v151, vcc
	global_load_dwordx2 v[160:161], v[150:151], off
	global_load_dwordx2 v[158:159], v[152:153], off offset:2048
	global_load_dwordx2 v[154:155], v[152:153], off offset:3072
	global_load_dwordx2 v[156:157], v[152:153], off offset:1024
	v_add_u32_e32 v1, 48, v1
	v_mad_i64_i32 v[148:149], s[4:5], v1, s33, v[148:149]
	s_waitcnt vmcnt(0)
; __device__ __forceinline__ f32x4 un_unorm8(unsigned w) { return (f32x4){fmaxf((float)(w & 255u), 0.5f), fmaxf((float)((w >> 8) & 255u), 0.5f), fmaxf((float)((w >> 16) & 255u), 0.5f), fmaxf((float)(w >> 24), 0.5f)}; }
; #define EPI_OPAQUE asm volatile("" : "+v"(fr), "+v"(fq));
;     __device__ __forceinline__ void seam(f32x4 (&acc)[2][2][4][2], const Unit& u, int n, int wr, int wc, int fr, int fq) const {
;         EPI_OPAQUE
; #pragma unroll
;         for (int ai = 0; ai < 2; ++ai) {
;             u32x2 ga[4][2], gb[4][2];
; #pragma unroll
;             for (int m = 0; m < 4; ++m)
; #pragma unroll
;                 for (int bj = 0; bj < 2; ++bj) { const int row = u.pm * 256 + ai * 128 + wr * 64 + m * 16 + fr, col = u.pn * 256 + bj * 128 + wc * 32 + 8 * fq;
;                     const unsigned char* gp = (const unsigned char*)P + (size_t)row * ROWB + GATE_B0 + n * DM + col; ga[m][bj] = *(const u32x2*)gp; gb[m][bj] = *(const u32x2*)(gp + DM); }
; #pragma unroll
;             for (int m = 0; m < 4; ++m)
; #pragma unroll
;                 for (int bj = 0; bj < 2; ++bj) { const f32x4 a0 = un_unorm8(ga[m][bj].x), a1 = un_unorm8(ga[m][bj].y), b0 = un_unorm8(gb[m][bj].x), b1 = un_unorm8(gb[m][bj].y);
; #pragma unroll
;                     for (int j = 0; j < 4; ++j) { acc[ai][bj][m][0][j] *= a0[j] * __builtin_amdgcn_rcpf(b0[j]); acc[ai][bj][m][1][j] *= a1[j] * __builtin_amdgcn_rcpf(b1[j]); } }
;             asm volatile("" ::: "memory");
;         }
;     }
	v_cvt_f32_ubyte0_e32 v1, v172
	v_max_f32_e32 v208, 0.5, v1
	v_cvt_f32_ubyte1_e32 v1, v172
	v_max_f32_e32 v209, 0.5, v1
	v_cvt_f32_ubyte2_e32 v1, v172
	v_max_f32_e32 v210, 0.5, v1
	v_cvt_f32_ubyte3_e32 v1, v172
	v_max_f32_e32 v211, 0.5, v1
	v_cvt_f32_ubyte0_e32 v1, v173
	v_max_f32_e32 v212, 0.5, v1
	v_cvt_f32_ubyte1_e32 v1, v173
	v_max_f32_e32 v213, 0.5, v1
	v_cvt_f32_ubyte2_e32 v1, v173
	v_max_f32_e32 v172, 0.5, v1
	v_cvt_f32_ubyte3_e32 v1, v173
	v_cvt_f32_ubyte1_e32 v214, v174
	v_max_f32_e32 v173, 0.5, v1
	v_cvt_f32_ubyte0_e32 v1, v174
	v_max_f32_e32 v215, 0.5, v214
	v_cvt_f32_ubyte2_e32 v214, v174
	v_cvt_f32_ubyte3_e32 v174, v174
	v_max_f32_e32 v217, 0.5, v174
	v_cvt_f32_ubyte0_e32 v174, v175
	v_max_f32_e32 v216, 0.5, v214
	v_max_f32_e32 v214, 0.5, v174
	v_cvt_f32_ubyte1_e32 v174, v175
	v_max_f32_e32 v218, 0.5, v174
	v_cvt_f32_ubyte2_e32 v174, v175
	v_max_f32_e32 v219, 0.5, v174
	v_cvt_f32_ubyte3_e32 v174, v175
	v_max_f32_e32 v220, 0.5, v174
	v_max_f32_e32 v1, 0.5, v1
	v_rcp_f32_e32 v175, v215
	v_rcp_f32_e32 v215, v218
	v_rcp_f32_e32 v218, v219
	v_rcp_f32_e32 v219, v220
	v_rcp_f32_e32 v174, v1
	v_rcp_f32_e32 v214, v214
	v_rcp_f32_e32 v216, v216
	v_rcp_f32_e32 v217, v217
	v_pk_mul_f32 v[172:173], v[172:173], v[218:219]
	v_cvt_f32_ubyte0_e32 v1, v178
	v_pk_mul_f32 v[174:175], v[208:209], v[174:175]
	v_pk_mul_f32 v[62:63], v[62:63], v[172:173]
	v_max_f32_e32 v172, 0.5, v1
	v_cvt_f32_ubyte1_e32 v1, v178
	v_pk_mul_f32 v[64:65], v[64:65], v[174:175]
	v_pk_mul_f32 v[174:175], v[212:213], v[214:215]
	v_max_f32_e32 v173, 0.5, v1
	v_cvt_f32_ubyte2_e32 v1, v178
	v_pk_mul_f32 v[60:61], v[60:61], v[174:175]
	v_max_f32_e32 v174, 0.5, v1
	v_cvt_f32_ubyte3_e32 v1, v178
	v_pk_mul_f32 v[208:209], v[210:211], v[216:217]
	v_max_f32_e32 v175, 0.5, v1
	v_cvt_f32_ubyte0_e32 v1, v179
	v_pk_mul_f32 v[66:67], v[66:67], v[208:209]
	v_max_f32_e32 v208, 0.5, v1
	v_cvt_f32_ubyte1_e32 v1, v179
	v_max_f32_e32 v209, 0.5, v1
	v_cvt_f32_ubyte2_e32 v1, v179
	v_max_f32_e32 v178, 0.5, v1
	v_cvt_f32_ubyte3_e32 v1, v179
	v_cvt_f32_ubyte1_e32 v210, v176
	v_max_f32_e32 v179, 0.5, v1
	v_cvt_f32_ubyte0_e32 v1, v176
	v_max_f32_e32 v211, 0.5, v210
	v_cvt_f32_ubyte2_e32 v210, v176
	v_cvt_f32_ubyte3_e32 v176, v176
	v_lshl_add_u64 v[148:149], v[148:149], 0, s[56:57]
	v_max_f32_e32 v213, 0.5, v176
	v_cvt_f32_ubyte0_e32 v176, v177
	v_lshl_add_u64 v[2:3], v[148:149], 0, v[2:3]
	v_max_f32_e32 v212, 0.5, v210
	v_max_f32_e32 v210, 0.5, v176
	v_cvt_f32_ubyte1_e32 v176, v177
	v_lshl_add_u64 v[148:149], v[2:3], 0, s[64:65]
	v_add_co_u32_e32 v2, vcc, s12, v2
	v_max_f32_e32 v214, 0.5, v176
	v_cvt_f32_ubyte2_e32 v176, v177
	v_addc_co_u32_e32 v3, vcc, 0, v3, vcc
	v_max_f32_e32 v1, 0.5, v1
	v_max_f32_e32 v215, 0.5, v176
	v_cvt_f32_ubyte3_e32 v176, v177
	global_load_dwordx2 v[152:153], v[2:3], off
	global_load_dwordx2 v[150:151], v[148:149], off offset:2048
	s_nop 0
	global_load_dwordx2 v[2:3], v[148:149], off offset:3072
	s_nop 0
	global_load_dwordx2 v[148:149], v[148:149], off offset:1024
	v_max_f32_e32 v216, 0.5, v176
	v_rcp_f32_e32 v176, v1
	v_rcp_f32_e32 v177, v211
	v_rcp_f32_e32 v210, v210
	v_rcp_f32_e32 v211, v214
	v_rcp_f32_e32 v212, v212
	v_rcp_f32_e32 v213, v213
	v_rcp_f32_e32 v214, v215
	v_rcp_f32_e32 v215, v216
	v_pk_mul_f32 v[172:173], v[172:173], v[176:177]
	v_cvt_f32_ubyte0_e32 v1, v184
	v_pk_mul_f32 v[56:57], v[56:57], v[172:173]
	v_pk_mul_f32 v[172:173], v[208:209], v[210:211]
	v_pk_mul_f32 v[174:175], v[174:175], v[212:213]
	v_pk_mul_f32 v[52:53], v[52:53], v[172:173]
	v_max_f32_e32 v172, 0.5, v1
	v_cvt_f32_ubyte1_e32 v1, v184
	v_pk_mul_f32 v[58:59], v[58:59], v[174:175]
	v_pk_mul_f32 v[174:175], v[178:179], v[214:215]
	v_max_f32_e32 v173, 0.5, v1
	v_cvt_f32_ubyte2_e32 v1, v184
	v_pk_mul_f32 v[54:55], v[54:55], v[174:175]
	v_max_f32_e32 v174, 0.5, v1
	v_cvt_f32_ubyte3_e32 v1, v184
	v_max_f32_e32 v175, 0.5, v1
	v_cvt_f32_ubyte0_e32 v1, v185
	v_max_f32_e32 v176, 0.5, v1
	v_cvt_f32_ubyte1_e32 v1, v185
	v_max_f32_e32 v177, 0.5, v1
	v_cvt_f32_ubyte2_e32 v1, v185
	v_cvt_f32_ubyte1_e32 v184, v186
	v_max_f32_e32 v178, 0.5, v1
	v_cvt_f32_ubyte3_e32 v1, v185
	v_max_f32_e32 v185, 0.5, v184
	v_cvt_f32_ubyte2_e32 v184, v186
	v_max_f32_e32 v208, 0.5, v184
	v_cvt_f32_ubyte3_e32 v184, v186
	v_max_f32_e32 v209, 0.5, v184
	v_cvt_f32_ubyte0_e32 v184, v187
	v_max_f32_e32 v179, 0.5, v1
	v_cvt_f32_ubyte0_e32 v1, v186
	v_max_f32_e32 v186, 0.5, v184
	v_cvt_f32_ubyte1_e32 v184, v187
	v_max_f32_e32 v210, 0.5, v184
	v_cvt_f32_ubyte2_e32 v184, v187
	v_max_f32_e32 v1, 0.5, v1
	v_max_f32_e32 v211, 0.5, v184
	v_cvt_f32_ubyte3_e32 v184, v187
	v_max_f32_e32 v212, 0.5, v184
	v_rcp_f32_e32 v184, v1
	v_rcp_f32_e32 v185, v185
	v_rcp_f32_e32 v186, v186
	v_rcp_f32_e32 v187, v210
	v_rcp_f32_e32 v208, v208
	v_rcp_f32_e32 v209, v209
	v_rcp_f32_e32 v210, v211
	v_rcp_f32_e32 v211, v212
	v_pk_mul_f32 v[172:173], v[172:173], v[184:185]
	v_cvt_f32_ubyte0_e32 v1, v170
	v_pk_mul_f32 v[48:49], v[48:49], v[172:173]
	v_pk_mul_f32 v[172:173], v[176:177], v[186:187]
	v_pk_mul_f32 v[174:175], v[174:175], v[208:209]
	v_pk_mul_f32 v[44:45], v[44:45], v[172:173]
	v_max_f32_e32 v172, 0.5, v1
	v_cvt_f32_ubyte1_e32 v1, v170
	v_pk_mul_f32 v[50:51], v[50:51], v[174:175]
	v_pk_mul_f32 v[174:175], v[178:179], v[210:211]
	v_max_f32_e32 v173, 0.5, v1
	v_cvt_f32_ubyte2_e32 v1, v170
	v_pk_mul_f32 v[46:47], v[46:47], v[174:175]
	v_max_f32_e32 v174, 0.5, v1
	v_cvt_f32_ubyte3_e32 v1, v170
	v_max_f32_e32 v175, 0.5, v1
	v_cvt_f32_ubyte0_e32 v1, v171
	v_max_f32_e32 v176, 0.5, v1
	v_cvt_f32_ubyte1_e32 v1, v171
	v_max_f32_e32 v177, 0.5, v1
	v_cvt_f32_ubyte2_e32 v1, v171
	v_max_f32_e32 v170, 0.5, v1
	v_cvt_f32_ubyte3_e32 v1, v171
	v_cvt_f32_ubyte1_e32 v178, v168
; __device__ __forceinline__ f32x4 un_unorm8(unsigned w) { return (f32x4){fmaxf((float)(w & 255u), 0.5f), fmaxf((float)((w >> 8) & 255u), 0.5f), fmaxf((float)((w >> 16) & 255u), 0.5f), fmaxf((float)(w >> 24), 0.5f)}; }
; #define EPI_OPAQUE asm volatile("" : "+v"(fr), "+v"(fq));
;     __device__ __forceinline__ void seam(f32x4 (&acc)[2][2][4][2], const Unit& u, int n, int wr, int wc, int fr, int fq) const {
;         EPI_OPAQUE
; #pragma unroll
;         for (int ai = 0; ai < 2; ++ai) {
;             u32x2 ga[4][2], gb[4][2];
; #pragma unroll
;             for (int m = 0; m < 4; ++m)
; #pragma unroll
;                 for (int bj = 0; bj < 2; ++bj) { const int row = u.pm * 256 + ai * 128 + wr * 64 + m * 16 + fr, col = u.pn * 256 + bj * 128 + wc * 32 + 8 * fq;
;                     const unsigned char* gp = (const unsigned char*)P + (size_t)row * ROWB + GATE_B0 + n * DM + col; ga[m][bj] = *(const u32x2*)gp; gb[m][bj] = *(const u32x2*)(gp + DM); }
; #pragma unroll
;             for (int m = 0; m < 4; ++m)
; #pragma unroll
;                 for (int bj = 0; bj < 2; ++bj) { const f32x4 a0 = un_unorm8(ga[m][bj].x), a1 = un_unorm8(ga[m][bj].y), b0 = un_unorm8(gb[m][bj].x), b1 = un_unorm8(gb[m][bj].y);
; #pragma unroll
;                     for (int j = 0; j < 4; ++j) { acc[ai][bj][m][0][j] *= a0[j] * __builtin_amdgcn_rcpf(b0[j]); acc[ai][bj][m][1][j] *= a1[j] * __builtin_amdgcn_rcpf(b1[j]); } }
;             asm volatile("" ::: "memory");
;         }
;     }
	v_max_f32_e32 v171, 0.5, v1
	v_cvt_f32_ubyte0_e32 v1, v168
	v_max_f32_e32 v179, 0.5, v178
	v_cvt_f32_ubyte2_e32 v178, v168
	v_cvt_f32_ubyte3_e32 v168, v168
	v_max_f32_e32 v185, 0.5, v168
	v_cvt_f32_ubyte0_e32 v168, v169
	v_max_f32_e32 v184, 0.5, v178
	v_max_f32_e32 v178, 0.5, v168
	v_cvt_f32_ubyte1_e32 v168, v169
	v_max_f32_e32 v186, 0.5, v168
	v_cvt_f32_ubyte2_e32 v168, v169
	v_max_f32_e32 v1, 0.5, v1
	v_max_f32_e32 v187, 0.5, v168
	v_cvt_f32_ubyte3_e32 v168, v169
	v_max_f32_e32 v208, 0.5, v168
	v_rcp_f32_e32 v168, v1
	v_rcp_f32_e32 v169, v179
	v_rcp_f32_e32 v178, v178
	v_rcp_f32_e32 v179, v186
	v_rcp_f32_e32 v186, v187
	v_rcp_f32_e32 v187, v208
	v_pk_mul_f32 v[168:169], v[172:173], v[168:169]
	v_rcp_f32_e32 v184, v184
	v_rcp_f32_e32 v185, v185
	v_pk_mul_f32 v[40:41], v[40:41], v[168:169]
	v_pk_mul_f32 v[168:169], v[176:177], v[178:179]
	v_cvt_f32_ubyte0_e32 v1, v160
	v_pk_mul_f32 v[36:37], v[36:37], v[168:169]
	v_max_f32_e32 v168, 0.5, v1
	v_cvt_f32_ubyte1_e32 v1, v160
	v_pk_mul_f32 v[170:171], v[170:171], v[186:187]
	v_max_f32_e32 v169, 0.5, v1
	v_cvt_f32_ubyte2_e32 v1, v160
	v_pk_mul_f32 v[38:39], v[38:39], v[170:171]
	v_max_f32_e32 v170, 0.5, v1
	v_cvt_f32_ubyte3_e32 v1, v160
	v_pk_mul_f32 v[172:173], v[174:175], v[184:185]
	v_max_f32_e32 v171, 0.5, v1
	v_cvt_f32_ubyte0_e32 v1, v161
	v_pk_mul_f32 v[42:43], v[42:43], v[172:173]
	v_max_f32_e32 v172, 0.5, v1
	v_cvt_f32_ubyte1_e32 v1, v161
	v_max_f32_e32 v173, 0.5, v1
	v_cvt_f32_ubyte2_e32 v1, v161
	v_max_f32_e32 v160, 0.5, v1
	v_cvt_f32_ubyte3_e32 v1, v161
	v_cvt_f32_ubyte1_e32 v174, v158
	v_max_f32_e32 v161, 0.5, v1
	v_cvt_f32_ubyte0_e32 v1, v158
	v_max_f32_e32 v175, 0.5, v174
	v_cvt_f32_ubyte2_e32 v174, v158
	v_cvt_f32_ubyte3_e32 v158, v158
	v_max_f32_e32 v177, 0.5, v158
	v_cvt_f32_ubyte0_e32 v158, v159
	v_max_f32_e32 v176, 0.5, v174
	v_max_f32_e32 v174, 0.5, v158
	v_cvt_f32_ubyte1_e32 v158, v159
	v_max_f32_e32 v178, 0.5, v158
	v_cvt_f32_ubyte2_e32 v158, v159
	v_max_f32_e32 v1, 0.5, v1
	v_max_f32_e32 v179, 0.5, v158
	v_cvt_f32_ubyte3_e32 v158, v159
	v_max_f32_e32 v184, 0.5, v158
	v_rcp_f32_e32 v158, v1
	v_rcp_f32_e32 v159, v175
	v_rcp_f32_e32 v174, v174
	v_rcp_f32_e32 v175, v178
	v_rcp_f32_e32 v178, v179
	v_rcp_f32_e32 v179, v184
	v_pk_mul_f32 v[158:159], v[168:169], v[158:159]
	v_rcp_f32_e32 v176, v176
	v_rcp_f32_e32 v177, v177
	v_pk_mul_f32 v[32:33], v[32:33], v[158:159]
	v_pk_mul_f32 v[158:159], v[172:173], v[174:175]
	v_cvt_f32_ubyte0_e32 v1, v156
	v_pk_mul_f32 v[28:29], v[28:29], v[158:159]
	v_max_f32_e32 v158, 0.5, v1
	v_cvt_f32_ubyte1_e32 v1, v156
	v_pk_mul_f32 v[160:161], v[160:161], v[178:179]
	v_max_f32_e32 v159, 0.5, v1
	v_cvt_f32_ubyte2_e32 v1, v156
	v_pk_mul_f32 v[30:31], v[30:31], v[160:161]
	v_max_f32_e32 v160, 0.5, v1
	v_cvt_f32_ubyte3_e32 v1, v156
	v_pk_mul_f32 v[168:169], v[170:171], v[176:177]
	v_max_f32_e32 v161, 0.5, v1
	v_cvt_f32_ubyte0_e32 v1, v157
	v_pk_mul_f32 v[34:35], v[34:35], v[168:169]
	v_max_f32_e32 v168, 0.5, v1
	v_cvt_f32_ubyte1_e32 v1, v157
	v_max_f32_e32 v169, 0.5, v1
	v_cvt_f32_ubyte2_e32 v1, v157
	v_max_f32_e32 v156, 0.5, v1
	v_cvt_f32_ubyte3_e32 v1, v157
	v_cvt_f32_ubyte1_e32 v170, v154
	v_max_f32_e32 v157, 0.5, v1
	v_cvt_f32_ubyte0_e32 v1, v154
	v_max_f32_e32 v171, 0.5, v170
	v_cvt_f32_ubyte2_e32 v170, v154
	v_cvt_f32_ubyte3_e32 v154, v154
	v_max_f32_e32 v173, 0.5, v154
	v_cvt_f32_ubyte0_e32 v154, v155
	v_max_f32_e32 v172, 0.5, v170
	v_max_f32_e32 v170, 0.5, v154
	v_cvt_f32_ubyte1_e32 v154, v155
	v_max_f32_e32 v174, 0.5, v154
	v_cvt_f32_ubyte2_e32 v154, v155
	v_max_f32_e32 v1, 0.5, v1
	v_max_f32_e32 v175, 0.5, v154
	v_cvt_f32_ubyte3_e32 v154, v155
	v_max_f32_e32 v176, 0.5, v154
	v_rcp_f32_e32 v154, v1
	v_rcp_f32_e32 v155, v171
	v_rcp_f32_e32 v170, v170
	v_rcp_f32_e32 v171, v174
	v_rcp_f32_e32 v174, v175
	v_rcp_f32_e32 v175, v176
	v_pk_mul_f32 v[154:155], v[158:159], v[154:155]
	v_rcp_f32_e32 v172, v172
	v_rcp_f32_e32 v173, v173
	v_pk_mul_f32 v[24:25], v[24:25], v[154:155]
	v_pk_mul_f32 v[154:155], v[168:169], v[170:171]
	s_waitcnt vmcnt(0)
; __device__ __forceinline__ f32x4 un_unorm8(unsigned w) { return (f32x4){fmaxf((float)(w & 255u), 0.5f), fmaxf((float)((w >> 8) & 255u), 0.5f), fmaxf((float)((w >> 16) & 255u), 0.5f), fmaxf((float)(w >> 24), 0.5f)}; }
; #define EPI_OPAQUE asm volatile("" : "+v"(fr), "+v"(fq));
;     __device__ __forceinline__ void seam(f32x4 (&acc)[2][2][4][2], const Unit& u, int n, int wr, int wc, int fr, int fq) const {
;         EPI_OPAQUE
; #pragma unroll
;         for (int ai = 0; ai < 2; ++ai) {
;             u32x2 ga[4][2], gb[4][2];
; #pragma unroll
;             for (int m = 0; m < 4; ++m)
; #pragma unroll
;                 for (int bj = 0; bj < 2; ++bj) { const int row = u.pm * 256 + ai * 128 + wr * 64 + m * 16 + fr, col = u.pn * 256 + bj * 128 + wc * 32 + 8 * fq;
;                     const unsigned char* gp = (const unsigned char*)P + (size_t)row * ROWB + GATE_B0 + n * DM + col; ga[m][bj] = *(const u32x2*)gp; gb[m][bj] = *(const u32x2*)(gp + DM); }
; #pragma unroll
;             for (int m = 0; m < 4; ++m)
; #pragma unroll
;                 for (int bj = 0; bj < 2; ++bj) { const f32x4 a0 = un_unorm8(ga[m][bj].x), a1 = un_unorm8(ga[m][bj].y), b0 = un_unorm8(gb[m][bj].x), b1 = un_unorm8(gb[m][bj].y);
; #pragma unroll
;                     for (int j = 0; j < 4; ++j) { acc[ai][bj][m][0][j] *= a0[j] * __builtin_amdgcn_rcpf(b0[j]); acc[ai][bj][m][1][j] *= a1[j] * __builtin_amdgcn_rcpf(b1[j]); } }
;             asm volatile("" ::: "memory");
;         }
;     }
	v_cvt_f32_ubyte0_e32 v1, v152
	v_pk_mul_f32 v[20:21], v[20:21], v[154:155]
	v_max_f32_e32 v154, 0.5, v1
	v_cvt_f32_ubyte1_e32 v1, v152
	v_pk_mul_f32 v[156:157], v[156:157], v[174:175]
	v_max_f32_e32 v155, 0.5, v1
	v_cvt_f32_ubyte2_e32 v1, v152
	v_pk_mul_f32 v[22:23], v[22:23], v[156:157]
	v_max_f32_e32 v156, 0.5, v1
	v_cvt_f32_ubyte3_e32 v1, v152
	v_pk_mul_f32 v[158:159], v[160:161], v[172:173]
	v_max_f32_e32 v157, 0.5, v1
	v_cvt_f32_ubyte0_e32 v1, v153
	v_pk_mul_f32 v[26:27], v[26:27], v[158:159]
	v_max_f32_e32 v158, 0.5, v1
	v_cvt_f32_ubyte1_e32 v1, v153
	v_max_f32_e32 v159, 0.5, v1
	v_cvt_f32_ubyte2_e32 v1, v153
	v_max_f32_e32 v152, 0.5, v1
	v_cvt_f32_ubyte3_e32 v1, v153
	v_cvt_f32_ubyte1_e32 v160, v150
	v_max_f32_e32 v153, 0.5, v1
	v_cvt_f32_ubyte0_e32 v1, v150
	v_max_f32_e32 v161, 0.5, v160
	v_cvt_f32_ubyte2_e32 v160, v150
	v_cvt_f32_ubyte3_e32 v150, v150
	v_max_f32_e32 v169, 0.5, v150
	v_cvt_f32_ubyte0_e32 v150, v151
	v_max_f32_e32 v168, 0.5, v160
	v_max_f32_e32 v160, 0.5, v150
	v_cvt_f32_ubyte1_e32 v150, v151
	v_max_f32_e32 v170, 0.5, v150
	v_cvt_f32_ubyte2_e32 v150, v151
	v_max_f32_e32 v1, 0.5, v1
	v_max_f32_e32 v171, 0.5, v150
	v_cvt_f32_ubyte3_e32 v150, v151
	v_max_f32_e32 v172, 0.5, v150
	v_rcp_f32_e32 v150, v1
	v_rcp_f32_e32 v151, v161
	v_rcp_f32_e32 v160, v160
	v_rcp_f32_e32 v161, v170
	v_rcp_f32_e32 v170, v171
	v_rcp_f32_e32 v171, v172
	v_pk_mul_f32 v[150:151], v[154:155], v[150:151]
	v_rcp_f32_e32 v168, v168
	v_rcp_f32_e32 v169, v169
	v_pk_mul_f32 v[16:17], v[16:17], v[150:151]
	v_pk_mul_f32 v[150:151], v[158:159], v[160:161]
	v_cvt_f32_ubyte0_e32 v1, v148
	v_pk_mul_f32 v[12:13], v[12:13], v[150:151]
	v_max_f32_e32 v150, 0.5, v1
	v_cvt_f32_ubyte1_e32 v1, v148
	v_pk_mul_f32 v[152:153], v[152:153], v[170:171]
	v_max_f32_e32 v151, 0.5, v1
	v_cvt_f32_ubyte2_e32 v1, v148
	v_pk_mul_f32 v[14:15], v[14:15], v[152:153]
	v_max_f32_e32 v152, 0.5, v1
	v_cvt_f32_ubyte3_e32 v1, v148
	v_pk_mul_f32 v[154:155], v[156:157], v[168:169]
	v_max_f32_e32 v153, 0.5, v1
	v_cvt_f32_ubyte0_e32 v1, v149
	v_pk_mul_f32 v[18:19], v[18:19], v[154:155]
	v_max_f32_e32 v154, 0.5, v1
	v_cvt_f32_ubyte1_e32 v1, v149
	v_max_f32_e32 v155, 0.5, v1
	v_cvt_f32_ubyte2_e32 v1, v149
	v_max_f32_e32 v148, 0.5, v1
	v_cvt_f32_ubyte3_e32 v1, v149
	v_cvt_f32_ubyte1_e32 v156, v2
	v_max_f32_e32 v149, 0.5, v1
	v_cvt_f32_ubyte0_e32 v1, v2
	v_max_f32_e32 v157, 0.5, v156
	v_cvt_f32_ubyte2_e32 v156, v2
	v_cvt_f32_ubyte3_e32 v2, v2
	v_max_f32_e32 v159, 0.5, v2
	v_cvt_f32_ubyte0_e32 v2, v3
	v_max_f32_e32 v158, 0.5, v156
	v_max_f32_e32 v156, 0.5, v2
	v_cvt_f32_ubyte1_e32 v2, v3
	v_max_f32_e32 v160, 0.5, v2
	v_cvt_f32_ubyte2_e32 v2, v3
	v_max_f32_e32 v1, 0.5, v1
	v_max_f32_e32 v161, 0.5, v2
	v_cvt_f32_ubyte3_e32 v2, v3
	v_max_f32_e32 v168, 0.5, v2
	v_rcp_f32_e32 v2, v1
	v_rcp_f32_e32 v3, v157
	v_rcp_f32_e32 v156, v156
	v_rcp_f32_e32 v158, v158
	v_rcp_f32_e32 v159, v159
	v_rcp_f32_e32 v157, v160
	v_rcp_f32_e32 v160, v161
	v_rcp_f32_e32 v161, v168
	v_pk_mul_f32 v[2:3], v[150:151], v[2:3]
	v_pk_mul_f32 v[150:151], v[152:153], v[158:159]
	v_pk_mul_f32 v[8:9], v[8:9], v[2:3]
	v_pk_mul_f32 v[2:3], v[154:155], v[156:157]
	v_pk_mul_f32 v[148:149], v[148:149], v[160:161]
	v_pk_mul_f32 v[10:11], v[10:11], v[150:151]
	v_pk_mul_f32 v[6:7], v[6:7], v[148:149]
	v_pk_mul_f32 v[4:5], v[4:5], v[2:3]
	s_andn2_b64 vcc, exec, s[44:45]
	s_cbranch_vccnz .Lsm_b
	s_barrier

; __device__ __forceinline__ u32x4 pack8(f32x4 a, f32x4 b) { u32x4 w; w.x = cvt_pk_bf16(a[0], a[1]); w.y = cvt_pk_bf16(a[2], a[3]); w.z = cvt_pk_bf16(b[0], b[1]); w.w = cvt_pk_bf16(b[2], b[3]); return w; }
; __device__ __forceinline__ f32x4 un_unorm8(unsigned w) { return (f32x4){fmaxf((float)(w & 255u), 0.5f), fmaxf((float)((w >> 8) & 255u), 0.5f), fmaxf((float)((w >> 16) & 255u), 0.5f), fmaxf((float)(w >> 24), 0.5f)}; }
; #define EPI_OPAQUE asm volatile("" : "+v"(fr), "+v"(fq));
;     __device__ __forceinline__ void operator()(f32x4 (&acc)[2][2][4][2], const Unit& u, int wr, int wc, int fr, int fq) const {
;         EPI_OPAQUE
; #pragma unroll
;         for (int ai = 0; ai < 2; ++ai) {
;             u32x2 gg[4][2];
; #pragma unroll
;             for (int m = 0; m < 4; ++m)
; #pragma unroll
;                 for (int bj = 0; bj < 2; ++bj) { const int row = u.pm * 256 + ai * 128 + wr * 64 + m * 16 + fr, col = u.pn * 256 + bj * 128 + wc * 32 + 8 * fq;
;                     gg[m][bj] = *(const u32x2*)((const unsigned char*)P + (size_t)row * ROWB + GATE_B0 + 2 * DM + col); }
;             asm volatile("" ::: "memory");
; #pragma unroll
;             for (int m = 0; m < 4; ++m)
; #pragma unroll
;                 for (int bj = 0; bj < 2; ++bj) { const int row = u.pm * 256 + ai * 128 + wr * 64 + m * 16 + fr, col = u.pn * 256 + bj * 128 + wc * 32 + 8 * fq;
;                     const f32x4 g0 = un_unorm8(gg[m][bj].x) * (1.0f / 255.0f), g1 = un_unorm8(gg[m][bj].y) * (1.0f / 255.0f);
;                     *(u32x4*)(MG + (size_t)row * DM + col) = pack8(acc[ai][bj][m][0] * g0, acc[ai][bj][m][1] * g1); }
;             asm volatile("" ::: "memory");
;         }
;     }
.LBB0_623:
	v_mov_b32_e32 v1, v181
	v_mov_b32_e32 v2, v180
	s_add_i32 s8, s8, s20
	v_mov_b64_e32 v[150:151], s[68:69]
	s_lshr_b32 s98, s42, 7
	s_bfe_u32 s99, s42, 0x10006
	s_or_b32 s98, s98, s99
	v_sub_u32_e32 v245, s98, v180
	s_and_b32 s99, s42, 32
	s_lshl_b32 s99, s99, 4
	v_lshl_add_u32 v246, v181, 7, s99
	v_lshl_add_u32 v246, v180, 3, v246
	v_mad_i32_i24 v246, v245, s33, v246
	v_ashrrev_i32_e32 v247, 31, v246
	v_add_u32_e32 v146, s8, v2
	v_lshl_add_u32 v144, v1, 3, s42
	v_mad_i64_i32 v[2:3], s[4:5], v146, s33, v[150:151]
	v_ashrrev_i32_e32 v145, 31, v144
	v_lshl_add_u64 v[2:3], v[2:3], 0, s[84:85]
	v_lshl_add_u64 v[148:149], v[2:3], 0, v[246:247]
	global_load_dwordx2 v[178:179], v[148:149], off
	v_add_u32_e32 v148, 0x400, v246
	v_ashrrev_i32_e32 v149, 31, v148
	v_lshl_add_u64 v[2:3], v[2:3], 0, v[148:149]
	global_load_dwordx2 v[176:177], v[2:3], off
	v_add_u32_e32 v174, 16, v146
	v_mad_i64_i32 v[2:3], s[4:5], v174, s33, v[150:151]
	v_lshl_add_u64 v[2:3], v[2:3], 0, s[84:85]
	v_lshl_add_u64 v[152:153], v[2:3], 0, v[246:247]
	global_load_dwordx2 v[172:173], v[152:153], off
	v_lshl_add_u64 v[2:3], v[2:3], 0, v[148:149]
	global_load_dwordx2 v[168:169], v[2:3], off
	v_add_u32_e32 v170, 32, v146
	v_mad_i64_i32 v[2:3], s[4:5], v170, s33, v[150:151]
	v_lshl_add_u64 v[2:3], v[2:3], 0, s[84:85]
	v_lshl_add_u64 v[152:153], v[2:3], 0, v[246:247]
	global_load_dwordx2 v[160:161], v[152:153], off
	v_lshl_add_u64 v[2:3], v[2:3], 0, v[148:149]
	global_load_dwordx2 v[154:155], v[2:3], off
	v_add_u32_e32 v156, 48, v146
	v_mad_i64_i32 v[2:3], s[4:5], v156, s33, v[150:151]
	v_lshl_add_u64 v[2:3], v[2:3], 0, s[84:85]
	v_lshl_add_u64 v[152:153], v[2:3], 0, v[246:247]
	global_load_dwordx2 v[158:159], v[152:153], off
	v_lshl_add_u64 v[2:3], v[2:3], 0, v[148:149]
	global_load_dwordx2 v[152:153], v[2:3], off
	v_ashrrev_i32_e32 v147, 31, v146
	v_lshlrev_b64 v[2:3], 12, v[146:147]
	v_ashrrev_i32_e32 v175, 31, v174
	v_ashrrev_i32_e32 v171, 31, v170
	v_ashrrev_i32_e32 v157, 31, v156
	s_and_b64 vcc, exec, s[40:41]
	s_waitcnt vmcnt(0)
	v_cvt_f32_ubyte0_e32 v1, v178
	v_max_f32_e32 v184, 0.5, v1
	v_cvt_f32_ubyte1_e32 v1, v178
	v_max_f32_e32 v185, 0.5, v1
	v_cvt_f32_ubyte2_e32 v1, v178
	v_max_f32_e32 v186, 0.5, v1
	v_cvt_f32_ubyte3_e32 v1, v178
	v_max_f32_e32 v187, 0.5, v1
	v_cvt_f32_ubyte0_e32 v1, v179
	v_max_f32_e32 v208, 0.5, v1
	v_cvt_f32_ubyte1_e32 v1, v179
	v_max_f32_e32 v209, 0.5, v1
	v_cvt_f32_ubyte2_e32 v1, v179
	v_max_f32_e32 v178, 0.5, v1
	v_cvt_f32_ubyte3_e32 v1, v179
	v_pk_mul_f32 v[184:185], v[184:185], s[86:87] op_sel_hi:[1,0]
	v_max_f32_e32 v179, 0.5, v1
	v_pk_mul_f32 v[186:187], v[186:187], s[86:87] op_sel_hi:[1,0]
	v_pk_mul_f32 v[208:209], v[208:209], s[86:87] op_sel_hi:[1,0]
	v_pk_mul_f32 v[178:179], v[178:179], s[86:87] op_sel_hi:[1,0]
	v_pk_mul_f32 v[128:129], v[128:129], v[184:185]
	v_pk_mul_f32 v[130:131], v[130:131], v[186:187]
	v_pk_mul_f32 v[178:179], v[126:127], v[178:179]
	v_pk_mul_f32 v[126:127], v[124:125], v[208:209]
	v_cvt_pk_bf16_f32 v124, v128, v129
	v_lshl_add_u64 v[128:129], s[72:73], 0, v[2:3]
	v_lshlrev_b64 v[2:3], 1, v[144:145]
	v_cvt_pk_bf16_f32 v125, v130, v131
	v_cvt_pk_bf16_f32 v126, v126, v127
	v_cvt_pk_bf16_f32 v127, v178, v179
	v_lshl_add_u64 v[128:129], v[128:129], 0, v[2:3]
	v_cvt_f32_ubyte0_e32 v1, v176
	global_store_dwordx4 v[128:129], v[124:127], off
	s_nop 1
	v_max_f32_e32 v124, 0.5, v1
	v_cvt_f32_ubyte1_e32 v1, v176
	v_max_f32_e32 v125, 0.5, v1
	v_cvt_f32_ubyte2_e32 v1, v176
	v_max_f32_e32 v126, 0.5, v1
	v_cvt_f32_ubyte3_e32 v1, v176
	v_max_f32_e32 v127, 0.5, v1
	v_cvt_f32_ubyte0_e32 v1, v177
	v_max_f32_e32 v130, 0.5, v1
	v_cvt_f32_ubyte1_e32 v1, v177
	v_max_f32_e32 v131, 0.5, v1
	v_cvt_f32_ubyte2_e32 v1, v177
	v_max_f32_e32 v176, 0.5, v1
	v_cvt_f32_ubyte3_e32 v1, v177
	v_max_f32_e32 v177, 0.5, v1
	v_pk_mul_f32 v[124:125], v[124:125], s[86:87] op_sel_hi:[1,0]
	v_pk_mul_f32 v[126:127], v[126:127], s[86:87] op_sel_hi:[1,0]
	v_pk_mul_f32 v[130:131], v[130:131], s[86:87] op_sel_hi:[1,0]
	v_pk_mul_f32 v[176:177], v[176:177], s[86:87] op_sel_hi:[1,0]
	v_pk_mul_f32 v[122:123], v[122:123], v[126:127]
	v_pk_mul_f32 v[120:121], v[120:121], v[124:125]
	v_pk_mul_f32 v[124:125], v[118:119], v[176:177]
	v_pk_mul_f32 v[118:119], v[116:117], v[130:131]
	v_cvt_pk_bf16_f32 v116, v120, v121
	v_cvt_pk_bf16_f32 v117, v122, v123
	v_cvt_pk_bf16_f32 v118, v118, v119
	v_cvt_pk_bf16_f32 v119, v124, v125
	v_cvt_f32_ubyte0_e32 v1, v172
	global_store_dwordx4 v[128:129], v[116:119], off offset:256
	s_nop 1
	v_max_f32_e32 v118, 0.5, v1
	v_cvt_f32_ubyte1_e32 v1, v172
	v_max_f32_e32 v119, 0.5, v1
	v_cvt_f32_ubyte2_e32 v1, v172
	v_max_f32_e32 v120, 0.5, v1
	v_cvt_f32_ubyte3_e32 v1, v172
	v_max_f32_e32 v121, 0.5, v1
	v_cvt_f32_ubyte0_e32 v1, v173
	v_max_f32_e32 v122, 0.5, v1
	v_cvt_f32_ubyte1_e32 v1, v173
	v_max_f32_e32 v123, 0.5, v1
	v_cvt_f32_ubyte2_e32 v1, v173
	v_max_f32_e32 v124, 0.5, v1
	v_cvt_f32_ubyte3_e32 v1, v173
	v_pk_mul_f32 v[118:119], v[118:119], s[86:87] op_sel_hi:[1,0]
	v_max_f32_e32 v125, 0.5, v1
	v_lshlrev_b64 v[116:117], 12, v[174:175]
	v_pk_mul_f32 v[120:121], v[120:121], s[86:87] op_sel_hi:[1,0]
	v_pk_mul_f32 v[122:123], v[122:123], s[86:87] op_sel_hi:[1,0]
	v_pk_mul_f32 v[124:125], v[124:125], s[86:87] op_sel_hi:[1,0]
	v_pk_mul_f32 v[112:113], v[112:113], v[118:119]
	v_pk_mul_f32 v[114:115], v[114:115], v[120:121]
	v_pk_mul_f32 v[118:119], v[110:111], v[124:125]
	v_pk_mul_f32 v[110:111], v[108:109], v[122:123]
	v_cvt_pk_bf16_f32 v108, v112, v113
	v_lshl_add_u64 v[112:113], s[72:73], 0, v[116:117]
	v_cvt_pk_bf16_f32 v109, v114, v115
	v_cvt_pk_bf16_f32 v110, v110, v111
	v_cvt_pk_bf16_f32 v111, v118, v119
; __device__ __forceinline__ u32x4 pack8(f32x4 a, f32x4 b) { u32x4 w; w.x = cvt_pk_bf16(a[0], a[1]); w.y = cvt_pk_bf16(a[2], a[3]); w.z = cvt_pk_bf16(b[0], b[1]); w.w = cvt_pk_bf16(b[2], b[3]); return w; }
; __device__ __forceinline__ f32x4 un_unorm8(unsigned w) { return (f32x4){fmaxf((float)(w & 255u), 0.5f), fmaxf((float)((w >> 8) & 255u), 0.5f), fmaxf((float)((w >> 16) & 255u), 0.5f), fmaxf((float)(w >> 24), 0.5f)}; }
; #define EPI_OPAQUE asm volatile("" : "+v"(fr), "+v"(fq));
;     __device__ __forceinline__ void operator()(f32x4 (&acc)[2][2][4][2], const Unit& u, int wr, int wc, int fr, int fq) const {
;         EPI_OPAQUE
; #pragma unroll
;         for (int ai = 0; ai < 2; ++ai) {
;             u32x2 gg[4][2];
; #pragma unroll
;             for (int m = 0; m < 4; ++m)
; #pragma unroll
;                 for (int bj = 0; bj < 2; ++bj) { const int row = u.pm * 256 + ai * 128 + wr * 64 + m * 16 + fr, col = u.pn * 256 + bj * 128 + wc * 32 + 8 * fq;
;                     gg[m][bj] = *(const u32x2*)((const unsigned char*)P + (size_t)row * ROWB + GATE_B0 + 2 * DM + col); }
;             asm volatile("" ::: "memory");
; #pragma unroll
;             for (int m = 0; m < 4; ++m)
; #pragma unroll
;                 for (int bj = 0; bj < 2; ++bj) { const int row = u.pm * 256 + ai * 128 + wr * 64 + m * 16 + fr, col = u.pn * 256 + bj * 128 + wc * 32 + 8 * fq;
;                     const f32x4 g0 = un_unorm8(gg[m][bj].x) * (1.0f / 255.0f), g1 = un_unorm8(gg[m][bj].y) * (1.0f / 255.0f);
;                     *(u32x4*)(MG + (size_t)row * DM + col) = pack8(acc[ai][bj][m][0] * g0, acc[ai][bj][m][1] * g1); }
;             asm volatile("" ::: "memory");
;         }
;     }
	v_lshl_add_u64 v[112:113], v[112:113], 0, v[2:3]
	v_cvt_f32_ubyte0_e32 v1, v168
	global_store_dwordx4 v[112:113], v[108:111], off
	s_nop 1
	v_max_f32_e32 v108, 0.5, v1
	v_cvt_f32_ubyte1_e32 v1, v168
	v_max_f32_e32 v109, 0.5, v1
	v_cvt_f32_ubyte2_e32 v1, v168
	v_max_f32_e32 v110, 0.5, v1
	v_cvt_f32_ubyte3_e32 v1, v168
	v_max_f32_e32 v111, 0.5, v1
	v_cvt_f32_ubyte0_e32 v1, v169
	v_max_f32_e32 v114, 0.5, v1
	v_cvt_f32_ubyte1_e32 v1, v169
	v_max_f32_e32 v115, 0.5, v1
	v_cvt_f32_ubyte2_e32 v1, v169
	v_max_f32_e32 v116, 0.5, v1
	v_cvt_f32_ubyte3_e32 v1, v169
	v_max_f32_e32 v117, 0.5, v1
	v_pk_mul_f32 v[108:109], v[108:109], s[86:87] op_sel_hi:[1,0]
	v_pk_mul_f32 v[110:111], v[110:111], s[86:87] op_sel_hi:[1,0]
	v_pk_mul_f32 v[114:115], v[114:115], s[86:87] op_sel_hi:[1,0]
	v_pk_mul_f32 v[116:117], v[116:117], s[86:87] op_sel_hi:[1,0]
	v_pk_mul_f32 v[106:107], v[106:107], v[110:111]
	v_pk_mul_f32 v[104:105], v[104:105], v[108:109]
	v_pk_mul_f32 v[108:109], v[102:103], v[116:117]
	v_pk_mul_f32 v[102:103], v[100:101], v[114:115]
	v_cvt_pk_bf16_f32 v100, v104, v105
	v_cvt_pk_bf16_f32 v101, v106, v107
	v_cvt_pk_bf16_f32 v102, v102, v103
	v_cvt_pk_bf16_f32 v103, v108, v109
	v_cvt_f32_ubyte0_e32 v1, v160
	global_store_dwordx4 v[112:113], v[100:103], off offset:256
	s_nop 1
	v_max_f32_e32 v102, 0.5, v1
	v_cvt_f32_ubyte1_e32 v1, v160
	v_max_f32_e32 v103, 0.5, v1
	v_cvt_f32_ubyte2_e32 v1, v160
	v_max_f32_e32 v104, 0.5, v1
	v_cvt_f32_ubyte3_e32 v1, v160
	v_max_f32_e32 v105, 0.5, v1
	v_cvt_f32_ubyte0_e32 v1, v161
	v_max_f32_e32 v106, 0.5, v1
	v_cvt_f32_ubyte1_e32 v1, v161
	v_max_f32_e32 v107, 0.5, v1
	v_cvt_f32_ubyte2_e32 v1, v161
	v_max_f32_e32 v108, 0.5, v1
	v_cvt_f32_ubyte3_e32 v1, v161
	v_pk_mul_f32 v[102:103], v[102:103], s[86:87] op_sel_hi:[1,0]
	v_max_f32_e32 v109, 0.5, v1
	v_lshlrev_b64 v[100:101], 12, v[170:171]
	v_pk_mul_f32 v[104:105], v[104:105], s[86:87] op_sel_hi:[1,0]
	v_pk_mul_f32 v[106:107], v[106:107], s[86:87] op_sel_hi:[1,0]
	v_pk_mul_f32 v[108:109], v[108:109], s[86:87] op_sel_hi:[1,0]
	v_pk_mul_f32 v[96:97], v[96:97], v[102:103]
	v_pk_mul_f32 v[98:99], v[98:99], v[104:105]
	v_pk_mul_f32 v[102:103], v[94:95], v[108:109]
	v_pk_mul_f32 v[94:95], v[92:93], v[106:107]
	v_cvt_pk_bf16_f32 v92, v96, v97
	v_lshl_add_u64 v[96:97], s[72:73], 0, v[100:101]
	v_cvt_pk_bf16_f32 v93, v98, v99
	v_cvt_pk_bf16_f32 v94, v94, v95
	v_cvt_pk_bf16_f32 v95, v102, v103
	v_lshl_add_u64 v[96:97], v[96:97], 0, v[2:3]
	v_cvt_f32_ubyte0_e32 v1, v154
	global_store_dwordx4 v[96:97], v[92:95], off
	s_nop 1
	v_max_f32_e32 v92, 0.5, v1
	v_cvt_f32_ubyte1_e32 v1, v154
	v_max_f32_e32 v93, 0.5, v1
	v_cvt_f32_ubyte2_e32 v1, v154
	v_max_f32_e32 v94, 0.5, v1
	v_cvt_f32_ubyte3_e32 v1, v154
	v_max_f32_e32 v95, 0.5, v1
	v_cvt_f32_ubyte0_e32 v1, v155
	v_max_f32_e32 v98, 0.5, v1
	v_cvt_f32_ubyte1_e32 v1, v155
	v_max_f32_e32 v99, 0.5, v1
	v_cvt_f32_ubyte2_e32 v1, v155
	v_max_f32_e32 v100, 0.5, v1
	v_cvt_f32_ubyte3_e32 v1, v155
	v_max_f32_e32 v101, 0.5, v1
	v_pk_mul_f32 v[92:93], v[92:93], s[86:87] op_sel_hi:[1,0]
	v_pk_mul_f32 v[94:95], v[94:95], s[86:87] op_sel_hi:[1,0]
	v_pk_mul_f32 v[98:99], v[98:99], s[86:87] op_sel_hi:[1,0]
	v_pk_mul_f32 v[100:101], v[100:101], s[86:87] op_sel_hi:[1,0]
	v_pk_mul_f32 v[90:91], v[90:91], v[94:95]
	v_pk_mul_f32 v[88:89], v[88:89], v[92:93]
	v_pk_mul_f32 v[92:93], v[86:87], v[100:101]
	v_pk_mul_f32 v[86:87], v[84:85], v[98:99]
	v_cvt_pk_bf16_f32 v84, v88, v89
	v_cvt_pk_bf16_f32 v85, v90, v91
	v_cvt_pk_bf16_f32 v86, v86, v87
	v_cvt_pk_bf16_f32 v87, v92, v93
	v_cvt_f32_ubyte0_e32 v1, v158
	global_store_dwordx4 v[96:97], v[84:87], off offset:256
	s_nop 1
	v_max_f32_e32 v86, 0.5, v1
	v_cvt_f32_ubyte1_e32 v1, v158
	v_max_f32_e32 v87, 0.5, v1
	v_cvt_f32_ubyte2_e32 v1, v158
	v_max_f32_e32 v88, 0.5, v1
	v_cvt_f32_ubyte3_e32 v1, v158
	v_max_f32_e32 v89, 0.5, v1
	v_cvt_f32_ubyte0_e32 v1, v159
	v_max_f32_e32 v90, 0.5, v1
	v_cvt_f32_ubyte1_e32 v1, v159
	v_max_f32_e32 v91, 0.5, v1
	v_cvt_f32_ubyte2_e32 v1, v159
	v_max_f32_e32 v92, 0.5, v1
	v_cvt_f32_ubyte3_e32 v1, v159
	v_pk_mul_f32 v[86:87], v[86:87], s[86:87] op_sel_hi:[1,0]
	v_max_f32_e32 v93, 0.5, v1
	v_lshlrev_b64 v[84:85], 12, v[156:157]
	v_pk_mul_f32 v[88:89], v[88:89], s[86:87] op_sel_hi:[1,0]
	v_pk_mul_f32 v[90:91], v[90:91], s[86:87] op_sel_hi:[1,0]
	v_pk_mul_f32 v[92:93], v[92:93], s[86:87] op_sel_hi:[1,0]
	v_pk_mul_f32 v[80:81], v[80:81], v[86:87]
	v_pk_mul_f32 v[82:83], v[82:83], v[88:89]
	v_pk_mul_f32 v[86:87], v[78:79], v[92:93]
	v_pk_mul_f32 v[78:79], v[76:77], v[90:91]
	v_cvt_pk_bf16_f32 v76, v80, v81
	v_lshl_add_u64 v[80:81], s[72:73], 0, v[84:85]
	v_cvt_pk_bf16_f32 v77, v82, v83
	v_cvt_pk_bf16_f32 v78, v78, v79
	v_cvt_pk_bf16_f32 v79, v86, v87
	v_lshl_add_u64 v[80:81], v[80:81], 0, v[2:3]
	v_cvt_f32_ubyte0_e32 v1, v152
	global_store_dwordx4 v[80:81], v[76:79], off
	v_add_u32_e32 v88, 0xa0, v146
	v_ashrrev_i32_e32 v89, 31, v88
	v_max_f32_e32 v76, 0.5, v1
	v_cvt_f32_ubyte1_e32 v1, v152
	v_max_f32_e32 v77, 0.5, v1
	v_cvt_f32_ubyte2_e32 v1, v152
	v_max_f32_e32 v78, 0.5, v1
	v_cvt_f32_ubyte3_e32 v1, v152
	v_max_f32_e32 v79, 0.5, v1
	v_cvt_f32_ubyte0_e32 v1, v153
	v_max_f32_e32 v82, 0.5, v1
	v_cvt_f32_ubyte1_e32 v1, v153
	v_max_f32_e32 v83, 0.5, v1
	v_cvt_f32_ubyte2_e32 v1, v153
	v_max_f32_e32 v84, 0.5, v1
	v_cvt_f32_ubyte3_e32 v1, v153
	v_max_f32_e32 v85, 0.5, v1
	v_pk_mul_f32 v[76:77], v[76:77], s[86:87] op_sel_hi:[1,0]
	v_pk_mul_f32 v[78:79], v[78:79], s[86:87] op_sel_hi:[1,0]
	v_pk_mul_f32 v[82:83], v[82:83], s[86:87] op_sel_hi:[1,0]
	v_pk_mul_f32 v[84:85], v[84:85], s[86:87] op_sel_hi:[1,0]
	v_pk_mul_f32 v[74:75], v[74:75], v[78:79]
	v_pk_mul_f32 v[72:73], v[72:73], v[76:77]
; __device__ __forceinline__ u32x4 pack8(f32x4 a, f32x4 b) { u32x4 w; w.x = cvt_pk_bf16(a[0], a[1]); w.y = cvt_pk_bf16(a[2], a[3]); w.z = cvt_pk_bf16(b[0], b[1]); w.w = cvt_pk_bf16(b[2], b[3]); return w; }
; __device__ __forceinline__ f32x4 un_unorm8(unsigned w) { return (f32x4){fmaxf((float)(w & 255u), 0.5f), fmaxf((float)((w >> 8) & 255u), 0.5f), fmaxf((float)((w >> 16) & 255u), 0.5f), fmaxf((float)(w >> 24), 0.5f)}; }
; #define EPI_OPAQUE asm volatile("" : "+v"(fr), "+v"(fq));
;     __device__ __forceinline__ void operator()(f32x4 (&acc)[2][2][4][2], const Unit& u, int wr, int wc, int fr, int fq) const {
;         EPI_OPAQUE
; #pragma unroll
;         for (int ai = 0; ai < 2; ++ai) {
;             u32x2 gg[4][2];
; #pragma unroll
;             for (int m = 0; m < 4; ++m)
; #pragma unroll
;                 for (int bj = 0; bj < 2; ++bj) { const int row = u.pm * 256 + ai * 128 + wr * 64 + m * 16 + fr, col = u.pn * 256 + bj * 128 + wc * 32 + 8 * fq;
;                     gg[m][bj] = *(const u32x2*)((const unsigned char*)P + (size_t)row * ROWB + GATE_B0 + 2 * DM + col); }
;             asm volatile("" ::: "memory");
; #pragma unroll
;             for (int m = 0; m < 4; ++m)
; #pragma unroll
;                 for (int bj = 0; bj < 2; ++bj) { const int row = u.pm * 256 + ai * 128 + wr * 64 + m * 16 + fr, col = u.pn * 256 + bj * 128 + wc * 32 + 8 * fq;
;                     const f32x4 g0 = un_unorm8(gg[m][bj].x) * (1.0f / 255.0f), g1 = un_unorm8(gg[m][bj].y) * (1.0f / 255.0f);
;                     *(u32x4*)(MG + (size_t)row * DM + col) = pack8(acc[ai][bj][m][0] * g0, acc[ai][bj][m][1] * g1); }
;             asm volatile("" ::: "memory");
;         }
;     }
	v_pk_mul_f32 v[76:77], v[70:71], v[84:85]
	v_pk_mul_f32 v[70:71], v[68:69], v[82:83]
	v_cvt_pk_bf16_f32 v68, v72, v73
	v_cvt_pk_bf16_f32 v69, v74, v75
	v_cvt_pk_bf16_f32 v70, v70, v71
	v_cvt_pk_bf16_f32 v71, v76, v77
	v_add_u32_e32 v76, 0x80, v146
	global_store_dwordx4 v[80:81], v[68:71], off offset:256
	v_add_u32_e32 v82, 0x90, v146
	v_add_u32_e32 v72, 0xb0, v146
	v_mad_i64_i32 v[68:69], s[4:5], v76, s33, v[150:151]
	v_lshl_add_u64 v[68:69], v[68:69], 0, s[84:85]
	v_lshl_add_u64 v[70:71], v[68:69], 0, v[246:247]
	global_load_dwordx2 v[78:79], v[70:71], off
	v_lshl_add_u64 v[68:69], v[68:69], 0, v[148:149]
	global_load_dwordx2 v[80:81], v[68:69], off
	v_mad_i64_i32 v[68:69], s[4:5], v82, s33, v[150:151]
	v_lshl_add_u64 v[68:69], v[68:69], 0, s[84:85]
	v_lshl_add_u64 v[70:71], v[68:69], 0, v[246:247]
	global_load_dwordx2 v[84:85], v[70:71], off
	v_lshl_add_u64 v[68:69], v[68:69], 0, v[148:149]
	global_load_dwordx2 v[86:87], v[68:69], off
	v_mad_i64_i32 v[68:69], s[4:5], v88, s33, v[150:151]
	v_lshl_add_u64 v[68:69], v[68:69], 0, s[84:85]
	v_lshl_add_u64 v[70:71], v[68:69], 0, v[246:247]
	global_load_dwordx2 v[90:91], v[70:71], off
	v_lshl_add_u64 v[68:69], v[68:69], 0, v[148:149]
	global_load_dwordx2 v[74:75], v[68:69], off
	v_mad_i64_i32 v[68:69], s[4:5], v72, s33, v[150:151]
	v_lshl_add_u64 v[68:69], v[68:69], 0, s[84:85]
	v_lshl_add_u64 v[70:71], v[68:69], 0, v[246:247]
	global_load_dwordx2 v[70:71], v[70:71], off
	v_lshl_add_u64 v[68:69], v[68:69], 0, v[148:149]
	global_load_dwordx2 v[68:69], v[68:69], off
	v_ashrrev_i32_e32 v77, 31, v76
	v_lshlrev_b64 v[76:77], 12, v[76:77]
	v_ashrrev_i32_e32 v83, 31, v82
	v_ashrrev_i32_e32 v73, 31, v72
	s_mov_b64 s[4:5], -1
	s_waitcnt vmcnt(7)
	v_cvt_f32_ubyte0_e32 v1, v78
	v_max_f32_e32 v92, 0.5, v1
	v_cvt_f32_ubyte1_e32 v1, v78
	v_max_f32_e32 v93, 0.5, v1
	v_cvt_f32_ubyte2_e32 v1, v78
	v_max_f32_e32 v94, 0.5, v1
	v_cvt_f32_ubyte3_e32 v1, v78
	v_max_f32_e32 v95, 0.5, v1
	v_cvt_f32_ubyte0_e32 v1, v79
	v_max_f32_e32 v96, 0.5, v1
	v_cvt_f32_ubyte1_e32 v1, v79
	v_max_f32_e32 v97, 0.5, v1
	v_cvt_f32_ubyte2_e32 v1, v79
	v_max_f32_e32 v78, 0.5, v1
	v_cvt_f32_ubyte3_e32 v1, v79
	v_pk_mul_f32 v[92:93], v[92:93], s[86:87] op_sel_hi:[1,0]
	v_max_f32_e32 v79, 0.5, v1
	v_pk_mul_f32 v[94:95], v[94:95], s[86:87] op_sel_hi:[1,0]
	v_pk_mul_f32 v[96:97], v[96:97], s[86:87] op_sel_hi:[1,0]
	v_pk_mul_f32 v[78:79], v[78:79], s[86:87] op_sel_hi:[1,0]
	v_pk_mul_f32 v[64:65], v[64:65], v[92:93]
	v_pk_mul_f32 v[66:67], v[66:67], v[94:95]
	v_pk_mul_f32 v[78:79], v[62:63], v[78:79]
	v_pk_mul_f32 v[62:63], v[60:61], v[96:97]
	v_cvt_pk_bf16_f32 v60, v64, v65
	v_lshl_add_u64 v[64:65], s[72:73], 0, v[76:77]
	v_cvt_pk_bf16_f32 v61, v66, v67
	v_cvt_pk_bf16_f32 v62, v62, v63
	v_cvt_pk_bf16_f32 v63, v78, v79
	v_lshl_add_u64 v[64:65], v[64:65], 0, v[2:3]
	s_waitcnt vmcnt(6)
	v_cvt_f32_ubyte0_e32 v1, v80
	global_store_dwordx4 v[64:65], v[60:63], off
	s_nop 1
	v_max_f32_e32 v60, 0.5, v1
	v_cvt_f32_ubyte1_e32 v1, v80
	v_max_f32_e32 v61, 0.5, v1
	v_cvt_f32_ubyte2_e32 v1, v80
	v_max_f32_e32 v62, 0.5, v1
	v_cvt_f32_ubyte3_e32 v1, v80
	v_max_f32_e32 v63, 0.5, v1
	v_cvt_f32_ubyte0_e32 v1, v81
	v_max_f32_e32 v66, 0.5, v1
	v_cvt_f32_ubyte1_e32 v1, v81
	v_max_f32_e32 v67, 0.5, v1
	v_cvt_f32_ubyte2_e32 v1, v81
	v_max_f32_e32 v76, 0.5, v1
	v_cvt_f32_ubyte3_e32 v1, v81
	v_max_f32_e32 v77, 0.5, v1
	v_pk_mul_f32 v[60:61], v[60:61], s[86:87] op_sel_hi:[1,0]
	v_pk_mul_f32 v[62:63], v[62:63], s[86:87] op_sel_hi:[1,0]
	v_pk_mul_f32 v[66:67], v[66:67], s[86:87] op_sel_hi:[1,0]
	v_pk_mul_f32 v[76:77], v[76:77], s[86:87] op_sel_hi:[1,0]
	v_pk_mul_f32 v[58:59], v[58:59], v[62:63]
	v_pk_mul_f32 v[56:57], v[56:57], v[60:61]
	v_pk_mul_f32 v[60:61], v[54:55], v[76:77]
	v_pk_mul_f32 v[54:55], v[52:53], v[66:67]
	v_cvt_pk_bf16_f32 v52, v56, v57
	v_cvt_pk_bf16_f32 v53, v58, v59
	v_cvt_pk_bf16_f32 v54, v54, v55
	v_cvt_pk_bf16_f32 v55, v60, v61
	s_waitcnt vmcnt(6)
	v_cvt_f32_ubyte0_e32 v1, v84
	global_store_dwordx4 v[64:65], v[52:55], off offset:256
	s_nop 1
	v_max_f32_e32 v54, 0.5, v1
	v_cvt_f32_ubyte1_e32 v1, v84
	v_max_f32_e32 v55, 0.5, v1
	v_cvt_f32_ubyte2_e32 v1, v84
	v_max_f32_e32 v56, 0.5, v1
	v_cvt_f32_ubyte3_e32 v1, v84
	v_max_f32_e32 v57, 0.5, v1
	v_cvt_f32_ubyte0_e32 v1, v85
	v_max_f32_e32 v58, 0.5, v1
	v_cvt_f32_ubyte1_e32 v1, v85
	v_max_f32_e32 v59, 0.5, v1
	v_cvt_f32_ubyte2_e32 v1, v85
	v_max_f32_e32 v60, 0.5, v1
	v_cvt_f32_ubyte3_e32 v1, v85
	v_pk_mul_f32 v[54:55], v[54:55], s[86:87] op_sel_hi:[1,0]
	v_max_f32_e32 v61, 0.5, v1
	v_lshlrev_b64 v[52:53], 12, v[82:83]
	v_pk_mul_f32 v[56:57], v[56:57], s[86:87] op_sel_hi:[1,0]
	v_pk_mul_f32 v[58:59], v[58:59], s[86:87] op_sel_hi:[1,0]
	v_pk_mul_f32 v[60:61], v[60:61], s[86:87] op_sel_hi:[1,0]
	v_pk_mul_f32 v[48:49], v[48:49], v[54:55]
	v_pk_mul_f32 v[50:51], v[50:51], v[56:57]
	v_pk_mul_f32 v[54:55], v[46:47], v[60:61]
	v_pk_mul_f32 v[46:47], v[44:45], v[58:59]
	v_cvt_pk_bf16_f32 v44, v48, v49
	v_lshl_add_u64 v[48:49], s[72:73], 0, v[52:53]
	v_cvt_pk_bf16_f32 v45, v50, v51
	v_cvt_pk_bf16_f32 v46, v46, v47
	v_cvt_pk_bf16_f32 v47, v54, v55
	v_lshl_add_u64 v[48:49], v[48:49], 0, v[2:3]
	s_waitcnt vmcnt(6)
; __device__ __forceinline__ u32x4 pack8(f32x4 a, f32x4 b) { u32x4 w; w.x = cvt_pk_bf16(a[0], a[1]); w.y = cvt_pk_bf16(a[2], a[3]); w.z = cvt_pk_bf16(b[0], b[1]); w.w = cvt_pk_bf16(b[2], b[3]); return w; }
; __device__ __forceinline__ f32x4 un_unorm8(unsigned w) { return (f32x4){fmaxf((float)(w & 255u), 0.5f), fmaxf((float)((w >> 8) & 255u), 0.5f), fmaxf((float)((w >> 16) & 255u), 0.5f), fmaxf((float)(w >> 24), 0.5f)}; }
; #define PG8_BAR __builtin_amdgcn_s_barrier()
; #define EPI_OPAQUE asm volatile("" : "+v"(fr), "+v"(fq));
; template <class Epi, class Order = StaticOrder, bool HALFN = false>
; __device__ __forceinline__ void gemm_phase(LAS unsigned char* lds, const Gemm g, const Epi& E) {
;     ...
;         cur = nxt; cA = nA; cB = nB; ++ui;
;         if (wr == 1) PG8_BAR;
;     __device__ __forceinline__ void operator()(f32x4 (&acc)[2][2][4][2], const Unit& u, int wr, int wc, int fr, int fq) const {
;         EPI_OPAQUE
; #pragma unroll
;         for (int ai = 0; ai < 2; ++ai) {
;             u32x2 gg[4][2];
; #pragma unroll
;             for (int m = 0; m < 4; ++m)
; #pragma unroll
;                 for (int bj = 0; bj < 2; ++bj) { const int row = u.pm * 256 + ai * 128 + wr * 64 + m * 16 + fr, col = u.pn * 256 + bj * 128 + wc * 32 + 8 * fq;
;                     gg[m][bj] = *(const u32x2*)((const unsigned char*)P + (size_t)row * ROWB + GATE_B0 + 2 * DM + col); }
;             asm volatile("" ::: "memory");
; #pragma unroll
;             for (int m = 0; m < 4; ++m)
; #pragma unroll
;                 for (int bj = 0; bj < 2; ++bj) { const int row = u.pm * 256 + ai * 128 + wr * 64 + m * 16 + fr, col = u.pn * 256 + bj * 128 + wc * 32 + 8 * fq;
;                     const f32x4 g0 = un_unorm8(gg[m][bj].x) * (1.0f / 255.0f), g1 = un_unorm8(gg[m][bj].y) * (1.0f / 255.0f);
;                     *(u32x4*)(MG + (size_t)row * DM + col) = pack8(acc[ai][bj][m][0] * g0, acc[ai][bj][m][1] * g1); }
;             asm volatile("" ::: "memory");
;         }
;     }
	v_cvt_f32_ubyte0_e32 v1, v86
	global_store_dwordx4 v[48:49], v[44:47], off
	s_nop 1
	v_max_f32_e32 v44, 0.5, v1
	v_cvt_f32_ubyte1_e32 v1, v86
	v_max_f32_e32 v45, 0.5, v1
	v_cvt_f32_ubyte2_e32 v1, v86
	v_max_f32_e32 v46, 0.5, v1
	v_cvt_f32_ubyte3_e32 v1, v86
	v_max_f32_e32 v47, 0.5, v1
	v_cvt_f32_ubyte0_e32 v1, v87
	v_max_f32_e32 v50, 0.5, v1
	v_cvt_f32_ubyte1_e32 v1, v87
	v_max_f32_e32 v51, 0.5, v1
	v_cvt_f32_ubyte2_e32 v1, v87
	v_max_f32_e32 v52, 0.5, v1
	v_cvt_f32_ubyte3_e32 v1, v87
	v_max_f32_e32 v53, 0.5, v1
	v_pk_mul_f32 v[44:45], v[44:45], s[86:87] op_sel_hi:[1,0]
	v_pk_mul_f32 v[46:47], v[46:47], s[86:87] op_sel_hi:[1,0]
	v_pk_mul_f32 v[50:51], v[50:51], s[86:87] op_sel_hi:[1,0]
	v_pk_mul_f32 v[52:53], v[52:53], s[86:87] op_sel_hi:[1,0]
	v_pk_mul_f32 v[42:43], v[42:43], v[46:47]
	v_pk_mul_f32 v[40:41], v[40:41], v[44:45]
	v_pk_mul_f32 v[44:45], v[38:39], v[52:53]
	v_pk_mul_f32 v[38:39], v[36:37], v[50:51]
	v_cvt_pk_bf16_f32 v36, v40, v41
	v_cvt_pk_bf16_f32 v37, v42, v43
	v_cvt_pk_bf16_f32 v38, v38, v39
	v_cvt_pk_bf16_f32 v39, v44, v45
	s_waitcnt vmcnt(6)
	v_cvt_f32_ubyte0_e32 v1, v90
	global_store_dwordx4 v[48:49], v[36:39], off offset:256
	s_nop 1
	v_max_f32_e32 v38, 0.5, v1
	v_cvt_f32_ubyte1_e32 v1, v90
	v_max_f32_e32 v39, 0.5, v1
	v_cvt_f32_ubyte2_e32 v1, v90
	v_max_f32_e32 v40, 0.5, v1
	v_cvt_f32_ubyte3_e32 v1, v90
	v_max_f32_e32 v41, 0.5, v1
	v_cvt_f32_ubyte0_e32 v1, v91
	v_max_f32_e32 v42, 0.5, v1
	v_cvt_f32_ubyte1_e32 v1, v91
	v_max_f32_e32 v43, 0.5, v1
	v_cvt_f32_ubyte2_e32 v1, v91
	v_max_f32_e32 v44, 0.5, v1
	v_cvt_f32_ubyte3_e32 v1, v91
	v_pk_mul_f32 v[38:39], v[38:39], s[86:87] op_sel_hi:[1,0]
	v_max_f32_e32 v45, 0.5, v1
	v_lshlrev_b64 v[36:37], 12, v[88:89]
	v_pk_mul_f32 v[40:41], v[40:41], s[86:87] op_sel_hi:[1,0]
	v_pk_mul_f32 v[42:43], v[42:43], s[86:87] op_sel_hi:[1,0]
	v_pk_mul_f32 v[44:45], v[44:45], s[86:87] op_sel_hi:[1,0]
	v_pk_mul_f32 v[32:33], v[32:33], v[38:39]
	v_pk_mul_f32 v[34:35], v[34:35], v[40:41]
	v_pk_mul_f32 v[38:39], v[30:31], v[44:45]
	v_pk_mul_f32 v[30:31], v[28:29], v[42:43]
	v_cvt_pk_bf16_f32 v28, v32, v33
	v_lshl_add_u64 v[32:33], s[72:73], 0, v[36:37]
	v_cvt_pk_bf16_f32 v29, v34, v35
	v_cvt_pk_bf16_f32 v30, v30, v31
	v_cvt_pk_bf16_f32 v31, v38, v39
	v_lshl_add_u64 v[32:33], v[32:33], 0, v[2:3]
	s_waitcnt vmcnt(6)
	v_cvt_f32_ubyte0_e32 v1, v74
	global_store_dwordx4 v[32:33], v[28:31], off
	s_nop 1
	v_max_f32_e32 v28, 0.5, v1
	v_cvt_f32_ubyte1_e32 v1, v74
	v_max_f32_e32 v29, 0.5, v1
	v_cvt_f32_ubyte2_e32 v1, v74
	v_max_f32_e32 v30, 0.5, v1
	v_cvt_f32_ubyte3_e32 v1, v74
	v_max_f32_e32 v31, 0.5, v1
	v_cvt_f32_ubyte0_e32 v1, v75
	v_max_f32_e32 v34, 0.5, v1
	v_cvt_f32_ubyte1_e32 v1, v75
	v_max_f32_e32 v35, 0.5, v1
	v_cvt_f32_ubyte2_e32 v1, v75
	v_max_f32_e32 v36, 0.5, v1
	v_cvt_f32_ubyte3_e32 v1, v75
	v_max_f32_e32 v37, 0.5, v1
	v_pk_mul_f32 v[28:29], v[28:29], s[86:87] op_sel_hi:[1,0]
	v_pk_mul_f32 v[30:31], v[30:31], s[86:87] op_sel_hi:[1,0]
	v_pk_mul_f32 v[34:35], v[34:35], s[86:87] op_sel_hi:[1,0]
	v_pk_mul_f32 v[36:37], v[36:37], s[86:87] op_sel_hi:[1,0]
	v_pk_mul_f32 v[26:27], v[26:27], v[30:31]
	v_pk_mul_f32 v[24:25], v[24:25], v[28:29]
	v_pk_mul_f32 v[28:29], v[22:23], v[36:37]
	v_pk_mul_f32 v[22:23], v[20:21], v[34:35]
	v_cvt_pk_bf16_f32 v20, v24, v25
	v_cvt_pk_bf16_f32 v21, v26, v27
	v_cvt_pk_bf16_f32 v22, v22, v23
	v_cvt_pk_bf16_f32 v23, v28, v29
	s_waitcnt vmcnt(6)
	v_cvt_f32_ubyte0_e32 v1, v70
	global_store_dwordx4 v[32:33], v[20:23], off offset:256
	s_nop 1
	v_max_f32_e32 v22, 0.5, v1
	v_cvt_f32_ubyte1_e32 v1, v70
	v_max_f32_e32 v23, 0.5, v1
	v_cvt_f32_ubyte2_e32 v1, v70
	v_max_f32_e32 v24, 0.5, v1
	v_cvt_f32_ubyte3_e32 v1, v70
	v_max_f32_e32 v25, 0.5, v1
	v_cvt_f32_ubyte0_e32 v1, v71
	v_max_f32_e32 v26, 0.5, v1
	v_cvt_f32_ubyte1_e32 v1, v71
	v_max_f32_e32 v27, 0.5, v1
	v_cvt_f32_ubyte2_e32 v1, v71
	v_max_f32_e32 v28, 0.5, v1
	v_cvt_f32_ubyte3_e32 v1, v71
	v_pk_mul_f32 v[22:23], v[22:23], s[86:87] op_sel_hi:[1,0]
	v_max_f32_e32 v29, 0.5, v1
	v_lshlrev_b64 v[20:21], 12, v[72:73]
	v_pk_mul_f32 v[26:27], v[26:27], s[86:87] op_sel_hi:[1,0]
	v_pk_mul_f32 v[28:29], v[28:29], s[86:87] op_sel_hi:[1,0]
	v_pk_mul_f32 v[16:17], v[16:17], v[22:23]
	v_pk_mul_f32 v[24:25], v[24:25], s[86:87] op_sel_hi:[1,0]
	v_pk_mul_f32 v[22:23], v[14:15], v[28:29]
	v_pk_mul_f32 v[14:15], v[12:13], v[26:27]
	v_cvt_pk_bf16_f32 v12, v16, v17
	v_lshl_add_u64 v[16:17], s[72:73], 0, v[20:21]
	s_waitcnt vmcnt(6)
	v_cvt_f32_ubyte0_e32 v1, v68
	v_pk_mul_f32 v[18:19], v[18:19], v[24:25]
	v_lshl_add_u64 v[16:17], v[16:17], 0, v[2:3]
	v_max_f32_e32 v2, 0.5, v1
	v_cvt_f32_ubyte1_e32 v1, v68
	v_cvt_pk_bf16_f32 v13, v18, v19
	v_cvt_pk_bf16_f32 v14, v14, v15
	v_cvt_pk_bf16_f32 v15, v22, v23
	v_max_f32_e32 v3, 0.5, v1
	v_cvt_f32_ubyte2_e32 v1, v68
	global_store_dwordx4 v[16:17], v[12:15], off
	v_pk_mul_f32 v[2:3], v[2:3], s[86:87] op_sel_hi:[1,0]
	s_nop 0
	v_max_f32_e32 v12, 0.5, v1
	v_cvt_f32_ubyte3_e32 v1, v68
	v_max_f32_e32 v13, 0.5, v1
	v_cvt_f32_ubyte0_e32 v1, v69
	v_max_f32_e32 v14, 0.5, v1
	v_cvt_f32_ubyte1_e32 v1, v69
	v_max_f32_e32 v15, 0.5, v1
	v_cvt_f32_ubyte2_e32 v1, v69
	v_max_f32_e32 v18, 0.5, v1
	v_cvt_f32_ubyte3_e32 v1, v69
	v_max_f32_e32 v19, 0.5, v1
	v_pk_mul_f32 v[12:13], v[12:13], s[86:87] op_sel_hi:[1,0]
	v_pk_mul_f32 v[14:15], v[14:15], s[86:87] op_sel_hi:[1,0]
	v_pk_mul_f32 v[18:19], v[18:19], s[86:87] op_sel_hi:[1,0]
	v_pk_mul_f32 v[10:11], v[10:11], v[12:13]
	v_pk_mul_f32 v[2:3], v[8:9], v[2:3]
	v_pk_mul_f32 v[6:7], v[6:7], v[18:19]
	v_pk_mul_f32 v[4:5], v[4:5], v[14:15]
	v_cvt_pk_bf16_f32 v2, v2, v3
	v_cvt_pk_bf16_f32 v3, v10, v11
	v_cvt_pk_bf16_f32 v4, v4, v5
	v_cvt_pk_bf16_f32 v5, v6, v7
	global_store_dwordx4 v[16:17], v[2:5], off offset:256
	s_cbranch_vccnz .LBB0_597
	s_andn2_b64 vcc, exec, s[44:45]
	s_cbranch_vccnz .LBB0_596
	s_barrier
	s_branch .LBB0_596
